# v78 + DMA-first in 16-read segments, two-burst interleave (2 DMA, 4 reads, 2 DMA, 4 reads) in the 8-read segments
# baseline (speedup 1.0000x reference)
.Lbal_first_21:
	s_add_u32 s26, s24, 0xfffc0080
	s_addc_u32 s27, s25, -1
	s_cmp_eq_u32 s55, 12
	s_cselect_b32 s29, s19, s27
	s_cselect_b32 s28, s51, s26
	s_cselect_b32 s27, s17, s54
	s_cselect_b32 s26, s52, s53
	s_add_i32 m0, s38, 0xc000
	s_nop 0
	global_load_lds_dwordx4 v138, s[24:25]
	s_add_i32 m0, s38, 0xe000
	s_nop 0
	global_load_lds_dwordx4 v136, s[24:25]
	ds_read_b128 v[144:147], v151
	ds_read_b128 v[156:159], v151 offset:1024
	ds_read_b128 v[160:163], v151 offset:2048
	ds_read_b128 v[164:167], v151 offset:3072
	ds_read_b128 v[168:171], v152
	ds_read_b128 v[172:175], v152 offset:1024
	ds_read_b128 v[176:179], v152 offset:2048
	ds_read_b128 v[180:183], v152 offset:3072
	ds_read_b128 v[184:187], v153
	ds_read_b128 v[188:191], v153 offset:1024
	ds_read_b128 v[192:195], v153 offset:2048
	ds_read_b128 v[196:199], v153 offset:3072
	ds_read_b128 v[200:203], v153 offset:4096
	ds_read_b128 v[208:211], v153 offset:5120
	ds_read_b128 v[212:215], v153 offset:6144
	ds_read_b128 v[216:219], v153 offset:7168
	s_waitcnt vmcnt(8)
	s_waitcnt lgkmcnt(0)
	s_barrier
	s_waitcnt lgkmcnt(0)
	v_mfma_f32_16x16x32_bf16 v[124:127], v[144:147], v[184:187], v[124:127]
	v_mfma_f32_16x16x32_bf16 v[120:123], v[160:163], v[184:187], v[120:123]
	v_mfma_f32_16x16x32_bf16 v[108:111], v[144:147], v[192:195], v[108:111]
	v_mfma_f32_16x16x32_bf16 v[104:107], v[160:163], v[192:195], v[104:107]
	v_mfma_f32_16x16x32_bf16 v[92:95], v[144:147], v[200:203], v[92:95]
	v_mfma_f32_16x16x32_bf16 v[88:91], v[160:163], v[200:203], v[88:91]
	v_mfma_f32_16x16x32_bf16 v[76:79], v[144:147], v[212:215], v[76:79]
	v_mfma_f32_16x16x32_bf16 v[72:75], v[160:163], v[212:215], v[72:75]
	v_mfma_f32_16x16x32_bf16 v[124:127], v[156:159], v[188:191], v[124:127]
	v_mfma_f32_16x16x32_bf16 v[120:123], v[164:167], v[188:191], v[120:123]
	v_mfma_f32_16x16x32_bf16 v[108:111], v[156:159], v[196:199], v[108:111]
	v_mfma_f32_16x16x32_bf16 v[104:107], v[164:167], v[196:199], v[104:107]
	v_mfma_f32_16x16x32_bf16 v[92:95], v[156:159], v[208:211], v[92:95]
	v_mfma_f32_16x16x32_bf16 v[88:91], v[164:167], v[208:211], v[88:91]
	v_mfma_f32_16x16x32_bf16 v[76:79], v[156:159], v[216:219], v[76:79]
	v_mfma_f32_16x16x32_bf16 v[72:75], v[164:167], v[216:219], v[72:75]
	v_mfma_f32_16x16x32_bf16 v[116:119], v[168:171], v[184:187], v[116:119]
	v_mfma_f32_16x16x32_bf16 v[112:115], v[176:179], v[184:187], v[112:115]
	v_mfma_f32_16x16x32_bf16 v[100:103], v[168:171], v[192:195], v[100:103]
	v_mfma_f32_16x16x32_bf16 v[96:99], v[176:179], v[192:195], v[96:99]
	v_mfma_f32_16x16x32_bf16 v[84:87], v[168:171], v[200:203], v[84:87]
	v_mfma_f32_16x16x32_bf16 v[80:83], v[176:179], v[200:203], v[80:83]
	v_mfma_f32_16x16x32_bf16 v[68:71], v[168:171], v[212:215], v[68:71]
	v_mfma_f32_16x16x32_bf16 v[64:67], v[176:179], v[212:215], v[64:67]
	v_mfma_f32_16x16x32_bf16 v[116:119], v[172:175], v[188:191], v[116:119]
	v_mfma_f32_16x16x32_bf16 v[112:115], v[180:183], v[188:191], v[112:115]
	v_mfma_f32_16x16x32_bf16 v[100:103], v[172:175], v[196:199], v[100:103]
	v_mfma_f32_16x16x32_bf16 v[96:99], v[180:183], v[196:199], v[96:99]
	v_mfma_f32_16x16x32_bf16 v[84:87], v[172:175], v[208:211], v[84:87]
	v_mfma_f32_16x16x32_bf16 v[80:83], v[180:183], v[208:211], v[80:83]
	v_mfma_f32_16x16x32_bf16 v[68:71], v[172:175], v[216:219], v[68:71]
	v_mfma_f32_16x16x32_bf16 v[64:67], v[180:183], v[216:219], v[64:67]
	s_barrier
	s_add_i32 s56, s48, s35
	s_mov_b32 m0, s56
	s_nop 0
	global_load_lds_dwordx4 v132, s[26:27]
	s_add_i32 m0, s56, 0x2000
	s_add_u32 s56, s26, 0x40000
	s_mov_b64 s[98:99], s[26:27]
	s_addc_u32 s57, s27, 0
	s_add_i32 s58, s49, s35
	global_load_lds_dwordx4 v128, s[26:27]
	ds_read_b128 v[184:187], v153 offset:16384
	ds_read_b128 v[188:191], v153 offset:17408
	ds_read_b128 v[192:195], v153 offset:18432
	ds_read_b128 v[196:199], v153 offset:19456
	s_mov_b32 m0, s58
	s_mov_b64 s[100:101], s[28:29]
	global_load_lds_dwordx4 v132, s[56:57]
	s_add_i32 m0, s58, 0x2000
	s_nop 0
	global_load_lds_dwordx4 v128, s[56:57]
	ds_read_b128 v[200:203], v153 offset:20480
	ds_read_b128 v[208:211], v153 offset:21504
	ds_read_b128 v[212:215], v153 offset:22528
	ds_read_b128 v[216:219], v153 offset:23552
	s_waitcnt vmcnt(6)
	s_waitcnt lgkmcnt(0)
	s_barrier
	s_waitcnt lgkmcnt(0)
	v_mfma_f32_16x16x32_bf16 v[60:63], v[144:147], v[184:187], v[60:63]
	v_mfma_f32_16x16x32_bf16 v[56:59], v[160:163], v[184:187], v[56:59]
	v_mfma_f32_16x16x32_bf16 v[44:47], v[144:147], v[192:195], v[44:47]
	v_mfma_f32_16x16x32_bf16 v[40:43], v[160:163], v[192:195], v[40:43]
	v_mfma_f32_16x16x32_bf16 v[28:31], v[144:147], v[200:203], v[28:31]
	v_mfma_f32_16x16x32_bf16 v[24:27], v[160:163], v[200:203], v[24:27]
	v_mfma_f32_16x16x32_bf16 v[12:15], v[144:147], v[212:215], v[12:15]
	v_mfma_f32_16x16x32_bf16 v[8:11], v[160:163], v[212:215], v[8:11]
	v_mfma_f32_16x16x32_bf16 v[60:63], v[156:159], v[188:191], v[60:63]
	v_mfma_f32_16x16x32_bf16 v[56:59], v[164:167], v[188:191], v[56:59]
	v_mfma_f32_16x16x32_bf16 v[44:47], v[156:159], v[196:199], v[44:47]
	v_mfma_f32_16x16x32_bf16 v[40:43], v[164:167], v[196:199], v[40:43]
	v_mfma_f32_16x16x32_bf16 v[28:31], v[156:159], v[208:211], v[28:31]
	v_mfma_f32_16x16x32_bf16 v[24:27], v[164:167], v[208:211], v[24:27]
	v_mfma_f32_16x16x32_bf16 v[12:15], v[156:159], v[216:219], v[12:15]
	v_mfma_f32_16x16x32_bf16 v[8:11], v[164:167], v[216:219], v[8:11]
	v_mfma_f32_16x16x32_bf16 v[52:55], v[168:171], v[184:187], v[52:55]
	v_mfma_f32_16x16x32_bf16 v[48:51], v[176:179], v[184:187], v[48:51]
	v_mfma_f32_16x16x32_bf16 v[36:39], v[168:171], v[192:195], v[36:39]
	v_mfma_f32_16x16x32_bf16 v[32:35], v[176:179], v[192:195], v[32:35]
	v_mfma_f32_16x16x32_bf16 v[20:23], v[168:171], v[200:203], v[20:23]
	v_mfma_f32_16x16x32_bf16 v[16:19], v[176:179], v[200:203], v[16:19]
	v_mfma_f32_16x16x32_bf16 v[4:7], v[168:171], v[212:215], v[4:7]
	v_mfma_f32_16x16x32_bf16 v[0:3], v[176:179], v[212:215], v[0:3]
	v_mfma_f32_16x16x32_bf16 v[52:55], v[172:175], v[188:191], v[52:55]
	v_mfma_f32_16x16x32_bf16 v[48:51], v[180:183], v[188:191], v[48:51]
	v_mfma_f32_16x16x32_bf16 v[36:39], v[172:175], v[196:199], v[36:39]
	v_mfma_f32_16x16x32_bf16 v[32:35], v[180:183], v[196:199], v[32:35]
	v_mfma_f32_16x16x32_bf16 v[20:23], v[172:175], v[208:211], v[20:23]
	v_mfma_f32_16x16x32_bf16 v[16:19], v[180:183], v[208:211], v[16:19]
	v_mfma_f32_16x16x32_bf16 v[4:7], v[172:175], v[216:219], v[4:7]
	v_mfma_f32_16x16x32_bf16 v[0:3], v[180:183], v[216:219], v[0:3]
	s_barrier
	s_mov_b32 m0, s38
	s_nop 0
	global_load_lds_dwordx4 v134, s[28:29]
	s_mov_b32 m0, s39
	s_nop 0
	global_load_lds_dwordx4 v130, s[28:29]
	s_add_i32 s56, 0, 0x18000
	s_add_i32 s57, 0, 0x1c000
	s_add_u32 s28, s28, 0x40000
	s_addc_u32 s29, s29, 0
	s_mov_b32 m0, s40
	s_nop 0
	global_load_lds_dwordx4 v134, s[28:29]
	s_mov_b32 m0, s41
	s_nop 0
	global_load_lds_dwordx4 v130, s[28:29]
	v_add_u32_e32 v164, s56, v149
	v_add_u32_e32 v180, s57, v149
	ds_read_b128 v[144:147], v164
	ds_read_b128 v[156:159], v164 offset:1024
	ds_read_b128 v[160:163], v164 offset:2048
	ds_read_b128 v[164:167], v164 offset:3072
	ds_read_b128 v[168:171], v180
	ds_read_b128 v[172:175], v180 offset:1024
	ds_read_b128 v[176:179], v180 offset:2048
	ds_read_b128 v[180:183], v180 offset:3072
	ds_read_b128 v[184:187], v153 offset:32768
	ds_read_b128 v[188:191], v153 offset:33792
	ds_read_b128 v[192:195], v153 offset:34816
	ds_read_b128 v[196:199], v153 offset:35840
	ds_read_b128 v[200:203], v153 offset:36864
	ds_read_b128 v[208:211], v153 offset:37888
	ds_read_b128 v[212:215], v153 offset:38912
	ds_read_b128 v[216:219], v153 offset:39936
	s_waitcnt vmcnt(8)
	s_waitcnt lgkmcnt(0)
	s_barrier
	s_waitcnt lgkmcnt(0)
	v_mfma_f32_16x16x32_bf16 v[124:127], v[144:147], v[184:187], v[124:127]
	v_mfma_f32_16x16x32_bf16 v[120:123], v[160:163], v[184:187], v[120:123]
	v_mfma_f32_16x16x32_bf16 v[108:111], v[144:147], v[192:195], v[108:111]
	v_mfma_f32_16x16x32_bf16 v[104:107], v[160:163], v[192:195], v[104:107]
	v_mfma_f32_16x16x32_bf16 v[92:95], v[144:147], v[200:203], v[92:95]
	v_mfma_f32_16x16x32_bf16 v[88:91], v[160:163], v[200:203], v[88:91]
	v_mfma_f32_16x16x32_bf16 v[76:79], v[144:147], v[212:215], v[76:79]
	v_mfma_f32_16x16x32_bf16 v[72:75], v[160:163], v[212:215], v[72:75]
	v_mfma_f32_16x16x32_bf16 v[124:127], v[156:159], v[188:191], v[124:127]
	v_mfma_f32_16x16x32_bf16 v[120:123], v[164:167], v[188:191], v[120:123]
	v_mfma_f32_16x16x32_bf16 v[108:111], v[156:159], v[196:199], v[108:111]
	v_mfma_f32_16x16x32_bf16 v[104:107], v[164:167], v[196:199], v[104:107]
	v_mfma_f32_16x16x32_bf16 v[92:95], v[156:159], v[208:211], v[92:95]
	v_mfma_f32_16x16x32_bf16 v[88:91], v[164:167], v[208:211], v[88:91]
	v_mfma_f32_16x16x32_bf16 v[76:79], v[156:159], v[216:219], v[76:79]
	v_mfma_f32_16x16x32_bf16 v[72:75], v[164:167], v[216:219], v[72:75]
	v_mfma_f32_16x16x32_bf16 v[116:119], v[168:171], v[184:187], v[116:119]
	v_mfma_f32_16x16x32_bf16 v[112:115], v[176:179], v[184:187], v[112:115]
	v_mfma_f32_16x16x32_bf16 v[100:103], v[168:171], v[192:195], v[100:103]
	v_mfma_f32_16x16x32_bf16 v[96:99], v[176:179], v[192:195], v[96:99]
	v_mfma_f32_16x16x32_bf16 v[84:87], v[168:171], v[200:203], v[84:87]
	v_mfma_f32_16x16x32_bf16 v[80:83], v[176:179], v[200:203], v[80:83]
	v_mfma_f32_16x16x32_bf16 v[68:71], v[168:171], v[212:215], v[68:71]
	v_mfma_f32_16x16x32_bf16 v[64:67], v[176:179], v[212:215], v[64:67]
	v_mfma_f32_16x16x32_bf16 v[116:119], v[172:175], v[188:191], v[116:119]
	v_mfma_f32_16x16x32_bf16 v[112:115], v[180:183], v[188:191], v[112:115]
	v_mfma_f32_16x16x32_bf16 v[100:103], v[172:175], v[196:199], v[100:103]
	v_mfma_f32_16x16x32_bf16 v[96:99], v[180:183], v[196:199], v[96:99]
	v_mfma_f32_16x16x32_bf16 v[84:87], v[172:175], v[208:211], v[84:87]
	v_mfma_f32_16x16x32_bf16 v[80:83], v[180:183], v[208:211], v[80:83]
	v_mfma_f32_16x16x32_bf16 v[68:71], v[172:175], v[216:219], v[68:71]
	v_mfma_f32_16x16x32_bf16 v[64:67], v[180:183], v[216:219], v[64:67]
	s_barrier
	s_add_i32 s28, s56, s35
	s_mov_b32 m0, s28
	s_nop 0
	global_load_lds_dwordx4 v220, s[26:27]
	s_add_i32 m0, s28, 0x2000
	s_add_u32 s26, s26, 0x40080
	s_addc_u32 s27, s27, 0
	s_add_i32 s28, s57, s35
	global_load_lds_dwordx4 v204, s[98:99]
	ds_read_b128 v[184:187], v153 offset:49152
	ds_read_b128 v[188:191], v153 offset:50176
	ds_read_b128 v[192:195], v153 offset:51200
	ds_read_b128 v[196:199], v153 offset:52224
	s_mov_b32 m0, s28
	s_nop 0
	global_load_lds_dwordx4 v132, s[26:27]
	s_add_i32 m0, s28, 0x2000
	s_nop 0
	global_load_lds_dwordx4 v128, s[26:27]
	s_cmp_lg_u32 s55, 12
	s_cbranch_scc1 .Lbal_last_21
	s_mov_b32 m0, s45
	s_nop 0
	global_load_lds_dwordx4 v221, s[100:101]
	s_mov_b32 m0, s46
	s_nop 0
	global_load_lds_dwordx4 v205, s[100:101]
.Lbal_last_21:
	ds_read_b128 v[200:203], v153 offset:53248
	ds_read_b128 v[208:211], v153 offset:54272
	ds_read_b128 v[212:215], v153 offset:55296
	ds_read_b128 v[216:219], v153 offset:56320
	s_waitcnt vmcnt(6)
	s_waitcnt lgkmcnt(0)
	s_barrier
	s_waitcnt lgkmcnt(0)
	v_mfma_f32_16x16x32_bf16 v[60:63], v[144:147], v[184:187], v[60:63]
	v_mfma_f32_16x16x32_bf16 v[56:59], v[160:163], v[184:187], v[56:59]
	v_mfma_f32_16x16x32_bf16 v[44:47], v[144:147], v[192:195], v[44:47]
	v_mfma_f32_16x16x32_bf16 v[40:43], v[160:163], v[192:195], v[40:43]
	v_mfma_f32_16x16x32_bf16 v[28:31], v[144:147], v[200:203], v[28:31]
	v_mfma_f32_16x16x32_bf16 v[24:27], v[160:163], v[200:203], v[24:27]
	v_mfma_f32_16x16x32_bf16 v[12:15], v[144:147], v[212:215], v[12:15]
	v_mfma_f32_16x16x32_bf16 v[8:11], v[160:163], v[212:215], v[8:11]
	v_mfma_f32_16x16x32_bf16 v[60:63], v[156:159], v[188:191], v[60:63]
	v_mfma_f32_16x16x32_bf16 v[56:59], v[164:167], v[188:191], v[56:59]
	v_mfma_f32_16x16x32_bf16 v[44:47], v[156:159], v[196:199], v[44:47]
	v_mfma_f32_16x16x32_bf16 v[40:43], v[164:167], v[196:199], v[40:43]
	v_mfma_f32_16x16x32_bf16 v[28:31], v[156:159], v[208:211], v[28:31]
	v_mfma_f32_16x16x32_bf16 v[24:27], v[164:167], v[208:211], v[24:27]
	v_mfma_f32_16x16x32_bf16 v[12:15], v[156:159], v[216:219], v[12:15]
	v_mfma_f32_16x16x32_bf16 v[8:11], v[164:167], v[216:219], v[8:11]
	v_mfma_f32_16x16x32_bf16 v[52:55], v[168:171], v[184:187], v[52:55]
	v_mfma_f32_16x16x32_bf16 v[48:51], v[176:179], v[184:187], v[48:51]
	v_mfma_f32_16x16x32_bf16 v[36:39], v[168:171], v[192:195], v[36:39]
	v_mfma_f32_16x16x32_bf16 v[32:35], v[176:179], v[192:195], v[32:35]
	v_mfma_f32_16x16x32_bf16 v[20:23], v[168:171], v[200:203], v[20:23]
	v_mfma_f32_16x16x32_bf16 v[16:19], v[176:179], v[200:203], v[16:19]
	v_mfma_f32_16x16x32_bf16 v[4:7], v[168:171], v[212:215], v[4:7]
	v_mfma_f32_16x16x32_bf16 v[0:3], v[176:179], v[212:215], v[0:3]
	v_mfma_f32_16x16x32_bf16 v[52:55], v[172:175], v[188:191], v[52:55]
	v_mfma_f32_16x16x32_bf16 v[48:51], v[180:183], v[188:191], v[48:51]
	v_mfma_f32_16x16x32_bf16 v[36:39], v[172:175], v[196:199], v[36:39]
	v_mfma_f32_16x16x32_bf16 v[32:35], v[180:183], v[196:199], v[32:35]
	v_mfma_f32_16x16x32_bf16 v[20:23], v[172:175], v[208:211], v[20:23]
	v_mfma_f32_16x16x32_bf16 v[16:19], v[180:183], v[208:211], v[16:19]
	v_mfma_f32_16x16x32_bf16 v[4:7], v[172:175], v[216:219], v[4:7]
	v_mfma_f32_16x16x32_bf16 v[0:3], v[180:183], v[216:219], v[0:3]
	s_barrier
	s_add_i32 s55, s55, 2
	s_add_u32 s53, s53, 0x100
	s_addc_u32 s54, s54, 0
	s_add_u32 s24, s24, 0x100
	s_addc_u32 s25, s25, 0
	s_cmp_gt_u32 s55, 13
	s_cbranch_scc0 .LBB0_163
	s_setprio 0
	s_and_b64 vcc, exec, s[14:15]
	s_cbranch_vccz .LBB0_166
	s_barrier

.Lbal_first_20:
	s_add_u32 s30, s28, 0x100
	s_addc_u32 s31, s29, 0
	s_cmp_eq_u32 s58, 12
	s_cselect_b32 s37, s21, s31
	s_cselect_b32 s36, s27, s30
	s_cselect_b32 s35, s19, s57
	s_cselect_b32 s34, s55, s56
	s_add_i32 m0, s44, 0xc000
	s_nop 0
	global_load_lds_dwordx4 v134, s[28:29]
	s_add_i32 m0, s44, 0xe000
	s_nop 0
	global_load_lds_dwordx4 v132, s[28:29]
	ds_read_b128 v[140:143], v147
	ds_read_b128 v[150:153], v147 offset:1024
	ds_read_b128 v[154:157], v147 offset:2048
	ds_read_b128 v[158:161], v147 offset:3072
	ds_read_b128 v[162:165], v148
	ds_read_b128 v[166:169], v148 offset:1024
	ds_read_b128 v[170:173], v148 offset:2048
	ds_read_b128 v[174:177], v148 offset:3072
	ds_read_b128 v[178:181], v149
	ds_read_b128 v[182:185], v149 offset:1024
	ds_read_b128 v[186:189], v149 offset:2048
	ds_read_b128 v[190:193], v149 offset:3072
	ds_read_b128 v[194:197], v149 offset:4096
	ds_read_b128 v[198:201], v149 offset:5120
	ds_read_b128 v[202:205], v149 offset:6144
	ds_read_b128 v[208:211], v149 offset:7168
	s_waitcnt vmcnt(8)
	s_waitcnt lgkmcnt(0)
	s_barrier
	s_waitcnt lgkmcnt(0)
	v_mfma_f32_16x16x32_bf16 v[124:127], v[140:143], v[178:181], v[124:127]
	v_mfma_f32_16x16x32_bf16 v[120:123], v[154:157], v[178:181], v[120:123]
	v_mfma_f32_16x16x32_bf16 v[108:111], v[140:143], v[186:189], v[108:111]
	v_mfma_f32_16x16x32_bf16 v[104:107], v[154:157], v[186:189], v[104:107]
	v_mfma_f32_16x16x32_bf16 v[92:95], v[140:143], v[194:197], v[92:95]
	v_mfma_f32_16x16x32_bf16 v[88:91], v[154:157], v[194:197], v[88:91]
	v_mfma_f32_16x16x32_bf16 v[76:79], v[140:143], v[202:205], v[76:79]
	v_mfma_f32_16x16x32_bf16 v[72:75], v[154:157], v[202:205], v[72:75]
	v_mfma_f32_16x16x32_bf16 v[124:127], v[150:153], v[182:185], v[124:127]
	v_mfma_f32_16x16x32_bf16 v[120:123], v[158:161], v[182:185], v[120:123]
	v_mfma_f32_16x16x32_bf16 v[108:111], v[150:153], v[190:193], v[108:111]
	v_mfma_f32_16x16x32_bf16 v[104:107], v[158:161], v[190:193], v[104:107]
	v_mfma_f32_16x16x32_bf16 v[92:95], v[150:153], v[198:201], v[92:95]
	v_mfma_f32_16x16x32_bf16 v[88:91], v[158:161], v[198:201], v[88:91]
	v_mfma_f32_16x16x32_bf16 v[76:79], v[150:153], v[208:211], v[76:79]
	v_mfma_f32_16x16x32_bf16 v[72:75], v[158:161], v[208:211], v[72:75]
	v_mfma_f32_16x16x32_bf16 v[116:119], v[162:165], v[178:181], v[116:119]
	v_mfma_f32_16x16x32_bf16 v[112:115], v[170:173], v[178:181], v[112:115]
	v_mfma_f32_16x16x32_bf16 v[100:103], v[162:165], v[186:189], v[100:103]
	v_mfma_f32_16x16x32_bf16 v[96:99], v[170:173], v[186:189], v[96:99]
	v_mfma_f32_16x16x32_bf16 v[84:87], v[162:165], v[194:197], v[84:87]
	v_mfma_f32_16x16x32_bf16 v[80:83], v[170:173], v[194:197], v[80:83]
	v_mfma_f32_16x16x32_bf16 v[68:71], v[162:165], v[202:205], v[68:71]
	v_mfma_f32_16x16x32_bf16 v[64:67], v[170:173], v[202:205], v[64:67]
	v_mfma_f32_16x16x32_bf16 v[116:119], v[166:169], v[182:185], v[116:119]
	v_mfma_f32_16x16x32_bf16 v[112:115], v[174:177], v[182:185], v[112:115]
	v_mfma_f32_16x16x32_bf16 v[100:103], v[166:169], v[190:193], v[100:103]
	v_mfma_f32_16x16x32_bf16 v[96:99], v[174:177], v[190:193], v[96:99]
	v_mfma_f32_16x16x32_bf16 v[84:87], v[166:169], v[198:201], v[84:87]
	v_mfma_f32_16x16x32_bf16 v[80:83], v[174:177], v[198:201], v[80:83]
	v_mfma_f32_16x16x32_bf16 v[68:71], v[166:169], v[208:211], v[68:71]
	v_mfma_f32_16x16x32_bf16 v[64:67], v[174:177], v[208:211], v[64:67]
	s_barrier
	s_add_i32 s28, s52, s43
	s_mov_b32 m0, s28
	s_nop 0
	global_load_lds_dwordx4 v128, s[34:35]
	s_add_i32 m0, s28, 0x2000
	s_add_u32 s28, s34, 0x40000
	s_mov_b64 s[98:99], s[34:35]
	s_addc_u32 s29, s35, 0
	s_add_i32 s59, s53, s43
	global_load_lds_dwordx4 v130, s[34:35]
	ds_read_b128 v[178:181], v149 offset:16384
	ds_read_b128 v[182:185], v149 offset:17408
	ds_read_b128 v[186:189], v149 offset:18432
	ds_read_b128 v[190:193], v149 offset:19456
	s_mov_b32 m0, s59
	s_nop 0
	global_load_lds_dwordx4 v128, s[28:29]
	s_add_i32 m0, s59, 0x2000
	s_nop 0
	global_load_lds_dwordx4 v130, s[28:29]
	ds_read_b128 v[194:197], v149 offset:20480
	ds_read_b128 v[198:201], v149 offset:21504
	ds_read_b128 v[202:205], v149 offset:22528
	ds_read_b128 v[208:211], v149 offset:23552
	s_waitcnt vmcnt(6)
	s_waitcnt lgkmcnt(0)
	s_barrier
	s_waitcnt lgkmcnt(0)
	v_mfma_f32_16x16x32_bf16 v[60:63], v[140:143], v[178:181], v[60:63]
	v_mfma_f32_16x16x32_bf16 v[56:59], v[154:157], v[178:181], v[56:59]
	v_mfma_f32_16x16x32_bf16 v[44:47], v[140:143], v[186:189], v[44:47]
	v_mfma_f32_16x16x32_bf16 v[40:43], v[154:157], v[186:189], v[40:43]
	v_mfma_f32_16x16x32_bf16 v[28:31], v[140:143], v[194:197], v[28:31]
	v_mfma_f32_16x16x32_bf16 v[24:27], v[154:157], v[194:197], v[24:27]
	v_mfma_f32_16x16x32_bf16 v[12:15], v[140:143], v[202:205], v[12:15]
	v_mfma_f32_16x16x32_bf16 v[8:11], v[154:157], v[202:205], v[8:11]
	v_mfma_f32_16x16x32_bf16 v[60:63], v[150:153], v[182:185], v[60:63]
	v_mfma_f32_16x16x32_bf16 v[56:59], v[158:161], v[182:185], v[56:59]
	v_mfma_f32_16x16x32_bf16 v[44:47], v[150:153], v[190:193], v[44:47]
	v_mfma_f32_16x16x32_bf16 v[40:43], v[158:161], v[190:193], v[40:43]
	v_mfma_f32_16x16x32_bf16 v[28:31], v[150:153], v[198:201], v[28:31]
	v_mfma_f32_16x16x32_bf16 v[24:27], v[158:161], v[198:201], v[24:27]
	v_mfma_f32_16x16x32_bf16 v[12:15], v[150:153], v[208:211], v[12:15]
	v_mfma_f32_16x16x32_bf16 v[8:11], v[158:161], v[208:211], v[8:11]
	v_mfma_f32_16x16x32_bf16 v[52:55], v[162:165], v[178:181], v[52:55]
	v_mfma_f32_16x16x32_bf16 v[48:51], v[170:173], v[178:181], v[48:51]
	v_mfma_f32_16x16x32_bf16 v[36:39], v[162:165], v[186:189], v[36:39]
	v_mfma_f32_16x16x32_bf16 v[32:35], v[170:173], v[186:189], v[32:35]
	v_mfma_f32_16x16x32_bf16 v[20:23], v[162:165], v[194:197], v[20:23]
	v_mfma_f32_16x16x32_bf16 v[16:19], v[170:173], v[194:197], v[16:19]
	v_mfma_f32_16x16x32_bf16 v[4:7], v[162:165], v[202:205], v[4:7]
	v_mfma_f32_16x16x32_bf16 v[0:3], v[170:173], v[202:205], v[0:3]
	v_mfma_f32_16x16x32_bf16 v[52:55], v[166:169], v[182:185], v[52:55]
	v_mfma_f32_16x16x32_bf16 v[48:51], v[174:177], v[182:185], v[48:51]
	v_mfma_f32_16x16x32_bf16 v[36:39], v[166:169], v[190:193], v[36:39]
	v_mfma_f32_16x16x32_bf16 v[32:35], v[174:177], v[190:193], v[32:35]
	v_mfma_f32_16x16x32_bf16 v[20:23], v[166:169], v[198:201], v[20:23]
	v_mfma_f32_16x16x32_bf16 v[16:19], v[174:177], v[198:201], v[16:19]
	v_mfma_f32_16x16x32_bf16 v[4:7], v[166:169], v[208:211], v[4:7]
	v_mfma_f32_16x16x32_bf16 v[0:3], v[174:177], v[208:211], v[0:3]
	s_barrier
	s_mov_b32 m0, s44
	s_nop 0
	global_load_lds_dwordx4 v128, s[36:37]
	s_mov_b32 m0, s45
	s_nop 0
	global_load_lds_dwordx4 v130, s[36:37]
	s_add_i32 s59, 0, 0x18000
	s_add_i32 s60, 0, 0x1c000
	s_add_u32 s28, s36, 0x40000
	s_addc_u32 s29, s37, 0
	s_mov_b32 m0, s46
	s_nop 0
	global_load_lds_dwordx4 v128, s[28:29]
	s_mov_b32 m0, s47
	s_nop 0
	global_load_lds_dwordx4 v130, s[28:29]
	v_add_u32_e32 v158, s59, v145
	v_add_u32_e32 v174, s60, v145
	ds_read_b128 v[140:143], v158
	ds_read_b128 v[150:153], v158 offset:1024
	ds_read_b128 v[154:157], v158 offset:2048
	ds_read_b128 v[158:161], v158 offset:3072
	ds_read_b128 v[162:165], v174
	ds_read_b128 v[166:169], v174 offset:1024
	ds_read_b128 v[170:173], v174 offset:2048
	ds_read_b128 v[174:177], v174 offset:3072
	ds_read_b128 v[178:181], v149 offset:32768
	ds_read_b128 v[182:185], v149 offset:33792
	ds_read_b128 v[186:189], v149 offset:34816
	ds_read_b128 v[190:193], v149 offset:35840
	ds_read_b128 v[194:197], v149 offset:36864
	ds_read_b128 v[198:201], v149 offset:37888
	ds_read_b128 v[202:205], v149 offset:38912
	ds_read_b128 v[208:211], v149 offset:39936
	s_waitcnt vmcnt(8)
	s_waitcnt lgkmcnt(0)
	s_barrier
	s_waitcnt lgkmcnt(0)
	v_mfma_f32_16x16x32_bf16 v[124:127], v[140:143], v[178:181], v[124:127]
	v_mfma_f32_16x16x32_bf16 v[120:123], v[154:157], v[178:181], v[120:123]
	v_mfma_f32_16x16x32_bf16 v[108:111], v[140:143], v[186:189], v[108:111]
	v_mfma_f32_16x16x32_bf16 v[104:107], v[154:157], v[186:189], v[104:107]
	v_mfma_f32_16x16x32_bf16 v[92:95], v[140:143], v[194:197], v[92:95]
	v_mfma_f32_16x16x32_bf16 v[88:91], v[154:157], v[194:197], v[88:91]
	v_mfma_f32_16x16x32_bf16 v[76:79], v[140:143], v[202:205], v[76:79]
	v_mfma_f32_16x16x32_bf16 v[72:75], v[154:157], v[202:205], v[72:75]
	v_mfma_f32_16x16x32_bf16 v[124:127], v[150:153], v[182:185], v[124:127]
	v_mfma_f32_16x16x32_bf16 v[120:123], v[158:161], v[182:185], v[120:123]
	v_mfma_f32_16x16x32_bf16 v[108:111], v[150:153], v[190:193], v[108:111]
	v_mfma_f32_16x16x32_bf16 v[104:107], v[158:161], v[190:193], v[104:107]
	v_mfma_f32_16x16x32_bf16 v[92:95], v[150:153], v[198:201], v[92:95]
	v_mfma_f32_16x16x32_bf16 v[88:91], v[158:161], v[198:201], v[88:91]
	v_mfma_f32_16x16x32_bf16 v[76:79], v[150:153], v[208:211], v[76:79]
	v_mfma_f32_16x16x32_bf16 v[72:75], v[158:161], v[208:211], v[72:75]
	v_mfma_f32_16x16x32_bf16 v[116:119], v[162:165], v[178:181], v[116:119]
	v_mfma_f32_16x16x32_bf16 v[112:115], v[170:173], v[178:181], v[112:115]
	v_mfma_f32_16x16x32_bf16 v[100:103], v[162:165], v[186:189], v[100:103]
	v_mfma_f32_16x16x32_bf16 v[96:99], v[170:173], v[186:189], v[96:99]
	v_mfma_f32_16x16x32_bf16 v[84:87], v[162:165], v[194:197], v[84:87]
	v_mfma_f32_16x16x32_bf16 v[80:83], v[170:173], v[194:197], v[80:83]
	v_mfma_f32_16x16x32_bf16 v[68:71], v[162:165], v[202:205], v[68:71]
	v_mfma_f32_16x16x32_bf16 v[64:67], v[170:173], v[202:205], v[64:67]
	v_mfma_f32_16x16x32_bf16 v[116:119], v[166:169], v[182:185], v[116:119]
	v_mfma_f32_16x16x32_bf16 v[112:115], v[174:177], v[182:185], v[112:115]
	v_mfma_f32_16x16x32_bf16 v[100:103], v[166:169], v[190:193], v[100:103]
	v_mfma_f32_16x16x32_bf16 v[96:99], v[174:177], v[190:193], v[96:99]
	v_mfma_f32_16x16x32_bf16 v[84:87], v[166:169], v[198:201], v[84:87]
	v_mfma_f32_16x16x32_bf16 v[80:83], v[174:177], v[198:201], v[80:83]
	v_mfma_f32_16x16x32_bf16 v[68:71], v[166:169], v[208:211], v[68:71]
	v_mfma_f32_16x16x32_bf16 v[64:67], v[174:177], v[208:211], v[64:67]
	s_barrier
	s_add_i32 s28, s59, s43
	s_mov_b32 m0, s28
	s_nop 0
	global_load_lds_dwordx4 v212, s[34:35]
	s_add_i32 m0, s28, 0x2000
	s_add_u32 s28, s34, 0x40080
	s_addc_u32 s29, s35, 0
	s_add_i32 s34, s60, s43
	global_load_lds_dwordx4 v213, s[98:99]
	ds_read_b128 v[178:181], v149 offset:49152
	ds_read_b128 v[182:185], v149 offset:50176
	ds_read_b128 v[186:189], v149 offset:51200
	ds_read_b128 v[190:193], v149 offset:52224
	s_mov_b32 m0, s34
	s_nop 0
	global_load_lds_dwordx4 v128, s[28:29]
	s_add_i32 m0, s34, 0x2000
	s_nop 0
	global_load_lds_dwordx4 v130, s[28:29]
	s_cmp_lg_u32 s58, 12
	s_cbranch_scc1 .Lbal_last_20
	s_mov_b32 m0, s49
	s_nop 0
	global_load_lds_dwordx4 v212, s[36:37]
	s_mov_b32 m0, s50
	s_nop 0
	global_load_lds_dwordx4 v213, s[36:37]
.Lbal_last_20:
	ds_read_b128 v[194:197], v149 offset:53248
	ds_read_b128 v[198:201], v149 offset:54272
	ds_read_b128 v[202:205], v149 offset:55296
	ds_read_b128 v[208:211], v149 offset:56320
	s_waitcnt vmcnt(6)
	s_waitcnt lgkmcnt(0)
	s_barrier
	s_waitcnt lgkmcnt(0)
	v_mfma_f32_16x16x32_bf16 v[60:63], v[140:143], v[178:181], v[60:63]
	v_mfma_f32_16x16x32_bf16 v[56:59], v[154:157], v[178:181], v[56:59]
	v_mfma_f32_16x16x32_bf16 v[44:47], v[140:143], v[186:189], v[44:47]
	v_mfma_f32_16x16x32_bf16 v[40:43], v[154:157], v[186:189], v[40:43]
	v_mfma_f32_16x16x32_bf16 v[28:31], v[140:143], v[194:197], v[28:31]
	v_mfma_f32_16x16x32_bf16 v[24:27], v[154:157], v[194:197], v[24:27]
	v_mfma_f32_16x16x32_bf16 v[12:15], v[140:143], v[202:205], v[12:15]
	v_mfma_f32_16x16x32_bf16 v[8:11], v[154:157], v[202:205], v[8:11]
	v_mfma_f32_16x16x32_bf16 v[60:63], v[150:153], v[182:185], v[60:63]
	v_mfma_f32_16x16x32_bf16 v[56:59], v[158:161], v[182:185], v[56:59]
	v_mfma_f32_16x16x32_bf16 v[44:47], v[150:153], v[190:193], v[44:47]
	v_mfma_f32_16x16x32_bf16 v[40:43], v[158:161], v[190:193], v[40:43]
	v_mfma_f32_16x16x32_bf16 v[28:31], v[150:153], v[198:201], v[28:31]
	v_mfma_f32_16x16x32_bf16 v[24:27], v[158:161], v[198:201], v[24:27]
	v_mfma_f32_16x16x32_bf16 v[12:15], v[150:153], v[208:211], v[12:15]
	v_mfma_f32_16x16x32_bf16 v[8:11], v[158:161], v[208:211], v[8:11]
	v_mfma_f32_16x16x32_bf16 v[52:55], v[162:165], v[178:181], v[52:55]
	v_mfma_f32_16x16x32_bf16 v[48:51], v[170:173], v[178:181], v[48:51]
	v_mfma_f32_16x16x32_bf16 v[36:39], v[162:165], v[186:189], v[36:39]
	v_mfma_f32_16x16x32_bf16 v[32:35], v[170:173], v[186:189], v[32:35]
	v_mfma_f32_16x16x32_bf16 v[20:23], v[162:165], v[194:197], v[20:23]
	v_mfma_f32_16x16x32_bf16 v[16:19], v[170:173], v[194:197], v[16:19]
	v_mfma_f32_16x16x32_bf16 v[4:7], v[162:165], v[202:205], v[4:7]
	v_mfma_f32_16x16x32_bf16 v[0:3], v[170:173], v[202:205], v[0:3]
	v_mfma_f32_16x16x32_bf16 v[52:55], v[166:169], v[182:185], v[52:55]
	v_mfma_f32_16x16x32_bf16 v[48:51], v[174:177], v[182:185], v[48:51]
	v_mfma_f32_16x16x32_bf16 v[36:39], v[166:169], v[190:193], v[36:39]
	v_mfma_f32_16x16x32_bf16 v[32:35], v[174:177], v[190:193], v[32:35]
	v_mfma_f32_16x16x32_bf16 v[20:23], v[166:169], v[198:201], v[20:23]
	v_mfma_f32_16x16x32_bf16 v[16:19], v[174:177], v[198:201], v[16:19]
	v_mfma_f32_16x16x32_bf16 v[4:7], v[166:169], v[208:211], v[4:7]
	v_mfma_f32_16x16x32_bf16 v[0:3], v[174:177], v[208:211], v[0:3]
	s_barrier
	s_add_i32 s58, s58, 2
	s_add_u32 s56, s56, 0x100
	s_addc_u32 s57, s57, 0
	s_cmp_gt_u32 s58, 13
	s_mov_b64 s[28:29], s[30:31]
	s_cbranch_scc0 .LBB0_606
	s_setprio 0
	s_and_b64 vcc, exec, s[16:17]
	s_cbranch_vccz .LBB0_609
	s_barrier

.Lbal_first_19:
	s_add_u32 s28, s26, 0xfffc0080
	s_addc_u32 s29, s27, -1
	s_cmp_eq_u32 s53, 12
	s_cselect_b32 s31, s21, s29
	s_cselect_b32 s30, s49, s28
	s_cselect_b32 s29, s19, s52
	s_cselect_b32 s28, s50, s51
	s_add_i32 m0, s39, 0xc000
	s_nop 0
	global_load_lds_dwordx4 v138, s[26:27]
	s_add_i32 m0, s39, 0xe000
	s_nop 0
	global_load_lds_dwordx4 v136, s[26:27]
	ds_read_b128 v[144:147], v151
	ds_read_b128 v[156:159], v151 offset:1024
	ds_read_b128 v[160:163], v151 offset:2048
	ds_read_b128 v[164:167], v151 offset:3072
	ds_read_b128 v[168:171], v152
	ds_read_b128 v[172:175], v152 offset:1024
	ds_read_b128 v[176:179], v152 offset:2048
	ds_read_b128 v[180:183], v152 offset:3072
	ds_read_b128 v[184:187], v153
	ds_read_b128 v[188:191], v153 offset:1024
	ds_read_b128 v[192:195], v153 offset:2048
	ds_read_b128 v[196:199], v153 offset:3072
	ds_read_b128 v[200:203], v153 offset:4096
	ds_read_b128 v[208:211], v153 offset:5120
	ds_read_b128 v[212:215], v153 offset:6144
	ds_read_b128 v[216:219], v153 offset:7168
	s_waitcnt vmcnt(8)
	s_waitcnt lgkmcnt(0)
	s_barrier
	s_waitcnt lgkmcnt(0)
	v_mfma_f32_16x16x32_bf16 v[124:127], v[144:147], v[184:187], v[124:127]
	v_mfma_f32_16x16x32_bf16 v[120:123], v[160:163], v[184:187], v[120:123]
	v_mfma_f32_16x16x32_bf16 v[108:111], v[144:147], v[192:195], v[108:111]
	v_mfma_f32_16x16x32_bf16 v[104:107], v[160:163], v[192:195], v[104:107]
	v_mfma_f32_16x16x32_bf16 v[92:95], v[144:147], v[200:203], v[92:95]
	v_mfma_f32_16x16x32_bf16 v[88:91], v[160:163], v[200:203], v[88:91]
	v_mfma_f32_16x16x32_bf16 v[76:79], v[144:147], v[212:215], v[76:79]
	v_mfma_f32_16x16x32_bf16 v[72:75], v[160:163], v[212:215], v[72:75]
	v_mfma_f32_16x16x32_bf16 v[124:127], v[156:159], v[188:191], v[124:127]
	v_mfma_f32_16x16x32_bf16 v[120:123], v[164:167], v[188:191], v[120:123]
	v_mfma_f32_16x16x32_bf16 v[108:111], v[156:159], v[196:199], v[108:111]
	v_mfma_f32_16x16x32_bf16 v[104:107], v[164:167], v[196:199], v[104:107]
	v_mfma_f32_16x16x32_bf16 v[92:95], v[156:159], v[208:211], v[92:95]
	v_mfma_f32_16x16x32_bf16 v[88:91], v[164:167], v[208:211], v[88:91]
	v_mfma_f32_16x16x32_bf16 v[76:79], v[156:159], v[216:219], v[76:79]
	v_mfma_f32_16x16x32_bf16 v[72:75], v[164:167], v[216:219], v[72:75]
	v_mfma_f32_16x16x32_bf16 v[116:119], v[168:171], v[184:187], v[116:119]
	v_mfma_f32_16x16x32_bf16 v[112:115], v[176:179], v[184:187], v[112:115]
	v_mfma_f32_16x16x32_bf16 v[100:103], v[168:171], v[192:195], v[100:103]
	v_mfma_f32_16x16x32_bf16 v[96:99], v[176:179], v[192:195], v[96:99]
	v_mfma_f32_16x16x32_bf16 v[84:87], v[168:171], v[200:203], v[84:87]
	v_mfma_f32_16x16x32_bf16 v[80:83], v[176:179], v[200:203], v[80:83]
	v_mfma_f32_16x16x32_bf16 v[68:71], v[168:171], v[212:215], v[68:71]
	v_mfma_f32_16x16x32_bf16 v[64:67], v[176:179], v[212:215], v[64:67]
	v_mfma_f32_16x16x32_bf16 v[116:119], v[172:175], v[188:191], v[116:119]
	v_mfma_f32_16x16x32_bf16 v[112:115], v[180:183], v[188:191], v[112:115]
	v_mfma_f32_16x16x32_bf16 v[100:103], v[172:175], v[196:199], v[100:103]
	v_mfma_f32_16x16x32_bf16 v[96:99], v[180:183], v[196:199], v[96:99]
	v_mfma_f32_16x16x32_bf16 v[84:87], v[172:175], v[208:211], v[84:87]
	v_mfma_f32_16x16x32_bf16 v[80:83], v[180:183], v[208:211], v[80:83]
	v_mfma_f32_16x16x32_bf16 v[68:71], v[172:175], v[216:219], v[68:71]
	v_mfma_f32_16x16x32_bf16 v[64:67], v[180:183], v[216:219], v[64:67]
	s_barrier
	s_add_i32 s54, s46, s38
	s_mov_b32 m0, s54
	s_nop 0
	global_load_lds_dwordx4 v130, s[28:29]
	s_add_i32 m0, s54, 0x2000
	s_add_u32 s54, s28, 0x40000
	s_mov_b64 s[98:99], s[28:29]
	s_addc_u32 s55, s29, 0
	s_add_i32 s56, s47, s38
	global_load_lds_dwordx4 v134, s[28:29]
	ds_read_b128 v[184:187], v153 offset:16384
	ds_read_b128 v[188:191], v153 offset:17408
	ds_read_b128 v[192:195], v153 offset:18432
	ds_read_b128 v[196:199], v153 offset:19456
	s_mov_b32 m0, s56
	s_mov_b64 s[100:101], s[30:31]
	global_load_lds_dwordx4 v130, s[54:55]
	s_add_i32 m0, s56, 0x2000
	s_nop 0
	global_load_lds_dwordx4 v134, s[54:55]
	ds_read_b128 v[200:203], v153 offset:20480
	ds_read_b128 v[208:211], v153 offset:21504
	ds_read_b128 v[212:215], v153 offset:22528
	ds_read_b128 v[216:219], v153 offset:23552
	s_waitcnt vmcnt(6)
	s_waitcnt lgkmcnt(0)
	s_barrier
	s_waitcnt lgkmcnt(0)
	v_mfma_f32_16x16x32_bf16 v[60:63], v[144:147], v[184:187], v[60:63]
	v_mfma_f32_16x16x32_bf16 v[56:59], v[160:163], v[184:187], v[56:59]
	v_mfma_f32_16x16x32_bf16 v[44:47], v[144:147], v[192:195], v[44:47]
	v_mfma_f32_16x16x32_bf16 v[40:43], v[160:163], v[192:195], v[40:43]
	v_mfma_f32_16x16x32_bf16 v[28:31], v[144:147], v[200:203], v[28:31]
	v_mfma_f32_16x16x32_bf16 v[24:27], v[160:163], v[200:203], v[24:27]
	v_mfma_f32_16x16x32_bf16 v[12:15], v[144:147], v[212:215], v[12:15]
	v_mfma_f32_16x16x32_bf16 v[8:11], v[160:163], v[212:215], v[8:11]
	v_mfma_f32_16x16x32_bf16 v[60:63], v[156:159], v[188:191], v[60:63]
	v_mfma_f32_16x16x32_bf16 v[56:59], v[164:167], v[188:191], v[56:59]
	v_mfma_f32_16x16x32_bf16 v[44:47], v[156:159], v[196:199], v[44:47]
	v_mfma_f32_16x16x32_bf16 v[40:43], v[164:167], v[196:199], v[40:43]
	v_mfma_f32_16x16x32_bf16 v[28:31], v[156:159], v[208:211], v[28:31]
	v_mfma_f32_16x16x32_bf16 v[24:27], v[164:167], v[208:211], v[24:27]
	v_mfma_f32_16x16x32_bf16 v[12:15], v[156:159], v[216:219], v[12:15]
	v_mfma_f32_16x16x32_bf16 v[8:11], v[164:167], v[216:219], v[8:11]
	v_mfma_f32_16x16x32_bf16 v[52:55], v[168:171], v[184:187], v[52:55]
	v_mfma_f32_16x16x32_bf16 v[48:51], v[176:179], v[184:187], v[48:51]
	v_mfma_f32_16x16x32_bf16 v[36:39], v[168:171], v[192:195], v[36:39]
	v_mfma_f32_16x16x32_bf16 v[32:35], v[176:179], v[192:195], v[32:35]
	v_mfma_f32_16x16x32_bf16 v[20:23], v[168:171], v[200:203], v[20:23]
	v_mfma_f32_16x16x32_bf16 v[16:19], v[176:179], v[200:203], v[16:19]
	v_mfma_f32_16x16x32_bf16 v[4:7], v[168:171], v[212:215], v[4:7]
	v_mfma_f32_16x16x32_bf16 v[0:3], v[176:179], v[212:215], v[0:3]
	v_mfma_f32_16x16x32_bf16 v[52:55], v[172:175], v[188:191], v[52:55]
	v_mfma_f32_16x16x32_bf16 v[48:51], v[180:183], v[188:191], v[48:51]
	v_mfma_f32_16x16x32_bf16 v[36:39], v[172:175], v[196:199], v[36:39]
	v_mfma_f32_16x16x32_bf16 v[32:35], v[180:183], v[196:199], v[32:35]
	v_mfma_f32_16x16x32_bf16 v[20:23], v[172:175], v[208:211], v[20:23]
	v_mfma_f32_16x16x32_bf16 v[16:19], v[180:183], v[208:211], v[16:19]
	v_mfma_f32_16x16x32_bf16 v[4:7], v[172:175], v[216:219], v[4:7]
	v_mfma_f32_16x16x32_bf16 v[0:3], v[180:183], v[216:219], v[0:3]
	s_barrier
	s_mov_b32 m0, s39
	s_nop 0
	global_load_lds_dwordx4 v128, s[30:31]
	s_mov_b32 m0, s40
	s_nop 0
	global_load_lds_dwordx4 v132, s[30:31]
	s_add_i32 s54, 0, 0x18000
	s_add_i32 s55, 0, 0x1c000
	s_add_u32 s30, s30, 0x40000
	s_addc_u32 s31, s31, 0
	s_mov_b32 m0, s41
	s_nop 0
	global_load_lds_dwordx4 v128, s[30:31]
	s_mov_b32 m0, s42
	s_nop 0
	global_load_lds_dwordx4 v132, s[30:31]
	v_add_u32_e32 v155, s54, v149
	ds_read_b128 v[144:147], v155
	ds_read_b128 v[156:159], v155 offset:1024
	ds_read_b128 v[160:163], v155 offset:2048
	ds_read_b128 v[164:167], v155 offset:3072
	v_add_u32_e32 v155, s55, v149
	ds_read_b128 v[168:171], v155
	ds_read_b128 v[172:175], v155 offset:1024
	ds_read_b128 v[176:179], v155 offset:2048
	ds_read_b128 v[180:183], v155 offset:3072
	ds_read_b128 v[184:187], v153 offset:32768
	ds_read_b128 v[188:191], v153 offset:33792
	ds_read_b128 v[192:195], v153 offset:34816
	ds_read_b128 v[196:199], v153 offset:35840
	ds_read_b128 v[200:203], v153 offset:36864
	ds_read_b128 v[208:211], v153 offset:37888
	ds_read_b128 v[212:215], v153 offset:38912
	ds_read_b128 v[216:219], v153 offset:39936
	s_waitcnt vmcnt(8)
	s_waitcnt lgkmcnt(0)
	s_barrier
	s_waitcnt lgkmcnt(0)
	v_mfma_f32_16x16x32_bf16 v[124:127], v[144:147], v[184:187], v[124:127]
	v_mfma_f32_16x16x32_bf16 v[120:123], v[160:163], v[184:187], v[120:123]
	v_mfma_f32_16x16x32_bf16 v[108:111], v[144:147], v[192:195], v[108:111]
	v_mfma_f32_16x16x32_bf16 v[104:107], v[160:163], v[192:195], v[104:107]
	v_mfma_f32_16x16x32_bf16 v[92:95], v[144:147], v[200:203], v[92:95]
	v_mfma_f32_16x16x32_bf16 v[88:91], v[160:163], v[200:203], v[88:91]
	v_mfma_f32_16x16x32_bf16 v[76:79], v[144:147], v[212:215], v[76:79]
	v_mfma_f32_16x16x32_bf16 v[72:75], v[160:163], v[212:215], v[72:75]
	v_mfma_f32_16x16x32_bf16 v[124:127], v[156:159], v[188:191], v[124:127]
	v_mfma_f32_16x16x32_bf16 v[120:123], v[164:167], v[188:191], v[120:123]
	v_mfma_f32_16x16x32_bf16 v[108:111], v[156:159], v[196:199], v[108:111]
	v_mfma_f32_16x16x32_bf16 v[104:107], v[164:167], v[196:199], v[104:107]
	v_mfma_f32_16x16x32_bf16 v[92:95], v[156:159], v[208:211], v[92:95]
	v_mfma_f32_16x16x32_bf16 v[88:91], v[164:167], v[208:211], v[88:91]
	v_mfma_f32_16x16x32_bf16 v[76:79], v[156:159], v[216:219], v[76:79]
	v_mfma_f32_16x16x32_bf16 v[72:75], v[164:167], v[216:219], v[72:75]
	v_mfma_f32_16x16x32_bf16 v[116:119], v[168:171], v[184:187], v[116:119]
	v_mfma_f32_16x16x32_bf16 v[112:115], v[176:179], v[184:187], v[112:115]
	v_mfma_f32_16x16x32_bf16 v[100:103], v[168:171], v[192:195], v[100:103]
	v_mfma_f32_16x16x32_bf16 v[96:99], v[176:179], v[192:195], v[96:99]
	v_mfma_f32_16x16x32_bf16 v[84:87], v[168:171], v[200:203], v[84:87]
	v_mfma_f32_16x16x32_bf16 v[80:83], v[176:179], v[200:203], v[80:83]
	v_mfma_f32_16x16x32_bf16 v[68:71], v[168:171], v[212:215], v[68:71]
	v_mfma_f32_16x16x32_bf16 v[64:67], v[176:179], v[212:215], v[64:67]
	v_mfma_f32_16x16x32_bf16 v[116:119], v[172:175], v[188:191], v[116:119]
	v_mfma_f32_16x16x32_bf16 v[112:115], v[180:183], v[188:191], v[112:115]
	v_mfma_f32_16x16x32_bf16 v[100:103], v[172:175], v[196:199], v[100:103]
	v_mfma_f32_16x16x32_bf16 v[96:99], v[180:183], v[196:199], v[96:99]
	v_mfma_f32_16x16x32_bf16 v[84:87], v[172:175], v[208:211], v[84:87]
	v_mfma_f32_16x16x32_bf16 v[80:83], v[180:183], v[208:211], v[80:83]
	v_mfma_f32_16x16x32_bf16 v[68:71], v[172:175], v[216:219], v[68:71]
	v_mfma_f32_16x16x32_bf16 v[64:67], v[180:183], v[216:219], v[64:67]
	s_barrier
	s_add_i32 s30, s54, s38
	s_mov_b32 m0, s30
	s_nop 0
	global_load_lds_dwordx4 v205, s[28:29]
	s_add_i32 m0, s30, 0x2000
	s_add_u32 s28, s28, 0x40080
	s_addc_u32 s29, s29, 0
	s_add_i32 s30, s55, s38
	global_load_lds_dwordx4 v221, s[98:99]
	ds_read_b128 v[184:187], v153 offset:49152
	ds_read_b128 v[188:191], v153 offset:50176
	ds_read_b128 v[192:195], v153 offset:51200
	ds_read_b128 v[196:199], v153 offset:52224
	s_mov_b32 m0, s30
	s_nop 0
	global_load_lds_dwordx4 v130, s[28:29]
	s_add_i32 m0, s30, 0x2000
	s_nop 0
	global_load_lds_dwordx4 v134, s[28:29]
	s_cmp_lg_u32 s53, 12
	s_cbranch_scc1 .Lbal_last_19
	s_mov_b32 m0, s44
	s_nop 0
	global_load_lds_dwordx4 v204, s[100:101]
	s_mov_b32 m0, s45
	s_nop 0
	global_load_lds_dwordx4 v220, s[100:101]
.Lbal_last_19:
	ds_read_b128 v[200:203], v153 offset:53248
	ds_read_b128 v[208:211], v153 offset:54272
	ds_read_b128 v[212:215], v153 offset:55296
	ds_read_b128 v[216:219], v153 offset:56320
	s_waitcnt vmcnt(6)
	s_waitcnt lgkmcnt(0)
	s_barrier
	s_waitcnt lgkmcnt(0)
	v_mfma_f32_16x16x32_bf16 v[60:63], v[144:147], v[184:187], v[60:63]
	v_mfma_f32_16x16x32_bf16 v[56:59], v[160:163], v[184:187], v[56:59]
	v_mfma_f32_16x16x32_bf16 v[44:47], v[144:147], v[192:195], v[44:47]
	v_mfma_f32_16x16x32_bf16 v[40:43], v[160:163], v[192:195], v[40:43]
	v_mfma_f32_16x16x32_bf16 v[28:31], v[144:147], v[200:203], v[28:31]
	v_mfma_f32_16x16x32_bf16 v[24:27], v[160:163], v[200:203], v[24:27]
	v_mfma_f32_16x16x32_bf16 v[12:15], v[144:147], v[212:215], v[12:15]
	v_mfma_f32_16x16x32_bf16 v[8:11], v[160:163], v[212:215], v[8:11]
	v_mfma_f32_16x16x32_bf16 v[60:63], v[156:159], v[188:191], v[60:63]
	v_mfma_f32_16x16x32_bf16 v[56:59], v[164:167], v[188:191], v[56:59]
	v_mfma_f32_16x16x32_bf16 v[44:47], v[156:159], v[196:199], v[44:47]
	v_mfma_f32_16x16x32_bf16 v[40:43], v[164:167], v[196:199], v[40:43]
	v_mfma_f32_16x16x32_bf16 v[28:31], v[156:159], v[208:211], v[28:31]
	v_mfma_f32_16x16x32_bf16 v[24:27], v[164:167], v[208:211], v[24:27]
	v_mfma_f32_16x16x32_bf16 v[12:15], v[156:159], v[216:219], v[12:15]
	v_mfma_f32_16x16x32_bf16 v[8:11], v[164:167], v[216:219], v[8:11]
	v_mfma_f32_16x16x32_bf16 v[52:55], v[168:171], v[184:187], v[52:55]
	v_mfma_f32_16x16x32_bf16 v[48:51], v[176:179], v[184:187], v[48:51]
	v_mfma_f32_16x16x32_bf16 v[36:39], v[168:171], v[192:195], v[36:39]
	v_mfma_f32_16x16x32_bf16 v[32:35], v[176:179], v[192:195], v[32:35]
	v_mfma_f32_16x16x32_bf16 v[20:23], v[168:171], v[200:203], v[20:23]
	v_mfma_f32_16x16x32_bf16 v[16:19], v[176:179], v[200:203], v[16:19]
	v_mfma_f32_16x16x32_bf16 v[4:7], v[168:171], v[212:215], v[4:7]
	v_mfma_f32_16x16x32_bf16 v[0:3], v[176:179], v[212:215], v[0:3]
	v_mfma_f32_16x16x32_bf16 v[52:55], v[172:175], v[188:191], v[52:55]
	v_mfma_f32_16x16x32_bf16 v[48:51], v[180:183], v[188:191], v[48:51]
	v_mfma_f32_16x16x32_bf16 v[36:39], v[172:175], v[196:199], v[36:39]
	v_mfma_f32_16x16x32_bf16 v[32:35], v[180:183], v[196:199], v[32:35]
	v_mfma_f32_16x16x32_bf16 v[20:23], v[172:175], v[208:211], v[20:23]
	v_mfma_f32_16x16x32_bf16 v[16:19], v[180:183], v[208:211], v[16:19]
	v_mfma_f32_16x16x32_bf16 v[4:7], v[172:175], v[216:219], v[4:7]
	v_mfma_f32_16x16x32_bf16 v[0:3], v[180:183], v[216:219], v[0:3]
	s_barrier
	s_add_i32 s53, s53, 2
	s_add_u32 s51, s51, 0x100
	s_addc_u32 s52, s52, 0
	s_add_u32 s26, s26, 0x100
	s_addc_u32 s27, s27, 0
	s_cmp_gt_u32 s53, 13
	s_cbranch_scc0 .LBB0_699
	s_setprio 0
	s_and_b64 vcc, exec, s[16:17]
	s_cbranch_vccz .LBB0_702
	s_barrier

.Lbal_first_18:
	s_add_u32 s30, s28, 0x100
	s_addc_u32 s31, s29, 0
	s_cmp_eq_u32 s58, 60
	s_cselect_b32 s37, s21, s31
	s_cselect_b32 s36, s27, s30
	s_cselect_b32 s35, s19, s57
	s_cselect_b32 s34, s55, s56
	s_add_i32 m0, s44, 0xc000
	s_nop 0
	global_load_lds_dwordx4 v134, s[28:29]
	s_add_i32 m0, s44, 0xe000
	s_nop 0
	global_load_lds_dwordx4 v132, s[28:29]
	ds_read_b128 v[140:143], v147
	ds_read_b128 v[150:153], v147 offset:1024
	ds_read_b128 v[154:157], v147 offset:2048
	ds_read_b128 v[158:161], v147 offset:3072
	ds_read_b128 v[162:165], v148
	ds_read_b128 v[166:169], v148 offset:1024
	ds_read_b128 v[170:173], v148 offset:2048
	ds_read_b128 v[174:177], v148 offset:3072
	ds_read_b128 v[178:181], v149
	ds_read_b128 v[182:185], v149 offset:1024
	ds_read_b128 v[186:189], v149 offset:2048
	ds_read_b128 v[190:193], v149 offset:3072
	ds_read_b128 v[194:197], v149 offset:4096
	ds_read_b128 v[198:201], v149 offset:5120
	ds_read_b128 v[202:205], v149 offset:6144
	ds_read_b128 v[208:211], v149 offset:7168
	s_waitcnt vmcnt(8)
	s_waitcnt lgkmcnt(0)
	s_barrier
	s_waitcnt lgkmcnt(0)
	v_mfma_f32_16x16x32_bf16 v[124:127], v[140:143], v[178:181], v[124:127]
	v_mfma_f32_16x16x32_bf16 v[120:123], v[154:157], v[178:181], v[120:123]
	v_mfma_f32_16x16x32_bf16 v[108:111], v[140:143], v[186:189], v[108:111]
	v_mfma_f32_16x16x32_bf16 v[104:107], v[154:157], v[186:189], v[104:107]
	v_mfma_f32_16x16x32_bf16 v[92:95], v[140:143], v[194:197], v[92:95]
	v_mfma_f32_16x16x32_bf16 v[88:91], v[154:157], v[194:197], v[88:91]
	v_mfma_f32_16x16x32_bf16 v[76:79], v[140:143], v[202:205], v[76:79]
	v_mfma_f32_16x16x32_bf16 v[72:75], v[154:157], v[202:205], v[72:75]
	v_mfma_f32_16x16x32_bf16 v[124:127], v[150:153], v[182:185], v[124:127]
	v_mfma_f32_16x16x32_bf16 v[120:123], v[158:161], v[182:185], v[120:123]
	v_mfma_f32_16x16x32_bf16 v[108:111], v[150:153], v[190:193], v[108:111]
	v_mfma_f32_16x16x32_bf16 v[104:107], v[158:161], v[190:193], v[104:107]
	v_mfma_f32_16x16x32_bf16 v[92:95], v[150:153], v[198:201], v[92:95]
	v_mfma_f32_16x16x32_bf16 v[88:91], v[158:161], v[198:201], v[88:91]
	v_mfma_f32_16x16x32_bf16 v[76:79], v[150:153], v[208:211], v[76:79]
	v_mfma_f32_16x16x32_bf16 v[72:75], v[158:161], v[208:211], v[72:75]
	v_mfma_f32_16x16x32_bf16 v[116:119], v[162:165], v[178:181], v[116:119]
	v_mfma_f32_16x16x32_bf16 v[112:115], v[170:173], v[178:181], v[112:115]
	v_mfma_f32_16x16x32_bf16 v[100:103], v[162:165], v[186:189], v[100:103]
	v_mfma_f32_16x16x32_bf16 v[96:99], v[170:173], v[186:189], v[96:99]
	v_mfma_f32_16x16x32_bf16 v[84:87], v[162:165], v[194:197], v[84:87]
	v_mfma_f32_16x16x32_bf16 v[80:83], v[170:173], v[194:197], v[80:83]
	v_mfma_f32_16x16x32_bf16 v[68:71], v[162:165], v[202:205], v[68:71]
	v_mfma_f32_16x16x32_bf16 v[64:67], v[170:173], v[202:205], v[64:67]
	v_mfma_f32_16x16x32_bf16 v[116:119], v[166:169], v[182:185], v[116:119]
	v_mfma_f32_16x16x32_bf16 v[112:115], v[174:177], v[182:185], v[112:115]
	v_mfma_f32_16x16x32_bf16 v[100:103], v[166:169], v[190:193], v[100:103]
	v_mfma_f32_16x16x32_bf16 v[96:99], v[174:177], v[190:193], v[96:99]
	v_mfma_f32_16x16x32_bf16 v[84:87], v[166:169], v[198:201], v[84:87]
	v_mfma_f32_16x16x32_bf16 v[80:83], v[174:177], v[198:201], v[80:83]
	v_mfma_f32_16x16x32_bf16 v[68:71], v[166:169], v[208:211], v[68:71]
	v_mfma_f32_16x16x32_bf16 v[64:67], v[174:177], v[208:211], v[64:67]
	s_barrier
	s_add_i32 s28, s52, s43
	s_mov_b32 m0, s28
	s_nop 0
	global_load_lds_dwordx4 v128, s[34:35]
	s_add_i32 m0, s28, 0x2000
	s_add_u32 s28, s34, 0x100000
	s_mov_b64 s[98:99], s[34:35]
	s_addc_u32 s29, s35, 0
	s_add_i32 s59, s53, s43
	global_load_lds_dwordx4 v130, s[34:35]
	ds_read_b128 v[178:181], v149 offset:16384
	ds_read_b128 v[182:185], v149 offset:17408
	ds_read_b128 v[186:189], v149 offset:18432
	ds_read_b128 v[190:193], v149 offset:19456
	s_mov_b32 m0, s59
	s_nop 0
	global_load_lds_dwordx4 v128, s[28:29]
	s_add_i32 m0, s59, 0x2000
	s_nop 0
	global_load_lds_dwordx4 v130, s[28:29]
	ds_read_b128 v[194:197], v149 offset:20480
	ds_read_b128 v[198:201], v149 offset:21504
	ds_read_b128 v[202:205], v149 offset:22528
	ds_read_b128 v[208:211], v149 offset:23552
	s_waitcnt vmcnt(6)
	s_waitcnt lgkmcnt(0)
	s_barrier
	s_waitcnt lgkmcnt(0)
	v_mfma_f32_16x16x32_bf16 v[60:63], v[140:143], v[178:181], v[60:63]
	v_mfma_f32_16x16x32_bf16 v[56:59], v[154:157], v[178:181], v[56:59]
	v_mfma_f32_16x16x32_bf16 v[44:47], v[140:143], v[186:189], v[44:47]
	v_mfma_f32_16x16x32_bf16 v[40:43], v[154:157], v[186:189], v[40:43]
	v_mfma_f32_16x16x32_bf16 v[28:31], v[140:143], v[194:197], v[28:31]
	v_mfma_f32_16x16x32_bf16 v[24:27], v[154:157], v[194:197], v[24:27]
	v_mfma_f32_16x16x32_bf16 v[12:15], v[140:143], v[202:205], v[12:15]
	v_mfma_f32_16x16x32_bf16 v[8:11], v[154:157], v[202:205], v[8:11]
	v_mfma_f32_16x16x32_bf16 v[60:63], v[150:153], v[182:185], v[60:63]
	v_mfma_f32_16x16x32_bf16 v[56:59], v[158:161], v[182:185], v[56:59]
	v_mfma_f32_16x16x32_bf16 v[44:47], v[150:153], v[190:193], v[44:47]
	v_mfma_f32_16x16x32_bf16 v[40:43], v[158:161], v[190:193], v[40:43]
	v_mfma_f32_16x16x32_bf16 v[28:31], v[150:153], v[198:201], v[28:31]
	v_mfma_f32_16x16x32_bf16 v[24:27], v[158:161], v[198:201], v[24:27]
	v_mfma_f32_16x16x32_bf16 v[12:15], v[150:153], v[208:211], v[12:15]
	v_mfma_f32_16x16x32_bf16 v[8:11], v[158:161], v[208:211], v[8:11]
	v_mfma_f32_16x16x32_bf16 v[52:55], v[162:165], v[178:181], v[52:55]
	v_mfma_f32_16x16x32_bf16 v[48:51], v[170:173], v[178:181], v[48:51]
	v_mfma_f32_16x16x32_bf16 v[36:39], v[162:165], v[186:189], v[36:39]
	v_mfma_f32_16x16x32_bf16 v[32:35], v[170:173], v[186:189], v[32:35]
	v_mfma_f32_16x16x32_bf16 v[20:23], v[162:165], v[194:197], v[20:23]
	v_mfma_f32_16x16x32_bf16 v[16:19], v[170:173], v[194:197], v[16:19]
	v_mfma_f32_16x16x32_bf16 v[4:7], v[162:165], v[202:205], v[4:7]
	v_mfma_f32_16x16x32_bf16 v[0:3], v[170:173], v[202:205], v[0:3]
	v_mfma_f32_16x16x32_bf16 v[52:55], v[166:169], v[182:185], v[52:55]
	v_mfma_f32_16x16x32_bf16 v[48:51], v[174:177], v[182:185], v[48:51]
	v_mfma_f32_16x16x32_bf16 v[36:39], v[166:169], v[190:193], v[36:39]
	v_mfma_f32_16x16x32_bf16 v[32:35], v[174:177], v[190:193], v[32:35]
	v_mfma_f32_16x16x32_bf16 v[20:23], v[166:169], v[198:201], v[20:23]
	v_mfma_f32_16x16x32_bf16 v[16:19], v[174:177], v[198:201], v[16:19]
	v_mfma_f32_16x16x32_bf16 v[4:7], v[166:169], v[208:211], v[4:7]
	v_mfma_f32_16x16x32_bf16 v[0:3], v[174:177], v[208:211], v[0:3]
	s_barrier
	s_mov_b32 m0, s44
	s_nop 0
	global_load_lds_dwordx4 v128, s[36:37]
	s_mov_b32 m0, s45
	s_nop 0
	global_load_lds_dwordx4 v130, s[36:37]
	s_add_i32 s59, 0, 0x18000
	s_add_i32 s60, 0, 0x1c000
	s_add_u32 s28, s36, 0x100000
	s_addc_u32 s29, s37, 0
	s_mov_b32 m0, s46
	s_nop 0
	global_load_lds_dwordx4 v128, s[28:29]
	s_mov_b32 m0, s47
	s_nop 0
	global_load_lds_dwordx4 v130, s[28:29]
	v_add_u32_e32 v158, s59, v145
	v_add_u32_e32 v174, s60, v145
	ds_read_b128 v[140:143], v158
	ds_read_b128 v[150:153], v158 offset:1024
	ds_read_b128 v[154:157], v158 offset:2048
	ds_read_b128 v[158:161], v158 offset:3072
	ds_read_b128 v[162:165], v174
	ds_read_b128 v[166:169], v174 offset:1024
	ds_read_b128 v[170:173], v174 offset:2048
	ds_read_b128 v[174:177], v174 offset:3072
	ds_read_b128 v[178:181], v149 offset:32768
	ds_read_b128 v[182:185], v149 offset:33792
	ds_read_b128 v[186:189], v149 offset:34816
	ds_read_b128 v[190:193], v149 offset:35840
	ds_read_b128 v[194:197], v149 offset:36864
	ds_read_b128 v[198:201], v149 offset:37888
	ds_read_b128 v[202:205], v149 offset:38912
	ds_read_b128 v[208:211], v149 offset:39936
	s_waitcnt vmcnt(8)
	s_waitcnt lgkmcnt(0)
	s_barrier
	s_waitcnt lgkmcnt(0)
	v_mfma_f32_16x16x32_bf16 v[124:127], v[140:143], v[178:181], v[124:127]
	v_mfma_f32_16x16x32_bf16 v[120:123], v[154:157], v[178:181], v[120:123]
	v_mfma_f32_16x16x32_bf16 v[108:111], v[140:143], v[186:189], v[108:111]
	v_mfma_f32_16x16x32_bf16 v[104:107], v[154:157], v[186:189], v[104:107]
	v_mfma_f32_16x16x32_bf16 v[92:95], v[140:143], v[194:197], v[92:95]
	v_mfma_f32_16x16x32_bf16 v[88:91], v[154:157], v[194:197], v[88:91]
	v_mfma_f32_16x16x32_bf16 v[76:79], v[140:143], v[202:205], v[76:79]
	v_mfma_f32_16x16x32_bf16 v[72:75], v[154:157], v[202:205], v[72:75]
	v_mfma_f32_16x16x32_bf16 v[124:127], v[150:153], v[182:185], v[124:127]
	v_mfma_f32_16x16x32_bf16 v[120:123], v[158:161], v[182:185], v[120:123]
	v_mfma_f32_16x16x32_bf16 v[108:111], v[150:153], v[190:193], v[108:111]
	v_mfma_f32_16x16x32_bf16 v[104:107], v[158:161], v[190:193], v[104:107]
	v_mfma_f32_16x16x32_bf16 v[92:95], v[150:153], v[198:201], v[92:95]
	v_mfma_f32_16x16x32_bf16 v[88:91], v[158:161], v[198:201], v[88:91]
	v_mfma_f32_16x16x32_bf16 v[76:79], v[150:153], v[208:211], v[76:79]
	v_mfma_f32_16x16x32_bf16 v[72:75], v[158:161], v[208:211], v[72:75]
	v_mfma_f32_16x16x32_bf16 v[116:119], v[162:165], v[178:181], v[116:119]
	v_mfma_f32_16x16x32_bf16 v[112:115], v[170:173], v[178:181], v[112:115]
	v_mfma_f32_16x16x32_bf16 v[100:103], v[162:165], v[186:189], v[100:103]
	v_mfma_f32_16x16x32_bf16 v[96:99], v[170:173], v[186:189], v[96:99]
	v_mfma_f32_16x16x32_bf16 v[84:87], v[162:165], v[194:197], v[84:87]
	v_mfma_f32_16x16x32_bf16 v[80:83], v[170:173], v[194:197], v[80:83]
	v_mfma_f32_16x16x32_bf16 v[68:71], v[162:165], v[202:205], v[68:71]
	v_mfma_f32_16x16x32_bf16 v[64:67], v[170:173], v[202:205], v[64:67]
	v_mfma_f32_16x16x32_bf16 v[116:119], v[166:169], v[182:185], v[116:119]
	v_mfma_f32_16x16x32_bf16 v[112:115], v[174:177], v[182:185], v[112:115]
	v_mfma_f32_16x16x32_bf16 v[100:103], v[166:169], v[190:193], v[100:103]
	v_mfma_f32_16x16x32_bf16 v[96:99], v[174:177], v[190:193], v[96:99]
	v_mfma_f32_16x16x32_bf16 v[84:87], v[166:169], v[198:201], v[84:87]
	v_mfma_f32_16x16x32_bf16 v[80:83], v[174:177], v[198:201], v[80:83]
	v_mfma_f32_16x16x32_bf16 v[68:71], v[166:169], v[208:211], v[68:71]
	v_mfma_f32_16x16x32_bf16 v[64:67], v[174:177], v[208:211], v[64:67]
	s_barrier
	s_add_i32 s28, s59, s43
	s_mov_b32 m0, s28
	s_nop 0
	global_load_lds_dwordx4 v212, s[34:35]
	s_add_i32 m0, s28, 0x2000
	s_add_u32 s28, s34, 0x100080
	s_addc_u32 s29, s35, 0
	s_add_i32 s34, s60, s43
	global_load_lds_dwordx4 v213, s[98:99]
	ds_read_b128 v[178:181], v149 offset:49152
	ds_read_b128 v[182:185], v149 offset:50176
	ds_read_b128 v[186:189], v149 offset:51200
	ds_read_b128 v[190:193], v149 offset:52224
	s_mov_b32 m0, s34
	s_nop 0
	global_load_lds_dwordx4 v128, s[28:29]
	s_add_i32 m0, s34, 0x2000
	s_nop 0
	global_load_lds_dwordx4 v130, s[28:29]
	s_cmp_lg_u32 s58, 60
	s_cbranch_scc1 .Lbal_last_18
	s_mov_b32 m0, s49
	s_nop 0
	global_load_lds_dwordx4 v212, s[36:37]
	s_mov_b32 m0, s50
	s_nop 0
	global_load_lds_dwordx4 v213, s[36:37]
.Lbal_last_18:
	ds_read_b128 v[194:197], v149 offset:53248
	ds_read_b128 v[198:201], v149 offset:54272
	ds_read_b128 v[202:205], v149 offset:55296
	ds_read_b128 v[208:211], v149 offset:56320
	s_waitcnt vmcnt(6)
	s_waitcnt lgkmcnt(0)
	s_barrier
	s_waitcnt lgkmcnt(0)
	v_mfma_f32_16x16x32_bf16 v[60:63], v[140:143], v[178:181], v[60:63]
	v_mfma_f32_16x16x32_bf16 v[56:59], v[154:157], v[178:181], v[56:59]
	v_mfma_f32_16x16x32_bf16 v[44:47], v[140:143], v[186:189], v[44:47]
	v_mfma_f32_16x16x32_bf16 v[40:43], v[154:157], v[186:189], v[40:43]
	v_mfma_f32_16x16x32_bf16 v[28:31], v[140:143], v[194:197], v[28:31]
	v_mfma_f32_16x16x32_bf16 v[24:27], v[154:157], v[194:197], v[24:27]
	v_mfma_f32_16x16x32_bf16 v[12:15], v[140:143], v[202:205], v[12:15]
	v_mfma_f32_16x16x32_bf16 v[8:11], v[154:157], v[202:205], v[8:11]
	v_mfma_f32_16x16x32_bf16 v[60:63], v[150:153], v[182:185], v[60:63]
	v_mfma_f32_16x16x32_bf16 v[56:59], v[158:161], v[182:185], v[56:59]
	v_mfma_f32_16x16x32_bf16 v[44:47], v[150:153], v[190:193], v[44:47]
	v_mfma_f32_16x16x32_bf16 v[40:43], v[158:161], v[190:193], v[40:43]
	v_mfma_f32_16x16x32_bf16 v[28:31], v[150:153], v[198:201], v[28:31]
	v_mfma_f32_16x16x32_bf16 v[24:27], v[158:161], v[198:201], v[24:27]
	v_mfma_f32_16x16x32_bf16 v[12:15], v[150:153], v[208:211], v[12:15]
	v_mfma_f32_16x16x32_bf16 v[8:11], v[158:161], v[208:211], v[8:11]
	v_mfma_f32_16x16x32_bf16 v[52:55], v[162:165], v[178:181], v[52:55]
	v_mfma_f32_16x16x32_bf16 v[48:51], v[170:173], v[178:181], v[48:51]
	v_mfma_f32_16x16x32_bf16 v[36:39], v[162:165], v[186:189], v[36:39]
	v_mfma_f32_16x16x32_bf16 v[32:35], v[170:173], v[186:189], v[32:35]
	v_mfma_f32_16x16x32_bf16 v[20:23], v[162:165], v[194:197], v[20:23]
	v_mfma_f32_16x16x32_bf16 v[16:19], v[170:173], v[194:197], v[16:19]
	v_mfma_f32_16x16x32_bf16 v[4:7], v[162:165], v[202:205], v[4:7]
	v_mfma_f32_16x16x32_bf16 v[0:3], v[170:173], v[202:205], v[0:3]
	v_mfma_f32_16x16x32_bf16 v[52:55], v[166:169], v[182:185], v[52:55]
	v_mfma_f32_16x16x32_bf16 v[48:51], v[174:177], v[182:185], v[48:51]
	v_mfma_f32_16x16x32_bf16 v[36:39], v[166:169], v[190:193], v[36:39]
	v_mfma_f32_16x16x32_bf16 v[32:35], v[174:177], v[190:193], v[32:35]
	v_mfma_f32_16x16x32_bf16 v[20:23], v[166:169], v[198:201], v[20:23]
	v_mfma_f32_16x16x32_bf16 v[16:19], v[174:177], v[198:201], v[16:19]
	v_mfma_f32_16x16x32_bf16 v[4:7], v[166:169], v[208:211], v[4:7]
	v_mfma_f32_16x16x32_bf16 v[0:3], v[174:177], v[208:211], v[0:3]
	s_barrier
	s_add_i32 s58, s58, 2
	s_add_u32 s56, s56, 0x100
	s_addc_u32 s57, s57, 0
	s_cmp_gt_u32 s58, 61
	s_mov_b64 s[28:29], s[30:31]
	s_cbranch_scc0 .LBB0_778
	s_setprio 0
	s_and_b64 vcc, exec, s[16:17]
	s_cbranch_vccz .LBB0_781
	s_barrier

.Lbal_first_17:
	s_add_u32 s38, s36, 0xfffc0080
	s_addc_u32 s39, s37, -1
	s_cmp_eq_u32 s61, 12
	s_cselect_b32 s41, s3, s39
	s_cselect_b32 s40, s29, s38
	s_cselect_b32 s39, s27, s60
	s_cselect_b32 s38, s58, s59
	s_add_i32 m0, s46, 0xc000
	s_nop 0
	global_load_lds_dwordx4 v134, s[36:37]
	s_add_i32 m0, s46, 0xe000
	s_nop 0
	global_load_lds_dwordx4 v132, s[36:37]
	ds_read_b128 v[140:143], v153
	ds_read_b128 v[144:147], v153 offset:1024
	ds_read_b128 v[158:161], v153 offset:2048
	ds_read_b128 v[162:165], v153 offset:3072
	ds_read_b128 v[166:169], v154
	ds_read_b128 v[170:173], v154 offset:1024
	ds_read_b128 v[174:177], v154 offset:2048
	ds_read_b128 v[178:181], v154 offset:3072
	ds_read_b128 v[182:185], v155
	ds_read_b128 v[186:189], v155 offset:1024
	ds_read_b128 v[190:193], v155 offset:2048
	ds_read_b128 v[194:197], v155 offset:3072
	ds_read_b128 v[198:201], v155 offset:4096
	ds_read_b128 v[202:205], v155 offset:5120
	ds_read_b128 v[208:211], v155 offset:6144
	ds_read_b128 v[212:215], v155 offset:7168
	s_waitcnt vmcnt(8)
	s_waitcnt lgkmcnt(0)
	s_barrier
	s_waitcnt lgkmcnt(0)
	v_mfma_f32_16x16x32_bf16 v[124:127], v[140:143], v[182:185], v[124:127]
	v_mfma_f32_16x16x32_bf16 v[120:123], v[158:161], v[182:185], v[120:123]
	v_mfma_f32_16x16x32_bf16 v[108:111], v[140:143], v[190:193], v[108:111]
	v_mfma_f32_16x16x32_bf16 v[104:107], v[158:161], v[190:193], v[104:107]
	v_mfma_f32_16x16x32_bf16 v[92:95], v[140:143], v[198:201], v[92:95]
	v_mfma_f32_16x16x32_bf16 v[88:91], v[158:161], v[198:201], v[88:91]
	v_mfma_f32_16x16x32_bf16 v[76:79], v[140:143], v[208:211], v[76:79]
	v_mfma_f32_16x16x32_bf16 v[72:75], v[158:161], v[208:211], v[72:75]
	v_mfma_f32_16x16x32_bf16 v[124:127], v[144:147], v[186:189], v[124:127]
	v_mfma_f32_16x16x32_bf16 v[120:123], v[162:165], v[186:189], v[120:123]
	v_mfma_f32_16x16x32_bf16 v[108:111], v[144:147], v[194:197], v[108:111]
	v_mfma_f32_16x16x32_bf16 v[104:107], v[162:165], v[194:197], v[104:107]
	v_mfma_f32_16x16x32_bf16 v[92:95], v[144:147], v[202:205], v[92:95]
	v_mfma_f32_16x16x32_bf16 v[88:91], v[162:165], v[202:205], v[88:91]
	v_mfma_f32_16x16x32_bf16 v[76:79], v[144:147], v[212:215], v[76:79]
	v_mfma_f32_16x16x32_bf16 v[72:75], v[162:165], v[212:215], v[72:75]
	v_mfma_f32_16x16x32_bf16 v[116:119], v[166:169], v[182:185], v[116:119]
	v_mfma_f32_16x16x32_bf16 v[112:115], v[174:177], v[182:185], v[112:115]
	v_mfma_f32_16x16x32_bf16 v[100:103], v[166:169], v[190:193], v[100:103]
	v_mfma_f32_16x16x32_bf16 v[96:99], v[174:177], v[190:193], v[96:99]
	v_mfma_f32_16x16x32_bf16 v[84:87], v[166:169], v[198:201], v[84:87]
	v_mfma_f32_16x16x32_bf16 v[80:83], v[174:177], v[198:201], v[80:83]
	v_mfma_f32_16x16x32_bf16 v[68:71], v[166:169], v[208:211], v[68:71]
	v_mfma_f32_16x16x32_bf16 v[64:67], v[174:177], v[208:211], v[64:67]
	v_mfma_f32_16x16x32_bf16 v[116:119], v[170:173], v[186:189], v[116:119]
	v_mfma_f32_16x16x32_bf16 v[112:115], v[178:181], v[186:189], v[112:115]
	v_mfma_f32_16x16x32_bf16 v[100:103], v[170:173], v[194:197], v[100:103]
	v_mfma_f32_16x16x32_bf16 v[96:99], v[178:181], v[194:197], v[96:99]
	v_mfma_f32_16x16x32_bf16 v[84:87], v[170:173], v[202:205], v[84:87]
	v_mfma_f32_16x16x32_bf16 v[80:83], v[178:181], v[202:205], v[80:83]
	v_mfma_f32_16x16x32_bf16 v[68:71], v[170:173], v[212:215], v[68:71]
	v_mfma_f32_16x16x32_bf16 v[64:67], v[178:181], v[212:215], v[64:67]
	s_barrier
	s_add_i32 s62, s54, s45
	s_mov_b32 m0, s62
	s_nop 0
	global_load_lds_dwordx4 v128, s[38:39]
	s_add_i32 m0, s62, 0x2000
	s_add_u32 s62, s38, 0x40000
	s_mov_b64 s[98:99], s[38:39]
	s_addc_u32 s63, s39, 0
	s_add_i32 s64, s55, s45
	global_load_lds_dwordx4 v130, s[38:39]
	ds_read_b128 v[182:185], v155 offset:16384
	ds_read_b128 v[186:189], v155 offset:17408
	ds_read_b128 v[190:193], v155 offset:18432
	ds_read_b128 v[194:197], v155 offset:19456
	s_mov_b32 m0, s64
	s_mov_b64 s[100:101], s[40:41]
	global_load_lds_dwordx4 v128, s[62:63]
	s_add_i32 m0, s64, 0x2000
	s_nop 0
	global_load_lds_dwordx4 v130, s[62:63]
	ds_read_b128 v[198:201], v155 offset:20480
	ds_read_b128 v[202:205], v155 offset:21504
	ds_read_b128 v[208:211], v155 offset:22528
	ds_read_b128 v[212:215], v155 offset:23552
	s_waitcnt vmcnt(6)
	s_waitcnt lgkmcnt(0)
	s_barrier
	s_waitcnt lgkmcnt(0)
	v_mfma_f32_16x16x32_bf16 v[60:63], v[140:143], v[182:185], v[60:63]
	v_mfma_f32_16x16x32_bf16 v[56:59], v[158:161], v[182:185], v[56:59]
	v_mfma_f32_16x16x32_bf16 v[44:47], v[140:143], v[190:193], v[44:47]
	v_mfma_f32_16x16x32_bf16 v[40:43], v[158:161], v[190:193], v[40:43]
	v_mfma_f32_16x16x32_bf16 v[28:31], v[140:143], v[198:201], v[28:31]
	v_mfma_f32_16x16x32_bf16 v[24:27], v[158:161], v[198:201], v[24:27]
	v_mfma_f32_16x16x32_bf16 v[12:15], v[140:143], v[208:211], v[12:15]
	v_mfma_f32_16x16x32_bf16 v[8:11], v[158:161], v[208:211], v[8:11]
	v_mfma_f32_16x16x32_bf16 v[60:63], v[144:147], v[186:189], v[60:63]
	v_mfma_f32_16x16x32_bf16 v[56:59], v[162:165], v[186:189], v[56:59]
	v_mfma_f32_16x16x32_bf16 v[44:47], v[144:147], v[194:197], v[44:47]
	v_mfma_f32_16x16x32_bf16 v[40:43], v[162:165], v[194:197], v[40:43]
	v_mfma_f32_16x16x32_bf16 v[28:31], v[144:147], v[202:205], v[28:31]
	v_mfma_f32_16x16x32_bf16 v[24:27], v[162:165], v[202:205], v[24:27]
	v_mfma_f32_16x16x32_bf16 v[12:15], v[144:147], v[212:215], v[12:15]
	v_mfma_f32_16x16x32_bf16 v[8:11], v[162:165], v[212:215], v[8:11]
	v_mfma_f32_16x16x32_bf16 v[52:55], v[166:169], v[182:185], v[52:55]
	v_mfma_f32_16x16x32_bf16 v[48:51], v[174:177], v[182:185], v[48:51]
	v_mfma_f32_16x16x32_bf16 v[36:39], v[166:169], v[190:193], v[36:39]
	v_mfma_f32_16x16x32_bf16 v[32:35], v[174:177], v[190:193], v[32:35]
	v_mfma_f32_16x16x32_bf16 v[20:23], v[166:169], v[198:201], v[20:23]
	v_mfma_f32_16x16x32_bf16 v[16:19], v[174:177], v[198:201], v[16:19]
	v_mfma_f32_16x16x32_bf16 v[4:7], v[166:169], v[208:211], v[4:7]
	v_mfma_f32_16x16x32_bf16 v[0:3], v[174:177], v[208:211], v[0:3]
	v_mfma_f32_16x16x32_bf16 v[52:55], v[170:173], v[186:189], v[52:55]
	v_mfma_f32_16x16x32_bf16 v[48:51], v[178:181], v[186:189], v[48:51]
	v_mfma_f32_16x16x32_bf16 v[36:39], v[170:173], v[194:197], v[36:39]
	v_mfma_f32_16x16x32_bf16 v[32:35], v[178:181], v[194:197], v[32:35]
	v_mfma_f32_16x16x32_bf16 v[20:23], v[170:173], v[202:205], v[20:23]
	v_mfma_f32_16x16x32_bf16 v[16:19], v[178:181], v[202:205], v[16:19]
	v_mfma_f32_16x16x32_bf16 v[4:7], v[170:173], v[212:215], v[4:7]
	v_mfma_f32_16x16x32_bf16 v[0:3], v[178:181], v[212:215], v[0:3]
	s_barrier
	s_mov_b32 m0, s46
	s_nop 0
	global_load_lds_dwordx4 v128, s[40:41]
	s_mov_b32 m0, s47
	s_nop 0
	global_load_lds_dwordx4 v130, s[40:41]
	s_add_i32 s62, 0, 0x18000
	s_add_i32 s63, 0, 0x1c000
	s_add_u32 s40, s40, 0x40000
	s_addc_u32 s41, s41, 0
	s_mov_b32 m0, s48
	s_nop 0
	global_load_lds_dwordx4 v128, s[40:41]
	s_mov_b32 m0, s49
	s_nop 0
	global_load_lds_dwordx4 v130, s[40:41]
	v_add_u32_e32 v157, s62, v151
	ds_read_b128 v[140:143], v157
	ds_read_b128 v[144:147], v157 offset:1024
	ds_read_b128 v[158:161], v157 offset:2048
	ds_read_b128 v[162:165], v157 offset:3072
	v_add_u32_e32 v157, s63, v151
	ds_read_b128 v[166:169], v157
	ds_read_b128 v[170:173], v157 offset:1024
	ds_read_b128 v[174:177], v157 offset:2048
	ds_read_b128 v[178:181], v157 offset:3072
	ds_read_b128 v[182:185], v155 offset:32768
	ds_read_b128 v[186:189], v155 offset:33792
	ds_read_b128 v[190:193], v155 offset:34816
	ds_read_b128 v[194:197], v155 offset:35840
	ds_read_b128 v[198:201], v155 offset:36864
	ds_read_b128 v[202:205], v155 offset:37888
	ds_read_b128 v[208:211], v155 offset:38912
	ds_read_b128 v[212:215], v155 offset:39936
	s_waitcnt vmcnt(8)
	s_waitcnt lgkmcnt(0)
	s_barrier
	s_waitcnt lgkmcnt(0)
	v_mfma_f32_16x16x32_bf16 v[124:127], v[140:143], v[182:185], v[124:127]
	v_mfma_f32_16x16x32_bf16 v[120:123], v[158:161], v[182:185], v[120:123]
	v_mfma_f32_16x16x32_bf16 v[108:111], v[140:143], v[190:193], v[108:111]
	v_mfma_f32_16x16x32_bf16 v[104:107], v[158:161], v[190:193], v[104:107]
	v_mfma_f32_16x16x32_bf16 v[92:95], v[140:143], v[198:201], v[92:95]
	v_mfma_f32_16x16x32_bf16 v[88:91], v[158:161], v[198:201], v[88:91]
	v_mfma_f32_16x16x32_bf16 v[76:79], v[140:143], v[208:211], v[76:79]
	v_mfma_f32_16x16x32_bf16 v[72:75], v[158:161], v[208:211], v[72:75]
	v_mfma_f32_16x16x32_bf16 v[124:127], v[144:147], v[186:189], v[124:127]
	v_mfma_f32_16x16x32_bf16 v[120:123], v[162:165], v[186:189], v[120:123]
	v_mfma_f32_16x16x32_bf16 v[108:111], v[144:147], v[194:197], v[108:111]
	v_mfma_f32_16x16x32_bf16 v[104:107], v[162:165], v[194:197], v[104:107]
	v_mfma_f32_16x16x32_bf16 v[92:95], v[144:147], v[202:205], v[92:95]
	v_mfma_f32_16x16x32_bf16 v[88:91], v[162:165], v[202:205], v[88:91]
	v_mfma_f32_16x16x32_bf16 v[76:79], v[144:147], v[212:215], v[76:79]
	v_mfma_f32_16x16x32_bf16 v[72:75], v[162:165], v[212:215], v[72:75]
	v_mfma_f32_16x16x32_bf16 v[116:119], v[166:169], v[182:185], v[116:119]
	v_mfma_f32_16x16x32_bf16 v[112:115], v[174:177], v[182:185], v[112:115]
	v_mfma_f32_16x16x32_bf16 v[100:103], v[166:169], v[190:193], v[100:103]
	v_mfma_f32_16x16x32_bf16 v[96:99], v[174:177], v[190:193], v[96:99]
	v_mfma_f32_16x16x32_bf16 v[84:87], v[166:169], v[198:201], v[84:87]
	v_mfma_f32_16x16x32_bf16 v[80:83], v[174:177], v[198:201], v[80:83]
	v_mfma_f32_16x16x32_bf16 v[68:71], v[166:169], v[208:211], v[68:71]
	v_mfma_f32_16x16x32_bf16 v[64:67], v[174:177], v[208:211], v[64:67]
	v_mfma_f32_16x16x32_bf16 v[116:119], v[170:173], v[186:189], v[116:119]
	v_mfma_f32_16x16x32_bf16 v[112:115], v[178:181], v[186:189], v[112:115]
	v_mfma_f32_16x16x32_bf16 v[100:103], v[170:173], v[194:197], v[100:103]
	v_mfma_f32_16x16x32_bf16 v[96:99], v[178:181], v[194:197], v[96:99]
	v_mfma_f32_16x16x32_bf16 v[84:87], v[170:173], v[202:205], v[84:87]
	v_mfma_f32_16x16x32_bf16 v[80:83], v[178:181], v[202:205], v[80:83]
	v_mfma_f32_16x16x32_bf16 v[68:71], v[170:173], v[212:215], v[68:71]
	v_mfma_f32_16x16x32_bf16 v[64:67], v[178:181], v[212:215], v[64:67]
	s_barrier
	s_add_i32 s40, s62, s45
	s_mov_b32 m0, s40
	s_nop 0
	global_load_lds_dwordx4 v148, s[38:39]
	s_add_i32 m0, s40, 0x2000
	s_add_u32 s38, s38, 0x40080
	s_addc_u32 s39, s39, 0
	s_add_i32 s40, s63, s45
	global_load_lds_dwordx4 v149, s[98:99]
	ds_read_b128 v[182:185], v155 offset:49152
	ds_read_b128 v[186:189], v155 offset:50176
	ds_read_b128 v[190:193], v155 offset:51200
	ds_read_b128 v[194:197], v155 offset:52224
	s_mov_b32 m0, s40
	s_nop 0
	global_load_lds_dwordx4 v128, s[38:39]
	s_add_i32 m0, s40, 0x2000
	s_nop 0
	global_load_lds_dwordx4 v130, s[38:39]
	s_cmp_lg_u32 s61, 12
	s_cbranch_scc1 .Lbal_last_17
	s_mov_b32 m0, s51
	s_nop 0
	global_load_lds_dwordx4 v148, s[100:101]
	s_mov_b32 m0, s52
	s_nop 0
	global_load_lds_dwordx4 v149, s[100:101]
.Lbal_last_17:
	ds_read_b128 v[198:201], v155 offset:53248
	ds_read_b128 v[202:205], v155 offset:54272
	ds_read_b128 v[208:211], v155 offset:55296
	ds_read_b128 v[212:215], v155 offset:56320
	s_waitcnt vmcnt(6)
	s_waitcnt lgkmcnt(0)
	s_barrier
	s_waitcnt lgkmcnt(0)
	v_mfma_f32_16x16x32_bf16 v[60:63], v[140:143], v[182:185], v[60:63]
	v_mfma_f32_16x16x32_bf16 v[56:59], v[158:161], v[182:185], v[56:59]
	v_mfma_f32_16x16x32_bf16 v[44:47], v[140:143], v[190:193], v[44:47]
	v_mfma_f32_16x16x32_bf16 v[40:43], v[158:161], v[190:193], v[40:43]
	v_mfma_f32_16x16x32_bf16 v[28:31], v[140:143], v[198:201], v[28:31]
	v_mfma_f32_16x16x32_bf16 v[24:27], v[158:161], v[198:201], v[24:27]
	v_mfma_f32_16x16x32_bf16 v[12:15], v[140:143], v[208:211], v[12:15]
	v_mfma_f32_16x16x32_bf16 v[8:11], v[158:161], v[208:211], v[8:11]
	v_mfma_f32_16x16x32_bf16 v[60:63], v[144:147], v[186:189], v[60:63]
	v_mfma_f32_16x16x32_bf16 v[56:59], v[162:165], v[186:189], v[56:59]
	v_mfma_f32_16x16x32_bf16 v[44:47], v[144:147], v[194:197], v[44:47]
	v_mfma_f32_16x16x32_bf16 v[40:43], v[162:165], v[194:197], v[40:43]
	v_mfma_f32_16x16x32_bf16 v[28:31], v[144:147], v[202:205], v[28:31]
	v_mfma_f32_16x16x32_bf16 v[24:27], v[162:165], v[202:205], v[24:27]
	v_mfma_f32_16x16x32_bf16 v[12:15], v[144:147], v[212:215], v[12:15]
	v_mfma_f32_16x16x32_bf16 v[8:11], v[162:165], v[212:215], v[8:11]
	v_mfma_f32_16x16x32_bf16 v[52:55], v[166:169], v[182:185], v[52:55]
	v_mfma_f32_16x16x32_bf16 v[48:51], v[174:177], v[182:185], v[48:51]
	v_mfma_f32_16x16x32_bf16 v[36:39], v[166:169], v[190:193], v[36:39]
	v_mfma_f32_16x16x32_bf16 v[32:35], v[174:177], v[190:193], v[32:35]
	v_mfma_f32_16x16x32_bf16 v[20:23], v[166:169], v[198:201], v[20:23]
	v_mfma_f32_16x16x32_bf16 v[16:19], v[174:177], v[198:201], v[16:19]
	v_mfma_f32_16x16x32_bf16 v[4:7], v[166:169], v[208:211], v[4:7]
	v_mfma_f32_16x16x32_bf16 v[0:3], v[174:177], v[208:211], v[0:3]
	v_mfma_f32_16x16x32_bf16 v[52:55], v[170:173], v[186:189], v[52:55]
	v_mfma_f32_16x16x32_bf16 v[48:51], v[178:181], v[186:189], v[48:51]
	v_mfma_f32_16x16x32_bf16 v[36:39], v[170:173], v[194:197], v[36:39]
	v_mfma_f32_16x16x32_bf16 v[32:35], v[178:181], v[194:197], v[32:35]
	v_mfma_f32_16x16x32_bf16 v[20:23], v[170:173], v[202:205], v[20:23]
	v_mfma_f32_16x16x32_bf16 v[16:19], v[178:181], v[202:205], v[16:19]
	v_mfma_f32_16x16x32_bf16 v[4:7], v[170:173], v[212:215], v[4:7]
	v_mfma_f32_16x16x32_bf16 v[0:3], v[178:181], v[212:215], v[0:3]
	s_barrier
	s_add_i32 s61, s61, 2
	s_add_u32 s59, s59, 0x100
	s_addc_u32 s60, s60, 0
	s_add_u32 s36, s36, 0x100
	s_addc_u32 s37, s37, 0
	s_cmp_gt_u32 s61, 13
	s_cbranch_scc0 .LBB0_895
	s_setprio 0
	s_and_b64 vcc, exec, s[24:25]
	s_cbranch_vccz .LBB0_898
	s_barrier

.Lbal_first_16:
	s_add_u32 s26, s6, 0xfffc0080
	s_addc_u32 s27, s7, -1
	s_cmp_eq_u32 s53, 12
	s_cselect_b32 s29, s19, s27
	s_cselect_b32 s28, s49, s26
	s_cselect_b32 s27, s17, s52
	s_cselect_b32 s26, s50, s51
	s_add_i32 m0, s25, 0xc000
	s_nop 0
	global_load_lds_dwordx4 v138, s[6:7]
	s_add_i32 m0, s25, 0xe000
	s_nop 0
	global_load_lds_dwordx4 v136, s[6:7]
	ds_read_b128 v[144:147], v151
	ds_read_b128 v[156:159], v151 offset:1024
	ds_read_b128 v[160:163], v151 offset:2048
	ds_read_b128 v[164:167], v151 offset:3072
	ds_read_b128 v[168:171], v152
	ds_read_b128 v[172:175], v152 offset:1024
	ds_read_b128 v[176:179], v152 offset:2048
	ds_read_b128 v[180:183], v152 offset:3072
	ds_read_b128 v[184:187], v153
	ds_read_b128 v[188:191], v153 offset:1024
	ds_read_b128 v[192:195], v153 offset:2048
	ds_read_b128 v[196:199], v153 offset:3072
	ds_read_b128 v[200:203], v153 offset:4096
	ds_read_b128 v[208:211], v153 offset:5120
	ds_read_b128 v[212:215], v153 offset:6144
	ds_read_b128 v[216:219], v153 offset:7168
	s_waitcnt vmcnt(8)
	s_waitcnt lgkmcnt(0)
	s_barrier
	s_waitcnt lgkmcnt(0)
	v_mfma_f32_16x16x32_bf16 v[124:127], v[144:147], v[184:187], v[124:127]
	v_mfma_f32_16x16x32_bf16 v[120:123], v[160:163], v[184:187], v[120:123]
	v_mfma_f32_16x16x32_bf16 v[108:111], v[144:147], v[192:195], v[108:111]
	v_mfma_f32_16x16x32_bf16 v[104:107], v[160:163], v[192:195], v[104:107]
	v_mfma_f32_16x16x32_bf16 v[92:95], v[144:147], v[200:203], v[92:95]
	v_mfma_f32_16x16x32_bf16 v[88:91], v[160:163], v[200:203], v[88:91]
	v_mfma_f32_16x16x32_bf16 v[76:79], v[144:147], v[212:215], v[76:79]
	v_mfma_f32_16x16x32_bf16 v[72:75], v[160:163], v[212:215], v[72:75]
	v_mfma_f32_16x16x32_bf16 v[124:127], v[156:159], v[188:191], v[124:127]
	v_mfma_f32_16x16x32_bf16 v[120:123], v[164:167], v[188:191], v[120:123]
	v_mfma_f32_16x16x32_bf16 v[108:111], v[156:159], v[196:199], v[108:111]
	v_mfma_f32_16x16x32_bf16 v[104:107], v[164:167], v[196:199], v[104:107]
	v_mfma_f32_16x16x32_bf16 v[92:95], v[156:159], v[208:211], v[92:95]
	v_mfma_f32_16x16x32_bf16 v[88:91], v[164:167], v[208:211], v[88:91]
	v_mfma_f32_16x16x32_bf16 v[76:79], v[156:159], v[216:219], v[76:79]
	v_mfma_f32_16x16x32_bf16 v[72:75], v[164:167], v[216:219], v[72:75]
	v_mfma_f32_16x16x32_bf16 v[116:119], v[168:171], v[184:187], v[116:119]
	v_mfma_f32_16x16x32_bf16 v[112:115], v[176:179], v[184:187], v[112:115]
	v_mfma_f32_16x16x32_bf16 v[100:103], v[168:171], v[192:195], v[100:103]
	v_mfma_f32_16x16x32_bf16 v[96:99], v[176:179], v[192:195], v[96:99]
	v_mfma_f32_16x16x32_bf16 v[84:87], v[168:171], v[200:203], v[84:87]
	v_mfma_f32_16x16x32_bf16 v[80:83], v[176:179], v[200:203], v[80:83]
	v_mfma_f32_16x16x32_bf16 v[68:71], v[168:171], v[212:215], v[68:71]
	v_mfma_f32_16x16x32_bf16 v[64:67], v[176:179], v[212:215], v[64:67]
	v_mfma_f32_16x16x32_bf16 v[116:119], v[172:175], v[188:191], v[116:119]
	v_mfma_f32_16x16x32_bf16 v[112:115], v[180:183], v[188:191], v[112:115]
	v_mfma_f32_16x16x32_bf16 v[100:103], v[172:175], v[196:199], v[100:103]
	v_mfma_f32_16x16x32_bf16 v[96:99], v[180:183], v[196:199], v[96:99]
	v_mfma_f32_16x16x32_bf16 v[84:87], v[172:175], v[208:211], v[84:87]
	v_mfma_f32_16x16x32_bf16 v[80:83], v[180:183], v[208:211], v[80:83]
	v_mfma_f32_16x16x32_bf16 v[68:71], v[172:175], v[216:219], v[68:71]
	v_mfma_f32_16x16x32_bf16 v[64:67], v[180:183], v[216:219], v[64:67]
	s_barrier
	s_add_i32 s54, s45, s38
	s_mov_b32 m0, s54
	s_nop 0
	global_load_lds_dwordx4 v130, s[26:27]
	s_add_i32 m0, s54, 0x2000
	s_add_u32 s54, s26, 0x40000
	s_mov_b64 s[98:99], s[26:27]
	s_addc_u32 s55, s27, 0
	s_add_i32 s56, s46, s38
	global_load_lds_dwordx4 v134, s[26:27]
	ds_read_b128 v[184:187], v153 offset:16384
	ds_read_b128 v[188:191], v153 offset:17408
	ds_read_b128 v[192:195], v153 offset:18432
	ds_read_b128 v[196:199], v153 offset:19456
	s_mov_b32 m0, s56
	s_mov_b64 s[100:101], s[28:29]
	global_load_lds_dwordx4 v130, s[54:55]
	s_add_i32 m0, s56, 0x2000
	s_nop 0
	global_load_lds_dwordx4 v134, s[54:55]
	ds_read_b128 v[200:203], v153 offset:20480
	ds_read_b128 v[208:211], v153 offset:21504
	ds_read_b128 v[212:215], v153 offset:22528
	ds_read_b128 v[216:219], v153 offset:23552
	s_waitcnt vmcnt(6)
	s_waitcnt lgkmcnt(0)
	s_barrier
	s_waitcnt lgkmcnt(0)
	v_mfma_f32_16x16x32_bf16 v[60:63], v[144:147], v[184:187], v[60:63]
	v_mfma_f32_16x16x32_bf16 v[56:59], v[160:163], v[184:187], v[56:59]
	v_mfma_f32_16x16x32_bf16 v[44:47], v[144:147], v[192:195], v[44:47]
	v_mfma_f32_16x16x32_bf16 v[40:43], v[160:163], v[192:195], v[40:43]
	v_mfma_f32_16x16x32_bf16 v[28:31], v[144:147], v[200:203], v[28:31]
	v_mfma_f32_16x16x32_bf16 v[24:27], v[160:163], v[200:203], v[24:27]
	v_mfma_f32_16x16x32_bf16 v[12:15], v[144:147], v[212:215], v[12:15]
	v_mfma_f32_16x16x32_bf16 v[8:11], v[160:163], v[212:215], v[8:11]
	v_mfma_f32_16x16x32_bf16 v[60:63], v[156:159], v[188:191], v[60:63]
	v_mfma_f32_16x16x32_bf16 v[56:59], v[164:167], v[188:191], v[56:59]
	v_mfma_f32_16x16x32_bf16 v[44:47], v[156:159], v[196:199], v[44:47]
	v_mfma_f32_16x16x32_bf16 v[40:43], v[164:167], v[196:199], v[40:43]
	v_mfma_f32_16x16x32_bf16 v[28:31], v[156:159], v[208:211], v[28:31]
	v_mfma_f32_16x16x32_bf16 v[24:27], v[164:167], v[208:211], v[24:27]
	v_mfma_f32_16x16x32_bf16 v[12:15], v[156:159], v[216:219], v[12:15]
	v_mfma_f32_16x16x32_bf16 v[8:11], v[164:167], v[216:219], v[8:11]
	v_mfma_f32_16x16x32_bf16 v[52:55], v[168:171], v[184:187], v[52:55]
	v_mfma_f32_16x16x32_bf16 v[48:51], v[176:179], v[184:187], v[48:51]
	v_mfma_f32_16x16x32_bf16 v[36:39], v[168:171], v[192:195], v[36:39]
	v_mfma_f32_16x16x32_bf16 v[32:35], v[176:179], v[192:195], v[32:35]
	v_mfma_f32_16x16x32_bf16 v[20:23], v[168:171], v[200:203], v[20:23]
	v_mfma_f32_16x16x32_bf16 v[16:19], v[176:179], v[200:203], v[16:19]
	v_mfma_f32_16x16x32_bf16 v[4:7], v[168:171], v[212:215], v[4:7]
	v_mfma_f32_16x16x32_bf16 v[0:3], v[176:179], v[212:215], v[0:3]
	v_mfma_f32_16x16x32_bf16 v[52:55], v[172:175], v[188:191], v[52:55]
	v_mfma_f32_16x16x32_bf16 v[48:51], v[180:183], v[188:191], v[48:51]
	v_mfma_f32_16x16x32_bf16 v[36:39], v[172:175], v[196:199], v[36:39]
	v_mfma_f32_16x16x32_bf16 v[32:35], v[180:183], v[196:199], v[32:35]
	v_mfma_f32_16x16x32_bf16 v[20:23], v[172:175], v[208:211], v[20:23]
	v_mfma_f32_16x16x32_bf16 v[16:19], v[180:183], v[208:211], v[16:19]
	v_mfma_f32_16x16x32_bf16 v[4:7], v[172:175], v[216:219], v[4:7]
	v_mfma_f32_16x16x32_bf16 v[0:3], v[180:183], v[216:219], v[0:3]
	s_barrier
	s_mov_b32 m0, s25
	s_nop 0
	global_load_lds_dwordx4 v128, s[28:29]
	s_mov_b32 m0, s39
	s_nop 0
	global_load_lds_dwordx4 v132, s[28:29]
	s_add_i32 s54, 0, 0x18000
	s_add_i32 s55, 0, 0x1c000
	s_add_u32 s28, s28, 0x40000
	s_addc_u32 s29, s29, 0
	s_mov_b32 m0, s40
	s_nop 0
	global_load_lds_dwordx4 v128, s[28:29]
	s_mov_b32 m0, s41
	s_nop 0
	global_load_lds_dwordx4 v132, s[28:29]
	v_add_u32_e32 v155, s54, v149
	ds_read_b128 v[144:147], v155
	ds_read_b128 v[156:159], v155 offset:1024
	ds_read_b128 v[160:163], v155 offset:2048
	ds_read_b128 v[164:167], v155 offset:3072
	v_add_u32_e32 v155, s55, v149
	ds_read_b128 v[168:171], v155
	ds_read_b128 v[172:175], v155 offset:1024
	ds_read_b128 v[176:179], v155 offset:2048
	ds_read_b128 v[180:183], v155 offset:3072
	ds_read_b128 v[184:187], v153 offset:32768
	ds_read_b128 v[188:191], v153 offset:33792
	ds_read_b128 v[192:195], v153 offset:34816
	ds_read_b128 v[196:199], v153 offset:35840
	ds_read_b128 v[200:203], v153 offset:36864
	ds_read_b128 v[208:211], v153 offset:37888
	ds_read_b128 v[212:215], v153 offset:38912
	ds_read_b128 v[216:219], v153 offset:39936
	s_waitcnt vmcnt(8)
	s_waitcnt lgkmcnt(0)
	s_barrier
	s_waitcnt lgkmcnt(0)
	v_mfma_f32_16x16x32_bf16 v[124:127], v[144:147], v[184:187], v[124:127]
	v_mfma_f32_16x16x32_bf16 v[120:123], v[160:163], v[184:187], v[120:123]
	v_mfma_f32_16x16x32_bf16 v[108:111], v[144:147], v[192:195], v[108:111]
	v_mfma_f32_16x16x32_bf16 v[104:107], v[160:163], v[192:195], v[104:107]
	v_mfma_f32_16x16x32_bf16 v[92:95], v[144:147], v[200:203], v[92:95]
	v_mfma_f32_16x16x32_bf16 v[88:91], v[160:163], v[200:203], v[88:91]
	v_mfma_f32_16x16x32_bf16 v[76:79], v[144:147], v[212:215], v[76:79]
	v_mfma_f32_16x16x32_bf16 v[72:75], v[160:163], v[212:215], v[72:75]
	v_mfma_f32_16x16x32_bf16 v[124:127], v[156:159], v[188:191], v[124:127]
	v_mfma_f32_16x16x32_bf16 v[120:123], v[164:167], v[188:191], v[120:123]
	v_mfma_f32_16x16x32_bf16 v[108:111], v[156:159], v[196:199], v[108:111]
	v_mfma_f32_16x16x32_bf16 v[104:107], v[164:167], v[196:199], v[104:107]
	v_mfma_f32_16x16x32_bf16 v[92:95], v[156:159], v[208:211], v[92:95]
	v_mfma_f32_16x16x32_bf16 v[88:91], v[164:167], v[208:211], v[88:91]
	v_mfma_f32_16x16x32_bf16 v[76:79], v[156:159], v[216:219], v[76:79]
	v_mfma_f32_16x16x32_bf16 v[72:75], v[164:167], v[216:219], v[72:75]
	v_mfma_f32_16x16x32_bf16 v[116:119], v[168:171], v[184:187], v[116:119]
	v_mfma_f32_16x16x32_bf16 v[112:115], v[176:179], v[184:187], v[112:115]
	v_mfma_f32_16x16x32_bf16 v[100:103], v[168:171], v[192:195], v[100:103]
	v_mfma_f32_16x16x32_bf16 v[96:99], v[176:179], v[192:195], v[96:99]
	v_mfma_f32_16x16x32_bf16 v[84:87], v[168:171], v[200:203], v[84:87]
	v_mfma_f32_16x16x32_bf16 v[80:83], v[176:179], v[200:203], v[80:83]
	v_mfma_f32_16x16x32_bf16 v[68:71], v[168:171], v[212:215], v[68:71]
	v_mfma_f32_16x16x32_bf16 v[64:67], v[176:179], v[212:215], v[64:67]
	v_mfma_f32_16x16x32_bf16 v[116:119], v[172:175], v[188:191], v[116:119]
	v_mfma_f32_16x16x32_bf16 v[112:115], v[180:183], v[188:191], v[112:115]
	v_mfma_f32_16x16x32_bf16 v[100:103], v[172:175], v[196:199], v[100:103]
	v_mfma_f32_16x16x32_bf16 v[96:99], v[180:183], v[196:199], v[96:99]
	v_mfma_f32_16x16x32_bf16 v[84:87], v[172:175], v[208:211], v[84:87]
	v_mfma_f32_16x16x32_bf16 v[80:83], v[180:183], v[208:211], v[80:83]
	v_mfma_f32_16x16x32_bf16 v[68:71], v[172:175], v[216:219], v[68:71]
	v_mfma_f32_16x16x32_bf16 v[64:67], v[180:183], v[216:219], v[64:67]
	s_barrier
	s_add_i32 s28, s54, s38
	s_mov_b32 m0, s28
	s_nop 0
	global_load_lds_dwordx4 v205, s[26:27]
	s_add_i32 m0, s28, 0x2000
	s_add_u32 s26, s26, 0x40080
	s_addc_u32 s27, s27, 0
	s_add_i32 s28, s55, s38
	global_load_lds_dwordx4 v221, s[98:99]
	ds_read_b128 v[184:187], v153 offset:49152
	ds_read_b128 v[188:191], v153 offset:50176
	ds_read_b128 v[192:195], v153 offset:51200
	ds_read_b128 v[196:199], v153 offset:52224
	s_mov_b32 m0, s28
	s_nop 0
	global_load_lds_dwordx4 v130, s[26:27]
	s_add_i32 m0, s28, 0x2000
	s_nop 0
	global_load_lds_dwordx4 v134, s[26:27]
	s_cmp_lg_u32 s53, 12
	s_cbranch_scc1 .Lbal_last_16
	s_mov_b32 m0, s43
	s_nop 0
	global_load_lds_dwordx4 v204, s[100:101]
	s_mov_b32 m0, s44
	s_nop 0
	global_load_lds_dwordx4 v220, s[100:101]
.Lbal_last_16:
	ds_read_b128 v[200:203], v153 offset:53248
	ds_read_b128 v[208:211], v153 offset:54272
	ds_read_b128 v[212:215], v153 offset:55296
	ds_read_b128 v[216:219], v153 offset:56320
	s_waitcnt vmcnt(6)
	s_waitcnt lgkmcnt(0)
	s_barrier
	s_waitcnt lgkmcnt(0)
	v_mfma_f32_16x16x32_bf16 v[60:63], v[144:147], v[184:187], v[60:63]
	v_mfma_f32_16x16x32_bf16 v[56:59], v[160:163], v[184:187], v[56:59]
	v_mfma_f32_16x16x32_bf16 v[44:47], v[144:147], v[192:195], v[44:47]
	v_mfma_f32_16x16x32_bf16 v[40:43], v[160:163], v[192:195], v[40:43]
	v_mfma_f32_16x16x32_bf16 v[28:31], v[144:147], v[200:203], v[28:31]
	v_mfma_f32_16x16x32_bf16 v[24:27], v[160:163], v[200:203], v[24:27]
	v_mfma_f32_16x16x32_bf16 v[12:15], v[144:147], v[212:215], v[12:15]
	v_mfma_f32_16x16x32_bf16 v[8:11], v[160:163], v[212:215], v[8:11]
	v_mfma_f32_16x16x32_bf16 v[60:63], v[156:159], v[188:191], v[60:63]
	v_mfma_f32_16x16x32_bf16 v[56:59], v[164:167], v[188:191], v[56:59]
	v_mfma_f32_16x16x32_bf16 v[44:47], v[156:159], v[196:199], v[44:47]
	v_mfma_f32_16x16x32_bf16 v[40:43], v[164:167], v[196:199], v[40:43]
	v_mfma_f32_16x16x32_bf16 v[28:31], v[156:159], v[208:211], v[28:31]
	v_mfma_f32_16x16x32_bf16 v[24:27], v[164:167], v[208:211], v[24:27]
	v_mfma_f32_16x16x32_bf16 v[12:15], v[156:159], v[216:219], v[12:15]
	v_mfma_f32_16x16x32_bf16 v[8:11], v[164:167], v[216:219], v[8:11]
	v_mfma_f32_16x16x32_bf16 v[52:55], v[168:171], v[184:187], v[52:55]
	v_mfma_f32_16x16x32_bf16 v[48:51], v[176:179], v[184:187], v[48:51]
	v_mfma_f32_16x16x32_bf16 v[36:39], v[168:171], v[192:195], v[36:39]
	v_mfma_f32_16x16x32_bf16 v[32:35], v[176:179], v[192:195], v[32:35]
	v_mfma_f32_16x16x32_bf16 v[20:23], v[168:171], v[200:203], v[20:23]
	v_mfma_f32_16x16x32_bf16 v[16:19], v[176:179], v[200:203], v[16:19]
	v_mfma_f32_16x16x32_bf16 v[4:7], v[168:171], v[212:215], v[4:7]
	v_mfma_f32_16x16x32_bf16 v[0:3], v[176:179], v[212:215], v[0:3]
	v_mfma_f32_16x16x32_bf16 v[52:55], v[172:175], v[188:191], v[52:55]
	v_mfma_f32_16x16x32_bf16 v[48:51], v[180:183], v[188:191], v[48:51]
	v_mfma_f32_16x16x32_bf16 v[36:39], v[172:175], v[196:199], v[36:39]
	v_mfma_f32_16x16x32_bf16 v[32:35], v[180:183], v[196:199], v[32:35]
	v_mfma_f32_16x16x32_bf16 v[20:23], v[172:175], v[208:211], v[20:23]
	v_mfma_f32_16x16x32_bf16 v[16:19], v[180:183], v[208:211], v[16:19]
	v_mfma_f32_16x16x32_bf16 v[4:7], v[172:175], v[216:219], v[4:7]
	v_mfma_f32_16x16x32_bf16 v[0:3], v[180:183], v[216:219], v[0:3]
	s_barrier
	s_add_i32 s53, s53, 2
	s_add_u32 s51, s51, 0x100
	s_addc_u32 s52, s52, 0
	s_add_u32 s6, s6, 0x100
	s_addc_u32 s7, s7, 0
	s_cmp_gt_u32 s53, 13
	s_cbranch_scc0 .LBB0_988
	s_setprio 0
	s_and_b64 vcc, exec, s[14:15]
	s_cbranch_vccz .LBB0_991
	s_barrier

.Lbal_first_15:
	s_add_u32 s26, s24, 0xfffe0080
	s_addc_u32 s27, s25, -1
	s_cmp_eq_u32 s50, 4
	s_cselect_b32 s29, s17, s27
	s_cselect_b32 s28, s46, s26
	s_cselect_b32 s27, s15, s49
	s_cselect_b32 s26, s47, s48
	s_add_i32 m0, s23, 0xc000
	s_nop 0
	global_load_lds_dwordx4 v138, s[24:25]
	s_add_i32 m0, s23, 0xe000
	s_nop 0
	global_load_lds_dwordx4 v136, s[24:25]
	ds_read_b128 v[144:147], v151
	ds_read_b128 v[154:157], v151 offset:1024
	ds_read_b128 v[158:161], v151 offset:2048
	ds_read_b128 v[162:165], v151 offset:3072
	ds_read_b128 v[166:169], v152
	ds_read_b128 v[170:173], v152 offset:1024
	ds_read_b128 v[174:177], v152 offset:2048
	ds_read_b128 v[178:181], v152 offset:3072
	ds_read_b128 v[182:185], v153
	ds_read_b128 v[186:189], v153 offset:1024
	ds_read_b128 v[190:193], v153 offset:2048
	ds_read_b128 v[194:197], v153 offset:3072
	ds_read_b128 v[198:201], v153 offset:4096
	ds_read_b128 v[202:205], v153 offset:5120
	ds_read_b128 v[208:211], v153 offset:6144
	ds_read_b128 v[212:215], v153 offset:7168
	s_waitcnt vmcnt(8)
	s_waitcnt lgkmcnt(0)
	s_barrier
	s_waitcnt lgkmcnt(0)
	v_mfma_f32_16x16x32_bf16 v[124:127], v[144:147], v[182:185], v[124:127]
	v_mfma_f32_16x16x32_bf16 v[120:123], v[158:161], v[182:185], v[120:123]
	v_mfma_f32_16x16x32_bf16 v[108:111], v[144:147], v[190:193], v[108:111]
	v_mfma_f32_16x16x32_bf16 v[104:107], v[158:161], v[190:193], v[104:107]
	v_mfma_f32_16x16x32_bf16 v[92:95], v[144:147], v[198:201], v[92:95]
	v_mfma_f32_16x16x32_bf16 v[88:91], v[158:161], v[198:201], v[88:91]
	v_mfma_f32_16x16x32_bf16 v[76:79], v[144:147], v[208:211], v[76:79]
	v_mfma_f32_16x16x32_bf16 v[72:75], v[158:161], v[208:211], v[72:75]
	v_mfma_f32_16x16x32_bf16 v[124:127], v[154:157], v[186:189], v[124:127]
	v_mfma_f32_16x16x32_bf16 v[120:123], v[162:165], v[186:189], v[120:123]
	v_mfma_f32_16x16x32_bf16 v[108:111], v[154:157], v[194:197], v[108:111]
	v_mfma_f32_16x16x32_bf16 v[104:107], v[162:165], v[194:197], v[104:107]
	v_mfma_f32_16x16x32_bf16 v[92:95], v[154:157], v[202:205], v[92:95]
	v_mfma_f32_16x16x32_bf16 v[88:91], v[162:165], v[202:205], v[88:91]
	v_mfma_f32_16x16x32_bf16 v[76:79], v[154:157], v[212:215], v[76:79]
	v_mfma_f32_16x16x32_bf16 v[72:75], v[162:165], v[212:215], v[72:75]
	v_mfma_f32_16x16x32_bf16 v[116:119], v[166:169], v[182:185], v[116:119]
	v_mfma_f32_16x16x32_bf16 v[112:115], v[174:177], v[182:185], v[112:115]
	v_mfma_f32_16x16x32_bf16 v[100:103], v[166:169], v[190:193], v[100:103]
	v_mfma_f32_16x16x32_bf16 v[96:99], v[174:177], v[190:193], v[96:99]
	v_mfma_f32_16x16x32_bf16 v[84:87], v[166:169], v[198:201], v[84:87]
	v_mfma_f32_16x16x32_bf16 v[80:83], v[174:177], v[198:201], v[80:83]
	v_mfma_f32_16x16x32_bf16 v[68:71], v[166:169], v[208:211], v[68:71]
	v_mfma_f32_16x16x32_bf16 v[64:67], v[174:177], v[208:211], v[64:67]
	v_mfma_f32_16x16x32_bf16 v[116:119], v[170:173], v[186:189], v[116:119]
	v_mfma_f32_16x16x32_bf16 v[112:115], v[178:181], v[186:189], v[112:115]
	v_mfma_f32_16x16x32_bf16 v[100:103], v[170:173], v[194:197], v[100:103]
	v_mfma_f32_16x16x32_bf16 v[96:99], v[178:181], v[194:197], v[96:99]
	v_mfma_f32_16x16x32_bf16 v[84:87], v[170:173], v[202:205], v[84:87]
	v_mfma_f32_16x16x32_bf16 v[80:83], v[178:181], v[202:205], v[80:83]
	v_mfma_f32_16x16x32_bf16 v[68:71], v[170:173], v[212:215], v[68:71]
	v_mfma_f32_16x16x32_bf16 v[64:67], v[178:181], v[212:215], v[64:67]
	s_barrier
	s_add_i32 s51, s43, s36
	s_mov_b32 m0, s51
	s_nop 0
	global_load_lds_dwordx4 v130, s[26:27]
	s_add_i32 m0, s51, 0x2000
	s_add_u32 s52, s26, 0x20000
	s_mov_b64 s[98:99], s[26:27]
	s_addc_u32 s53, s27, 0
	s_add_i32 s51, s44, s36
	global_load_lds_dwordx4 v134, s[26:27]
	ds_read_b128 v[182:185], v153 offset:16384
	ds_read_b128 v[186:189], v153 offset:17408
	ds_read_b128 v[190:193], v153 offset:18432
	ds_read_b128 v[194:197], v153 offset:19456
	s_mov_b32 m0, s51
	s_mov_b64 s[100:101], s[28:29]
	global_load_lds_dwordx4 v130, s[52:53]
	s_add_i32 m0, s51, 0x2000
	s_nop 0
	global_load_lds_dwordx4 v134, s[52:53]
	ds_read_b128 v[198:201], v153 offset:20480
	ds_read_b128 v[202:205], v153 offset:21504
	ds_read_b128 v[208:211], v153 offset:22528
	ds_read_b128 v[212:215], v153 offset:23552
	s_waitcnt vmcnt(6)
	s_waitcnt lgkmcnt(0)
	s_barrier
	s_waitcnt lgkmcnt(0)
	v_mfma_f32_16x16x32_bf16 v[60:63], v[144:147], v[182:185], v[60:63]
	v_mfma_f32_16x16x32_bf16 v[56:59], v[158:161], v[182:185], v[56:59]
	v_mfma_f32_16x16x32_bf16 v[44:47], v[144:147], v[190:193], v[44:47]
	v_mfma_f32_16x16x32_bf16 v[40:43], v[158:161], v[190:193], v[40:43]
	v_mfma_f32_16x16x32_bf16 v[28:31], v[144:147], v[198:201], v[28:31]
	v_mfma_f32_16x16x32_bf16 v[24:27], v[158:161], v[198:201], v[24:27]
	v_mfma_f32_16x16x32_bf16 v[12:15], v[144:147], v[208:211], v[12:15]
	v_mfma_f32_16x16x32_bf16 v[8:11], v[158:161], v[208:211], v[8:11]
	v_mfma_f32_16x16x32_bf16 v[60:63], v[154:157], v[186:189], v[60:63]
	v_mfma_f32_16x16x32_bf16 v[56:59], v[162:165], v[186:189], v[56:59]
	v_mfma_f32_16x16x32_bf16 v[44:47], v[154:157], v[194:197], v[44:47]
	v_mfma_f32_16x16x32_bf16 v[40:43], v[162:165], v[194:197], v[40:43]
	v_mfma_f32_16x16x32_bf16 v[28:31], v[154:157], v[202:205], v[28:31]
	v_mfma_f32_16x16x32_bf16 v[24:27], v[162:165], v[202:205], v[24:27]
	v_mfma_f32_16x16x32_bf16 v[12:15], v[154:157], v[212:215], v[12:15]
	v_mfma_f32_16x16x32_bf16 v[8:11], v[162:165], v[212:215], v[8:11]
	v_mfma_f32_16x16x32_bf16 v[52:55], v[166:169], v[182:185], v[52:55]
	v_mfma_f32_16x16x32_bf16 v[48:51], v[174:177], v[182:185], v[48:51]
	v_mfma_f32_16x16x32_bf16 v[36:39], v[166:169], v[190:193], v[36:39]
	v_mfma_f32_16x16x32_bf16 v[32:35], v[174:177], v[190:193], v[32:35]
	v_mfma_f32_16x16x32_bf16 v[20:23], v[166:169], v[198:201], v[20:23]
	v_mfma_f32_16x16x32_bf16 v[16:19], v[174:177], v[198:201], v[16:19]
	v_mfma_f32_16x16x32_bf16 v[4:7], v[166:169], v[208:211], v[4:7]
	v_mfma_f32_16x16x32_bf16 v[0:3], v[174:177], v[208:211], v[0:3]
	v_mfma_f32_16x16x32_bf16 v[52:55], v[170:173], v[186:189], v[52:55]
	v_mfma_f32_16x16x32_bf16 v[48:51], v[178:181], v[186:189], v[48:51]
	v_mfma_f32_16x16x32_bf16 v[36:39], v[170:173], v[194:197], v[36:39]
	v_mfma_f32_16x16x32_bf16 v[32:35], v[178:181], v[194:197], v[32:35]
	v_mfma_f32_16x16x32_bf16 v[20:23], v[170:173], v[202:205], v[20:23]
	v_mfma_f32_16x16x32_bf16 v[16:19], v[178:181], v[202:205], v[16:19]
	v_mfma_f32_16x16x32_bf16 v[4:7], v[170:173], v[212:215], v[4:7]
	v_mfma_f32_16x16x32_bf16 v[0:3], v[178:181], v[212:215], v[0:3]
	s_barrier
	s_mov_b32 m0, s23
	s_nop 0
	global_load_lds_dwordx4 v128, s[28:29]
	s_mov_b32 m0, s37
	s_nop 0
	global_load_lds_dwordx4 v132, s[28:29]
	s_add_i32 s51, 0, 0x18000
	s_add_i32 s52, 0, 0x1c000
	s_add_u32 s28, s28, 0x20000
	s_addc_u32 s29, s29, 0
	s_mov_b32 m0, s38
	s_nop 0
	global_load_lds_dwordx4 v128, s[28:29]
	s_mov_b32 m0, s39
	s_nop 0
	global_load_lds_dwordx4 v132, s[28:29]
	v_add_u32_e32 v162, s51, v149
	v_add_u32_e32 v178, s52, v149
	ds_read_b128 v[144:147], v162
	ds_read_b128 v[154:157], v162 offset:1024
	ds_read_b128 v[158:161], v162 offset:2048
	ds_read_b128 v[162:165], v162 offset:3072
	ds_read_b128 v[166:169], v178
	ds_read_b128 v[170:173], v178 offset:1024
	ds_read_b128 v[174:177], v178 offset:2048
	ds_read_b128 v[178:181], v178 offset:3072
	ds_read_b128 v[182:185], v153 offset:32768
	ds_read_b128 v[186:189], v153 offset:33792
	ds_read_b128 v[190:193], v153 offset:34816
	ds_read_b128 v[194:197], v153 offset:35840
	ds_read_b128 v[198:201], v153 offset:36864
	ds_read_b128 v[202:205], v153 offset:37888
	ds_read_b128 v[208:211], v153 offset:38912
	ds_read_b128 v[212:215], v153 offset:39936
	s_waitcnt vmcnt(8)
	s_waitcnt lgkmcnt(0)
	s_barrier
	s_waitcnt lgkmcnt(0)
	v_mfma_f32_16x16x32_bf16 v[124:127], v[144:147], v[182:185], v[124:127]
	v_mfma_f32_16x16x32_bf16 v[120:123], v[158:161], v[182:185], v[120:123]
	v_mfma_f32_16x16x32_bf16 v[108:111], v[144:147], v[190:193], v[108:111]
	v_mfma_f32_16x16x32_bf16 v[104:107], v[158:161], v[190:193], v[104:107]
	v_mfma_f32_16x16x32_bf16 v[92:95], v[144:147], v[198:201], v[92:95]
	v_mfma_f32_16x16x32_bf16 v[88:91], v[158:161], v[198:201], v[88:91]
	v_mfma_f32_16x16x32_bf16 v[76:79], v[144:147], v[208:211], v[76:79]
	v_mfma_f32_16x16x32_bf16 v[72:75], v[158:161], v[208:211], v[72:75]
	v_mfma_f32_16x16x32_bf16 v[124:127], v[154:157], v[186:189], v[124:127]
	v_mfma_f32_16x16x32_bf16 v[120:123], v[162:165], v[186:189], v[120:123]
	v_mfma_f32_16x16x32_bf16 v[108:111], v[154:157], v[194:197], v[108:111]
	v_mfma_f32_16x16x32_bf16 v[104:107], v[162:165], v[194:197], v[104:107]
	v_mfma_f32_16x16x32_bf16 v[92:95], v[154:157], v[202:205], v[92:95]
	v_mfma_f32_16x16x32_bf16 v[88:91], v[162:165], v[202:205], v[88:91]
	v_mfma_f32_16x16x32_bf16 v[76:79], v[154:157], v[212:215], v[76:79]
	v_mfma_f32_16x16x32_bf16 v[72:75], v[162:165], v[212:215], v[72:75]
	v_mfma_f32_16x16x32_bf16 v[116:119], v[166:169], v[182:185], v[116:119]
	v_mfma_f32_16x16x32_bf16 v[112:115], v[174:177], v[182:185], v[112:115]
	v_mfma_f32_16x16x32_bf16 v[100:103], v[166:169], v[190:193], v[100:103]
	v_mfma_f32_16x16x32_bf16 v[96:99], v[174:177], v[190:193], v[96:99]
	v_mfma_f32_16x16x32_bf16 v[84:87], v[166:169], v[198:201], v[84:87]
	v_mfma_f32_16x16x32_bf16 v[80:83], v[174:177], v[198:201], v[80:83]
	v_mfma_f32_16x16x32_bf16 v[68:71], v[166:169], v[208:211], v[68:71]
	v_mfma_f32_16x16x32_bf16 v[64:67], v[174:177], v[208:211], v[64:67]
	v_mfma_f32_16x16x32_bf16 v[116:119], v[170:173], v[186:189], v[116:119]
	v_mfma_f32_16x16x32_bf16 v[112:115], v[178:181], v[186:189], v[112:115]
	v_mfma_f32_16x16x32_bf16 v[100:103], v[170:173], v[194:197], v[100:103]
	v_mfma_f32_16x16x32_bf16 v[96:99], v[178:181], v[194:197], v[96:99]
	v_mfma_f32_16x16x32_bf16 v[84:87], v[170:173], v[202:205], v[84:87]
	v_mfma_f32_16x16x32_bf16 v[80:83], v[178:181], v[202:205], v[80:83]
	v_mfma_f32_16x16x32_bf16 v[68:71], v[170:173], v[212:215], v[68:71]
	v_mfma_f32_16x16x32_bf16 v[64:67], v[178:181], v[212:215], v[64:67]
	s_barrier
	s_add_i32 s28, s51, s36
	s_mov_b32 m0, s28
	s_nop 0
	global_load_lds_dwordx4 v217, s[26:27]
	s_add_i32 m0, s28, 0x2000
	s_add_u32 s26, s26, 0x20080
	s_addc_u32 s27, s27, 0
	s_add_i32 s28, s52, s36
	global_load_lds_dwordx4 v219, s[98:99]
	ds_read_b128 v[182:185], v153 offset:49152
	ds_read_b128 v[186:189], v153 offset:50176
	ds_read_b128 v[190:193], v153 offset:51200
	ds_read_b128 v[194:197], v153 offset:52224
	s_mov_b32 m0, s28
	s_nop 0
	global_load_lds_dwordx4 v130, s[26:27]
	s_add_i32 m0, s28, 0x2000
	s_nop 0
	global_load_lds_dwordx4 v134, s[26:27]
	s_cmp_lg_u32 s50, 4
	s_cbranch_scc1 .Lbal_last_15
	s_mov_b32 m0, s41
	s_nop 0
	global_load_lds_dwordx4 v216, s[100:101]
	s_mov_b32 m0, s42
	s_nop 0
	global_load_lds_dwordx4 v218, s[100:101]
.Lbal_last_15:
	ds_read_b128 v[198:201], v153 offset:53248
	ds_read_b128 v[202:205], v153 offset:54272
	ds_read_b128 v[208:211], v153 offset:55296
	ds_read_b128 v[212:215], v153 offset:56320
	s_waitcnt vmcnt(6)
	s_waitcnt lgkmcnt(0)
	s_barrier
	s_waitcnt lgkmcnt(0)
	v_mfma_f32_16x16x32_bf16 v[60:63], v[144:147], v[182:185], v[60:63]
	v_mfma_f32_16x16x32_bf16 v[56:59], v[158:161], v[182:185], v[56:59]
	v_mfma_f32_16x16x32_bf16 v[44:47], v[144:147], v[190:193], v[44:47]
	v_mfma_f32_16x16x32_bf16 v[40:43], v[158:161], v[190:193], v[40:43]
	v_mfma_f32_16x16x32_bf16 v[28:31], v[144:147], v[198:201], v[28:31]
	v_mfma_f32_16x16x32_bf16 v[24:27], v[158:161], v[198:201], v[24:27]
	v_mfma_f32_16x16x32_bf16 v[12:15], v[144:147], v[208:211], v[12:15]
	v_mfma_f32_16x16x32_bf16 v[8:11], v[158:161], v[208:211], v[8:11]
	v_mfma_f32_16x16x32_bf16 v[60:63], v[154:157], v[186:189], v[60:63]
	v_mfma_f32_16x16x32_bf16 v[56:59], v[162:165], v[186:189], v[56:59]
	v_mfma_f32_16x16x32_bf16 v[44:47], v[154:157], v[194:197], v[44:47]
	v_mfma_f32_16x16x32_bf16 v[40:43], v[162:165], v[194:197], v[40:43]
	v_mfma_f32_16x16x32_bf16 v[28:31], v[154:157], v[202:205], v[28:31]
	v_mfma_f32_16x16x32_bf16 v[24:27], v[162:165], v[202:205], v[24:27]
	v_mfma_f32_16x16x32_bf16 v[12:15], v[154:157], v[212:215], v[12:15]
	v_mfma_f32_16x16x32_bf16 v[8:11], v[162:165], v[212:215], v[8:11]
	v_mfma_f32_16x16x32_bf16 v[52:55], v[166:169], v[182:185], v[52:55]
	v_mfma_f32_16x16x32_bf16 v[48:51], v[174:177], v[182:185], v[48:51]
	v_mfma_f32_16x16x32_bf16 v[36:39], v[166:169], v[190:193], v[36:39]
	v_mfma_f32_16x16x32_bf16 v[32:35], v[174:177], v[190:193], v[32:35]
	v_mfma_f32_16x16x32_bf16 v[20:23], v[166:169], v[198:201], v[20:23]
	v_mfma_f32_16x16x32_bf16 v[16:19], v[174:177], v[198:201], v[16:19]
	v_mfma_f32_16x16x32_bf16 v[4:7], v[166:169], v[208:211], v[4:7]
	v_mfma_f32_16x16x32_bf16 v[0:3], v[174:177], v[208:211], v[0:3]
	v_mfma_f32_16x16x32_bf16 v[52:55], v[170:173], v[186:189], v[52:55]
	v_mfma_f32_16x16x32_bf16 v[48:51], v[178:181], v[186:189], v[48:51]
	v_mfma_f32_16x16x32_bf16 v[36:39], v[170:173], v[194:197], v[36:39]
	v_mfma_f32_16x16x32_bf16 v[32:35], v[178:181], v[194:197], v[32:35]
	v_mfma_f32_16x16x32_bf16 v[20:23], v[170:173], v[202:205], v[20:23]
	v_mfma_f32_16x16x32_bf16 v[16:19], v[178:181], v[202:205], v[16:19]
	v_mfma_f32_16x16x32_bf16 v[4:7], v[170:173], v[212:215], v[4:7]
	v_mfma_f32_16x16x32_bf16 v[0:3], v[178:181], v[212:215], v[0:3]
	s_barrier
	s_add_i32 s50, s50, 2
	s_add_u32 s48, s48, 0x100
	s_addc_u32 s49, s49, 0
	s_add_u32 s24, s24, 0x100
	s_addc_u32 s25, s25, 0
	s_cmp_gt_u32 s50, 5
	s_cbranch_scc0 .LBB0_1193
	s_setprio 0
	s_and_b64 vcc, exec, s[12:13]
	s_cbranch_vccz .LBB0_1196
	s_barrier

.Lbal_first_13:
	s_add_u32 s26, s24, 0xfffc0080
	s_addc_u32 s27, s25, -1
	s_cmp_eq_u32 s53, 12
	s_cselect_b32 s29, s19, s27
	s_cselect_b32 s28, s49, s26
	s_cselect_b32 s27, s17, s52
	s_cselect_b32 s26, s50, s51
	s_add_i32 m0, s39, 0xc000
	s_nop 0
	global_load_lds_dwordx4 v138, s[24:25]
	s_add_i32 m0, s39, 0xe000
	s_nop 0
	global_load_lds_dwordx4 v136, s[24:25]
	ds_read_b128 v[144:147], v151
	ds_read_b128 v[156:159], v151 offset:1024
	ds_read_b128 v[160:163], v151 offset:2048
	ds_read_b128 v[164:167], v151 offset:3072
	ds_read_b128 v[168:171], v152
	ds_read_b128 v[172:175], v152 offset:1024
	ds_read_b128 v[176:179], v152 offset:2048
	ds_read_b128 v[180:183], v152 offset:3072
	ds_read_b128 v[184:187], v153
	ds_read_b128 v[188:191], v153 offset:1024
	ds_read_b128 v[192:195], v153 offset:2048
	ds_read_b128 v[196:199], v153 offset:3072
	ds_read_b128 v[200:203], v153 offset:4096
	ds_read_b128 v[208:211], v153 offset:5120
	ds_read_b128 v[212:215], v153 offset:6144
	ds_read_b128 v[216:219], v153 offset:7168
	s_waitcnt vmcnt(8)
	s_waitcnt lgkmcnt(0)
	s_barrier
	s_waitcnt lgkmcnt(0)
	v_mfma_f32_16x16x32_bf16 v[124:127], v[144:147], v[184:187], v[124:127]
	v_mfma_f32_16x16x32_bf16 v[120:123], v[160:163], v[184:187], v[120:123]
	v_mfma_f32_16x16x32_bf16 v[108:111], v[144:147], v[192:195], v[108:111]
	v_mfma_f32_16x16x32_bf16 v[104:107], v[160:163], v[192:195], v[104:107]
	v_mfma_f32_16x16x32_bf16 v[92:95], v[144:147], v[200:203], v[92:95]
	v_mfma_f32_16x16x32_bf16 v[88:91], v[160:163], v[200:203], v[88:91]
	v_mfma_f32_16x16x32_bf16 v[76:79], v[144:147], v[212:215], v[76:79]
	v_mfma_f32_16x16x32_bf16 v[72:75], v[160:163], v[212:215], v[72:75]
	v_mfma_f32_16x16x32_bf16 v[124:127], v[156:159], v[188:191], v[124:127]
	v_mfma_f32_16x16x32_bf16 v[120:123], v[164:167], v[188:191], v[120:123]
	v_mfma_f32_16x16x32_bf16 v[108:111], v[156:159], v[196:199], v[108:111]
	v_mfma_f32_16x16x32_bf16 v[104:107], v[164:167], v[196:199], v[104:107]
	v_mfma_f32_16x16x32_bf16 v[92:95], v[156:159], v[208:211], v[92:95]
	v_mfma_f32_16x16x32_bf16 v[88:91], v[164:167], v[208:211], v[88:91]
	v_mfma_f32_16x16x32_bf16 v[76:79], v[156:159], v[216:219], v[76:79]
	v_mfma_f32_16x16x32_bf16 v[72:75], v[164:167], v[216:219], v[72:75]
	v_mfma_f32_16x16x32_bf16 v[116:119], v[168:171], v[184:187], v[116:119]
	v_mfma_f32_16x16x32_bf16 v[112:115], v[176:179], v[184:187], v[112:115]
	v_mfma_f32_16x16x32_bf16 v[100:103], v[168:171], v[192:195], v[100:103]
	v_mfma_f32_16x16x32_bf16 v[96:99], v[176:179], v[192:195], v[96:99]
	v_mfma_f32_16x16x32_bf16 v[84:87], v[168:171], v[200:203], v[84:87]
	v_mfma_f32_16x16x32_bf16 v[80:83], v[176:179], v[200:203], v[80:83]
	v_mfma_f32_16x16x32_bf16 v[68:71], v[168:171], v[212:215], v[68:71]
	v_mfma_f32_16x16x32_bf16 v[64:67], v[176:179], v[212:215], v[64:67]
	v_mfma_f32_16x16x32_bf16 v[116:119], v[172:175], v[188:191], v[116:119]
	v_mfma_f32_16x16x32_bf16 v[112:115], v[180:183], v[188:191], v[112:115]
	v_mfma_f32_16x16x32_bf16 v[100:103], v[172:175], v[196:199], v[100:103]
	v_mfma_f32_16x16x32_bf16 v[96:99], v[180:183], v[196:199], v[96:99]
	v_mfma_f32_16x16x32_bf16 v[84:87], v[172:175], v[208:211], v[84:87]
	v_mfma_f32_16x16x32_bf16 v[80:83], v[180:183], v[208:211], v[80:83]
	v_mfma_f32_16x16x32_bf16 v[68:71], v[172:175], v[216:219], v[68:71]
	v_mfma_f32_16x16x32_bf16 v[64:67], v[180:183], v[216:219], v[64:67]
	s_barrier
	s_add_i32 s54, s46, s38
	s_mov_b32 m0, s54
	s_nop 0
	global_load_lds_dwordx4 v130, s[26:27]
	s_add_i32 m0, s54, 0x2000
	s_add_u32 s54, s26, 0x40000
	s_mov_b64 s[98:99], s[26:27]
	s_addc_u32 s55, s27, 0
	s_add_i32 s56, s47, s38
	global_load_lds_dwordx4 v134, s[26:27]
	ds_read_b128 v[184:187], v153 offset:16384
	ds_read_b128 v[188:191], v153 offset:17408
	ds_read_b128 v[192:195], v153 offset:18432
	ds_read_b128 v[196:199], v153 offset:19456
	s_mov_b32 m0, s56
	s_mov_b64 s[100:101], s[28:29]
	global_load_lds_dwordx4 v130, s[54:55]
	s_add_i32 m0, s56, 0x2000
	s_nop 0
	global_load_lds_dwordx4 v134, s[54:55]
	ds_read_b128 v[200:203], v153 offset:20480
	ds_read_b128 v[208:211], v153 offset:21504
	ds_read_b128 v[212:215], v153 offset:22528
	ds_read_b128 v[216:219], v153 offset:23552
	s_waitcnt vmcnt(6)
	s_waitcnt lgkmcnt(0)
	s_barrier
	s_waitcnt lgkmcnt(0)
	v_mfma_f32_16x16x32_bf16 v[60:63], v[144:147], v[184:187], v[60:63]
	v_mfma_f32_16x16x32_bf16 v[56:59], v[160:163], v[184:187], v[56:59]
	v_mfma_f32_16x16x32_bf16 v[44:47], v[144:147], v[192:195], v[44:47]
	v_mfma_f32_16x16x32_bf16 v[40:43], v[160:163], v[192:195], v[40:43]
	v_mfma_f32_16x16x32_bf16 v[28:31], v[144:147], v[200:203], v[28:31]
	v_mfma_f32_16x16x32_bf16 v[24:27], v[160:163], v[200:203], v[24:27]
	v_mfma_f32_16x16x32_bf16 v[12:15], v[144:147], v[212:215], v[12:15]
	v_mfma_f32_16x16x32_bf16 v[8:11], v[160:163], v[212:215], v[8:11]
	v_mfma_f32_16x16x32_bf16 v[60:63], v[156:159], v[188:191], v[60:63]
	v_mfma_f32_16x16x32_bf16 v[56:59], v[164:167], v[188:191], v[56:59]
	v_mfma_f32_16x16x32_bf16 v[44:47], v[156:159], v[196:199], v[44:47]
	v_mfma_f32_16x16x32_bf16 v[40:43], v[164:167], v[196:199], v[40:43]
	v_mfma_f32_16x16x32_bf16 v[28:31], v[156:159], v[208:211], v[28:31]
	v_mfma_f32_16x16x32_bf16 v[24:27], v[164:167], v[208:211], v[24:27]
	v_mfma_f32_16x16x32_bf16 v[12:15], v[156:159], v[216:219], v[12:15]
	v_mfma_f32_16x16x32_bf16 v[8:11], v[164:167], v[216:219], v[8:11]
	v_mfma_f32_16x16x32_bf16 v[52:55], v[168:171], v[184:187], v[52:55]
	v_mfma_f32_16x16x32_bf16 v[48:51], v[176:179], v[184:187], v[48:51]
	v_mfma_f32_16x16x32_bf16 v[36:39], v[168:171], v[192:195], v[36:39]
	v_mfma_f32_16x16x32_bf16 v[32:35], v[176:179], v[192:195], v[32:35]
	v_mfma_f32_16x16x32_bf16 v[20:23], v[168:171], v[200:203], v[20:23]
	v_mfma_f32_16x16x32_bf16 v[16:19], v[176:179], v[200:203], v[16:19]
	v_mfma_f32_16x16x32_bf16 v[4:7], v[168:171], v[212:215], v[4:7]
	v_mfma_f32_16x16x32_bf16 v[0:3], v[176:179], v[212:215], v[0:3]
	v_mfma_f32_16x16x32_bf16 v[52:55], v[172:175], v[188:191], v[52:55]
	v_mfma_f32_16x16x32_bf16 v[48:51], v[180:183], v[188:191], v[48:51]
	v_mfma_f32_16x16x32_bf16 v[36:39], v[172:175], v[196:199], v[36:39]
	v_mfma_f32_16x16x32_bf16 v[32:35], v[180:183], v[196:199], v[32:35]
	v_mfma_f32_16x16x32_bf16 v[20:23], v[172:175], v[208:211], v[20:23]
	v_mfma_f32_16x16x32_bf16 v[16:19], v[180:183], v[208:211], v[16:19]
	v_mfma_f32_16x16x32_bf16 v[4:7], v[172:175], v[216:219], v[4:7]
	v_mfma_f32_16x16x32_bf16 v[0:3], v[180:183], v[216:219], v[0:3]
	s_barrier
	s_mov_b32 m0, s39
	s_nop 0
	global_load_lds_dwordx4 v128, s[28:29]
	s_mov_b32 m0, s40
	s_nop 0
	global_load_lds_dwordx4 v132, s[28:29]
	s_add_i32 s54, 0, 0x18000
	s_add_i32 s55, 0, 0x1c000
	s_add_u32 s28, s28, 0x40000
	s_addc_u32 s29, s29, 0
	s_mov_b32 m0, s41
	s_nop 0
	global_load_lds_dwordx4 v128, s[28:29]
	s_mov_b32 m0, s42
	s_nop 0
	global_load_lds_dwordx4 v132, s[28:29]
	v_add_u32_e32 v155, s54, v149
	ds_read_b128 v[144:147], v155
	ds_read_b128 v[156:159], v155 offset:1024
	ds_read_b128 v[160:163], v155 offset:2048
	ds_read_b128 v[164:167], v155 offset:3072
	v_add_u32_e32 v155, s55, v149
	ds_read_b128 v[168:171], v155
	ds_read_b128 v[172:175], v155 offset:1024
	ds_read_b128 v[176:179], v155 offset:2048
	ds_read_b128 v[180:183], v155 offset:3072
	ds_read_b128 v[184:187], v153 offset:32768
	ds_read_b128 v[188:191], v153 offset:33792
	ds_read_b128 v[192:195], v153 offset:34816
	ds_read_b128 v[196:199], v153 offset:35840
	ds_read_b128 v[200:203], v153 offset:36864
	ds_read_b128 v[208:211], v153 offset:37888
	ds_read_b128 v[212:215], v153 offset:38912
	ds_read_b128 v[216:219], v153 offset:39936
	s_waitcnt vmcnt(8)
	s_waitcnt lgkmcnt(0)
	s_barrier
	s_waitcnt lgkmcnt(0)
	v_mfma_f32_16x16x32_bf16 v[124:127], v[144:147], v[184:187], v[124:127]
	v_mfma_f32_16x16x32_bf16 v[120:123], v[160:163], v[184:187], v[120:123]
	v_mfma_f32_16x16x32_bf16 v[108:111], v[144:147], v[192:195], v[108:111]
	v_mfma_f32_16x16x32_bf16 v[104:107], v[160:163], v[192:195], v[104:107]
	v_mfma_f32_16x16x32_bf16 v[92:95], v[144:147], v[200:203], v[92:95]
	v_mfma_f32_16x16x32_bf16 v[88:91], v[160:163], v[200:203], v[88:91]
	v_mfma_f32_16x16x32_bf16 v[76:79], v[144:147], v[212:215], v[76:79]
	v_mfma_f32_16x16x32_bf16 v[72:75], v[160:163], v[212:215], v[72:75]
	v_mfma_f32_16x16x32_bf16 v[124:127], v[156:159], v[188:191], v[124:127]
	v_mfma_f32_16x16x32_bf16 v[120:123], v[164:167], v[188:191], v[120:123]
	v_mfma_f32_16x16x32_bf16 v[108:111], v[156:159], v[196:199], v[108:111]
	v_mfma_f32_16x16x32_bf16 v[104:107], v[164:167], v[196:199], v[104:107]
	v_mfma_f32_16x16x32_bf16 v[92:95], v[156:159], v[208:211], v[92:95]
	v_mfma_f32_16x16x32_bf16 v[88:91], v[164:167], v[208:211], v[88:91]
	v_mfma_f32_16x16x32_bf16 v[76:79], v[156:159], v[216:219], v[76:79]
	v_mfma_f32_16x16x32_bf16 v[72:75], v[164:167], v[216:219], v[72:75]
	v_mfma_f32_16x16x32_bf16 v[116:119], v[168:171], v[184:187], v[116:119]
	v_mfma_f32_16x16x32_bf16 v[112:115], v[176:179], v[184:187], v[112:115]
	v_mfma_f32_16x16x32_bf16 v[100:103], v[168:171], v[192:195], v[100:103]
	v_mfma_f32_16x16x32_bf16 v[96:99], v[176:179], v[192:195], v[96:99]
	v_mfma_f32_16x16x32_bf16 v[84:87], v[168:171], v[200:203], v[84:87]
	v_mfma_f32_16x16x32_bf16 v[80:83], v[176:179], v[200:203], v[80:83]
	v_mfma_f32_16x16x32_bf16 v[68:71], v[168:171], v[212:215], v[68:71]
	v_mfma_f32_16x16x32_bf16 v[64:67], v[176:179], v[212:215], v[64:67]
	v_mfma_f32_16x16x32_bf16 v[116:119], v[172:175], v[188:191], v[116:119]
	v_mfma_f32_16x16x32_bf16 v[112:115], v[180:183], v[188:191], v[112:115]
	v_mfma_f32_16x16x32_bf16 v[100:103], v[172:175], v[196:199], v[100:103]
	v_mfma_f32_16x16x32_bf16 v[96:99], v[180:183], v[196:199], v[96:99]
	v_mfma_f32_16x16x32_bf16 v[84:87], v[172:175], v[208:211], v[84:87]
	v_mfma_f32_16x16x32_bf16 v[80:83], v[180:183], v[208:211], v[80:83]
	v_mfma_f32_16x16x32_bf16 v[68:71], v[172:175], v[216:219], v[68:71]
	v_mfma_f32_16x16x32_bf16 v[64:67], v[180:183], v[216:219], v[64:67]
	s_barrier
	s_add_i32 s28, s54, s38
	s_mov_b32 m0, s28
	s_nop 0
	global_load_lds_dwordx4 v205, s[26:27]
	s_add_i32 m0, s28, 0x2000
	s_add_u32 s26, s26, 0x40080
	s_addc_u32 s27, s27, 0
	s_add_i32 s28, s55, s38
	global_load_lds_dwordx4 v221, s[98:99]
	ds_read_b128 v[184:187], v153 offset:49152
	ds_read_b128 v[188:191], v153 offset:50176
	ds_read_b128 v[192:195], v153 offset:51200
	ds_read_b128 v[196:199], v153 offset:52224
	s_mov_b32 m0, s28
	s_nop 0
	global_load_lds_dwordx4 v130, s[26:27]
	s_add_i32 m0, s28, 0x2000
	s_nop 0
	global_load_lds_dwordx4 v134, s[26:27]
	s_cmp_lg_u32 s53, 12
	s_cbranch_scc1 .Lbal_last_13
	s_mov_b32 m0, s44
	s_nop 0
	global_load_lds_dwordx4 v204, s[100:101]
	s_mov_b32 m0, s45
	s_nop 0
	global_load_lds_dwordx4 v220, s[100:101]
.Lbal_last_13:
	ds_read_b128 v[200:203], v153 offset:53248
	ds_read_b128 v[208:211], v153 offset:54272
	ds_read_b128 v[212:215], v153 offset:55296
	ds_read_b128 v[216:219], v153 offset:56320
	s_waitcnt vmcnt(6)
	s_waitcnt lgkmcnt(0)
	s_barrier
	s_waitcnt lgkmcnt(0)
	v_mfma_f32_16x16x32_bf16 v[60:63], v[144:147], v[184:187], v[60:63]
	v_mfma_f32_16x16x32_bf16 v[56:59], v[160:163], v[184:187], v[56:59]
	v_mfma_f32_16x16x32_bf16 v[44:47], v[144:147], v[192:195], v[44:47]
	v_mfma_f32_16x16x32_bf16 v[40:43], v[160:163], v[192:195], v[40:43]
	v_mfma_f32_16x16x32_bf16 v[28:31], v[144:147], v[200:203], v[28:31]
	v_mfma_f32_16x16x32_bf16 v[24:27], v[160:163], v[200:203], v[24:27]
	v_mfma_f32_16x16x32_bf16 v[12:15], v[144:147], v[212:215], v[12:15]
	v_mfma_f32_16x16x32_bf16 v[8:11], v[160:163], v[212:215], v[8:11]
	v_mfma_f32_16x16x32_bf16 v[60:63], v[156:159], v[188:191], v[60:63]
	v_mfma_f32_16x16x32_bf16 v[56:59], v[164:167], v[188:191], v[56:59]
	v_mfma_f32_16x16x32_bf16 v[44:47], v[156:159], v[196:199], v[44:47]
	v_mfma_f32_16x16x32_bf16 v[40:43], v[164:167], v[196:199], v[40:43]
	v_mfma_f32_16x16x32_bf16 v[28:31], v[156:159], v[208:211], v[28:31]
	v_mfma_f32_16x16x32_bf16 v[24:27], v[164:167], v[208:211], v[24:27]
	v_mfma_f32_16x16x32_bf16 v[12:15], v[156:159], v[216:219], v[12:15]
	v_mfma_f32_16x16x32_bf16 v[8:11], v[164:167], v[216:219], v[8:11]
	v_mfma_f32_16x16x32_bf16 v[52:55], v[168:171], v[184:187], v[52:55]
	v_mfma_f32_16x16x32_bf16 v[48:51], v[176:179], v[184:187], v[48:51]
	v_mfma_f32_16x16x32_bf16 v[36:39], v[168:171], v[192:195], v[36:39]
	v_mfma_f32_16x16x32_bf16 v[32:35], v[176:179], v[192:195], v[32:35]
	v_mfma_f32_16x16x32_bf16 v[20:23], v[168:171], v[200:203], v[20:23]
	v_mfma_f32_16x16x32_bf16 v[16:19], v[176:179], v[200:203], v[16:19]
	v_mfma_f32_16x16x32_bf16 v[4:7], v[168:171], v[212:215], v[4:7]
	v_mfma_f32_16x16x32_bf16 v[0:3], v[176:179], v[212:215], v[0:3]
	v_mfma_f32_16x16x32_bf16 v[52:55], v[172:175], v[188:191], v[52:55]
	v_mfma_f32_16x16x32_bf16 v[48:51], v[180:183], v[188:191], v[48:51]
	v_mfma_f32_16x16x32_bf16 v[36:39], v[172:175], v[196:199], v[36:39]
	v_mfma_f32_16x16x32_bf16 v[32:35], v[180:183], v[196:199], v[32:35]
	v_mfma_f32_16x16x32_bf16 v[20:23], v[172:175], v[208:211], v[20:23]
	v_mfma_f32_16x16x32_bf16 v[16:19], v[180:183], v[208:211], v[16:19]
	v_mfma_f32_16x16x32_bf16 v[4:7], v[172:175], v[216:219], v[4:7]
	v_mfma_f32_16x16x32_bf16 v[0:3], v[180:183], v[216:219], v[0:3]
	s_barrier
	s_add_i32 s53, s53, 2
	s_add_u32 s51, s51, 0x100
	s_addc_u32 s52, s52, 0
	s_add_u32 s24, s24, 0x100
	s_addc_u32 s25, s25, 0
	s_cmp_gt_u32 s53, 13
	s_cbranch_scc0 .LBB0_1365
	s_setprio 0
	s_and_b64 vcc, exec, s[14:15]
	s_cbranch_vccz .LBB0_1368
	s_barrier

.Lbal_first_11:
	s_add_u32 s38, s36, 0xfffc0080
	s_addc_u32 s39, s37, -1
	s_cmp_eq_u32 s61, 12
	s_cselect_b32 s41, s3, s39
	s_cselect_b32 s40, s29, s38
	s_cselect_b32 s39, s27, s60
	s_cselect_b32 s38, s58, s59
	s_add_i32 m0, s46, 0xc000
	s_nop 0
	global_load_lds_dwordx4 v134, s[36:37]
	s_add_i32 m0, s46, 0xe000
	s_nop 0
	global_load_lds_dwordx4 v132, s[36:37]
	ds_read_b128 v[140:143], v151
	ds_read_b128 v[144:147], v151 offset:1024
	ds_read_b128 v[156:159], v151 offset:2048
	ds_read_b128 v[160:163], v151 offset:3072
	ds_read_b128 v[164:167], v152
	ds_read_b128 v[168:171], v152 offset:1024
	ds_read_b128 v[172:175], v152 offset:2048
	ds_read_b128 v[176:179], v152 offset:3072
	ds_read_b128 v[180:183], v153
	ds_read_b128 v[184:187], v153 offset:1024
	ds_read_b128 v[188:191], v153 offset:2048
	ds_read_b128 v[192:195], v153 offset:3072
	ds_read_b128 v[196:199], v153 offset:4096
	ds_read_b128 v[200:203], v153 offset:5120
	ds_read_b128 v[208:211], v153 offset:6144
	ds_read_b128 v[212:215], v153 offset:7168
	s_waitcnt vmcnt(8)
	s_waitcnt lgkmcnt(0)
	s_barrier
	s_waitcnt lgkmcnt(0)
	v_mfma_f32_16x16x32_bf16 v[124:127], v[140:143], v[180:183], v[124:127]
	v_mfma_f32_16x16x32_bf16 v[120:123], v[156:159], v[180:183], v[120:123]
	v_mfma_f32_16x16x32_bf16 v[108:111], v[140:143], v[188:191], v[108:111]
	v_mfma_f32_16x16x32_bf16 v[104:107], v[156:159], v[188:191], v[104:107]
	v_mfma_f32_16x16x32_bf16 v[92:95], v[140:143], v[196:199], v[92:95]
	v_mfma_f32_16x16x32_bf16 v[88:91], v[156:159], v[196:199], v[88:91]
	v_mfma_f32_16x16x32_bf16 v[76:79], v[140:143], v[208:211], v[76:79]
	v_mfma_f32_16x16x32_bf16 v[72:75], v[156:159], v[208:211], v[72:75]
	v_mfma_f32_16x16x32_bf16 v[124:127], v[144:147], v[184:187], v[124:127]
	v_mfma_f32_16x16x32_bf16 v[120:123], v[160:163], v[184:187], v[120:123]
	v_mfma_f32_16x16x32_bf16 v[108:111], v[144:147], v[192:195], v[108:111]
	v_mfma_f32_16x16x32_bf16 v[104:107], v[160:163], v[192:195], v[104:107]
	v_mfma_f32_16x16x32_bf16 v[92:95], v[144:147], v[200:203], v[92:95]
	v_mfma_f32_16x16x32_bf16 v[88:91], v[160:163], v[200:203], v[88:91]
	v_mfma_f32_16x16x32_bf16 v[76:79], v[144:147], v[212:215], v[76:79]
	v_mfma_f32_16x16x32_bf16 v[72:75], v[160:163], v[212:215], v[72:75]
	v_mfma_f32_16x16x32_bf16 v[116:119], v[164:167], v[180:183], v[116:119]
	v_mfma_f32_16x16x32_bf16 v[112:115], v[172:175], v[180:183], v[112:115]
	v_mfma_f32_16x16x32_bf16 v[100:103], v[164:167], v[188:191], v[100:103]
	v_mfma_f32_16x16x32_bf16 v[96:99], v[172:175], v[188:191], v[96:99]
	v_mfma_f32_16x16x32_bf16 v[84:87], v[164:167], v[196:199], v[84:87]
	v_mfma_f32_16x16x32_bf16 v[80:83], v[172:175], v[196:199], v[80:83]
	v_mfma_f32_16x16x32_bf16 v[68:71], v[164:167], v[208:211], v[68:71]
	v_mfma_f32_16x16x32_bf16 v[64:67], v[172:175], v[208:211], v[64:67]
	v_mfma_f32_16x16x32_bf16 v[116:119], v[168:171], v[184:187], v[116:119]
	v_mfma_f32_16x16x32_bf16 v[112:115], v[176:179], v[184:187], v[112:115]
	v_mfma_f32_16x16x32_bf16 v[100:103], v[168:171], v[192:195], v[100:103]
	v_mfma_f32_16x16x32_bf16 v[96:99], v[176:179], v[192:195], v[96:99]
	v_mfma_f32_16x16x32_bf16 v[84:87], v[168:171], v[200:203], v[84:87]
	v_mfma_f32_16x16x32_bf16 v[80:83], v[176:179], v[200:203], v[80:83]
	v_mfma_f32_16x16x32_bf16 v[68:71], v[168:171], v[212:215], v[68:71]
	v_mfma_f32_16x16x32_bf16 v[64:67], v[176:179], v[212:215], v[64:67]
	s_barrier
	s_add_i32 s62, s54, s45
	s_mov_b32 m0, s62
	s_nop 0
	global_load_lds_dwordx4 v128, s[38:39]
	s_add_i32 m0, s62, 0x2000
	s_add_u32 s62, s38, 0x40000
	s_mov_b64 s[98:99], s[38:39]
	s_addc_u32 s63, s39, 0
	s_add_i32 s64, s55, s45
	global_load_lds_dwordx4 v130, s[38:39]
	ds_read_b128 v[180:183], v153 offset:16384
	ds_read_b128 v[184:187], v153 offset:17408
	ds_read_b128 v[188:191], v153 offset:18432
	ds_read_b128 v[192:195], v153 offset:19456
	s_mov_b32 m0, s64
	s_mov_b64 s[100:101], s[40:41]
	global_load_lds_dwordx4 v128, s[62:63]
	s_add_i32 m0, s64, 0x2000
	s_nop 0
	global_load_lds_dwordx4 v130, s[62:63]
	ds_read_b128 v[196:199], v153 offset:20480
	ds_read_b128 v[200:203], v153 offset:21504
	ds_read_b128 v[208:211], v153 offset:22528
	ds_read_b128 v[212:215], v153 offset:23552
	s_waitcnt vmcnt(6)
	s_waitcnt lgkmcnt(0)
	s_barrier
	s_waitcnt lgkmcnt(0)
	v_mfma_f32_16x16x32_bf16 v[60:63], v[140:143], v[180:183], v[60:63]
	v_mfma_f32_16x16x32_bf16 v[56:59], v[156:159], v[180:183], v[56:59]
	v_mfma_f32_16x16x32_bf16 v[44:47], v[140:143], v[188:191], v[44:47]
	v_mfma_f32_16x16x32_bf16 v[40:43], v[156:159], v[188:191], v[40:43]
	v_mfma_f32_16x16x32_bf16 v[28:31], v[140:143], v[196:199], v[28:31]
	v_mfma_f32_16x16x32_bf16 v[24:27], v[156:159], v[196:199], v[24:27]
	v_mfma_f32_16x16x32_bf16 v[12:15], v[140:143], v[208:211], v[12:15]
	v_mfma_f32_16x16x32_bf16 v[8:11], v[156:159], v[208:211], v[8:11]
	v_mfma_f32_16x16x32_bf16 v[60:63], v[144:147], v[184:187], v[60:63]
	v_mfma_f32_16x16x32_bf16 v[56:59], v[160:163], v[184:187], v[56:59]
	v_mfma_f32_16x16x32_bf16 v[44:47], v[144:147], v[192:195], v[44:47]
	v_mfma_f32_16x16x32_bf16 v[40:43], v[160:163], v[192:195], v[40:43]
	v_mfma_f32_16x16x32_bf16 v[28:31], v[144:147], v[200:203], v[28:31]
	v_mfma_f32_16x16x32_bf16 v[24:27], v[160:163], v[200:203], v[24:27]
	v_mfma_f32_16x16x32_bf16 v[12:15], v[144:147], v[212:215], v[12:15]
	v_mfma_f32_16x16x32_bf16 v[8:11], v[160:163], v[212:215], v[8:11]
	v_mfma_f32_16x16x32_bf16 v[52:55], v[164:167], v[180:183], v[52:55]
	v_mfma_f32_16x16x32_bf16 v[48:51], v[172:175], v[180:183], v[48:51]
	v_mfma_f32_16x16x32_bf16 v[36:39], v[164:167], v[188:191], v[36:39]
	v_mfma_f32_16x16x32_bf16 v[32:35], v[172:175], v[188:191], v[32:35]
	v_mfma_f32_16x16x32_bf16 v[20:23], v[164:167], v[196:199], v[20:23]
	v_mfma_f32_16x16x32_bf16 v[16:19], v[172:175], v[196:199], v[16:19]
	v_mfma_f32_16x16x32_bf16 v[4:7], v[164:167], v[208:211], v[4:7]
	v_mfma_f32_16x16x32_bf16 v[0:3], v[172:175], v[208:211], v[0:3]
	v_mfma_f32_16x16x32_bf16 v[52:55], v[168:171], v[184:187], v[52:55]
	v_mfma_f32_16x16x32_bf16 v[48:51], v[176:179], v[184:187], v[48:51]
	v_mfma_f32_16x16x32_bf16 v[36:39], v[168:171], v[192:195], v[36:39]
	v_mfma_f32_16x16x32_bf16 v[32:35], v[176:179], v[192:195], v[32:35]
	v_mfma_f32_16x16x32_bf16 v[20:23], v[168:171], v[200:203], v[20:23]
	v_mfma_f32_16x16x32_bf16 v[16:19], v[176:179], v[200:203], v[16:19]
	v_mfma_f32_16x16x32_bf16 v[4:7], v[168:171], v[212:215], v[4:7]
	v_mfma_f32_16x16x32_bf16 v[0:3], v[176:179], v[212:215], v[0:3]
	s_barrier
	s_mov_b32 m0, s46
	s_nop 0
	global_load_lds_dwordx4 v128, s[40:41]
	s_mov_b32 m0, s47
	s_nop 0
	global_load_lds_dwordx4 v130, s[40:41]
	s_add_i32 s62, 0, 0x18000
	s_add_i32 s63, 0, 0x1c000
	s_add_u32 s40, s40, 0x40000
	s_addc_u32 s41, s41, 0
	s_mov_b32 m0, s48
	s_nop 0
	global_load_lds_dwordx4 v128, s[40:41]
	s_mov_b32 m0, s49
	s_nop 0
	global_load_lds_dwordx4 v130, s[40:41]
	v_add_u32_e32 v155, s62, v149
	ds_read_b128 v[140:143], v155
	ds_read_b128 v[144:147], v155 offset:1024
	ds_read_b128 v[156:159], v155 offset:2048
	ds_read_b128 v[160:163], v155 offset:3072
	v_add_u32_e32 v155, s63, v149
	ds_read_b128 v[164:167], v155
	ds_read_b128 v[168:171], v155 offset:1024
	ds_read_b128 v[172:175], v155 offset:2048
	ds_read_b128 v[176:179], v155 offset:3072
	ds_read_b128 v[180:183], v153 offset:32768
	ds_read_b128 v[184:187], v153 offset:33792
	ds_read_b128 v[188:191], v153 offset:34816
	ds_read_b128 v[192:195], v153 offset:35840
	ds_read_b128 v[196:199], v153 offset:36864
	ds_read_b128 v[200:203], v153 offset:37888
	ds_read_b128 v[208:211], v153 offset:38912
	ds_read_b128 v[212:215], v153 offset:39936
	s_waitcnt vmcnt(8)
	s_waitcnt lgkmcnt(0)
	s_barrier
	s_waitcnt lgkmcnt(0)
	v_mfma_f32_16x16x32_bf16 v[124:127], v[140:143], v[180:183], v[124:127]
	v_mfma_f32_16x16x32_bf16 v[120:123], v[156:159], v[180:183], v[120:123]
	v_mfma_f32_16x16x32_bf16 v[108:111], v[140:143], v[188:191], v[108:111]
	v_mfma_f32_16x16x32_bf16 v[104:107], v[156:159], v[188:191], v[104:107]
	v_mfma_f32_16x16x32_bf16 v[92:95], v[140:143], v[196:199], v[92:95]
	v_mfma_f32_16x16x32_bf16 v[88:91], v[156:159], v[196:199], v[88:91]
	v_mfma_f32_16x16x32_bf16 v[76:79], v[140:143], v[208:211], v[76:79]
	v_mfma_f32_16x16x32_bf16 v[72:75], v[156:159], v[208:211], v[72:75]
	v_mfma_f32_16x16x32_bf16 v[124:127], v[144:147], v[184:187], v[124:127]
	v_mfma_f32_16x16x32_bf16 v[120:123], v[160:163], v[184:187], v[120:123]
	v_mfma_f32_16x16x32_bf16 v[108:111], v[144:147], v[192:195], v[108:111]
	v_mfma_f32_16x16x32_bf16 v[104:107], v[160:163], v[192:195], v[104:107]
	v_mfma_f32_16x16x32_bf16 v[92:95], v[144:147], v[200:203], v[92:95]
	v_mfma_f32_16x16x32_bf16 v[88:91], v[160:163], v[200:203], v[88:91]
	v_mfma_f32_16x16x32_bf16 v[76:79], v[144:147], v[212:215], v[76:79]
	v_mfma_f32_16x16x32_bf16 v[72:75], v[160:163], v[212:215], v[72:75]
	v_mfma_f32_16x16x32_bf16 v[116:119], v[164:167], v[180:183], v[116:119]
	v_mfma_f32_16x16x32_bf16 v[112:115], v[172:175], v[180:183], v[112:115]
	v_mfma_f32_16x16x32_bf16 v[100:103], v[164:167], v[188:191], v[100:103]
	v_mfma_f32_16x16x32_bf16 v[96:99], v[172:175], v[188:191], v[96:99]
	v_mfma_f32_16x16x32_bf16 v[84:87], v[164:167], v[196:199], v[84:87]
	v_mfma_f32_16x16x32_bf16 v[80:83], v[172:175], v[196:199], v[80:83]
	v_mfma_f32_16x16x32_bf16 v[68:71], v[164:167], v[208:211], v[68:71]
	v_mfma_f32_16x16x32_bf16 v[64:67], v[172:175], v[208:211], v[64:67]
	v_mfma_f32_16x16x32_bf16 v[116:119], v[168:171], v[184:187], v[116:119]
	v_mfma_f32_16x16x32_bf16 v[112:115], v[176:179], v[184:187], v[112:115]
	v_mfma_f32_16x16x32_bf16 v[100:103], v[168:171], v[192:195], v[100:103]
	v_mfma_f32_16x16x32_bf16 v[96:99], v[176:179], v[192:195], v[96:99]
	v_mfma_f32_16x16x32_bf16 v[84:87], v[168:171], v[200:203], v[84:87]
	v_mfma_f32_16x16x32_bf16 v[80:83], v[176:179], v[200:203], v[80:83]
	v_mfma_f32_16x16x32_bf16 v[68:71], v[168:171], v[212:215], v[68:71]
	v_mfma_f32_16x16x32_bf16 v[64:67], v[176:179], v[212:215], v[64:67]
	s_barrier
	s_add_i32 s40, s62, s45
	s_mov_b32 m0, s40
	s_nop 0
	global_load_lds_dwordx4 v204, s[38:39]
	s_add_i32 m0, s40, 0x2000
	s_add_u32 s38, s38, 0x40080
	s_addc_u32 s39, s39, 0
	s_add_i32 s40, s63, s45
	global_load_lds_dwordx4 v205, s[98:99]
	ds_read_b128 v[180:183], v153 offset:49152
	ds_read_b128 v[184:187], v153 offset:50176
	ds_read_b128 v[188:191], v153 offset:51200
	ds_read_b128 v[192:195], v153 offset:52224
	s_mov_b32 m0, s40
	s_nop 0
	global_load_lds_dwordx4 v128, s[38:39]
	s_add_i32 m0, s40, 0x2000
	s_nop 0
	global_load_lds_dwordx4 v130, s[38:39]
	s_cmp_lg_u32 s61, 12
	s_cbranch_scc1 .Lbal_last_11
	s_mov_b32 m0, s51
	s_nop 0
	global_load_lds_dwordx4 v204, s[100:101]
	s_mov_b32 m0, s52
	s_nop 0
	global_load_lds_dwordx4 v205, s[100:101]
.Lbal_last_11:
	ds_read_b128 v[196:199], v153 offset:53248
	ds_read_b128 v[200:203], v153 offset:54272
	ds_read_b128 v[208:211], v153 offset:55296
	ds_read_b128 v[212:215], v153 offset:56320
	s_waitcnt vmcnt(6)
	s_waitcnt lgkmcnt(0)
	s_barrier
	s_waitcnt lgkmcnt(0)
	v_mfma_f32_16x16x32_bf16 v[60:63], v[140:143], v[180:183], v[60:63]
	v_mfma_f32_16x16x32_bf16 v[56:59], v[156:159], v[180:183], v[56:59]
	v_mfma_f32_16x16x32_bf16 v[44:47], v[140:143], v[188:191], v[44:47]
	v_mfma_f32_16x16x32_bf16 v[40:43], v[156:159], v[188:191], v[40:43]
	v_mfma_f32_16x16x32_bf16 v[28:31], v[140:143], v[196:199], v[28:31]
	v_mfma_f32_16x16x32_bf16 v[24:27], v[156:159], v[196:199], v[24:27]
	v_mfma_f32_16x16x32_bf16 v[12:15], v[140:143], v[208:211], v[12:15]
	v_mfma_f32_16x16x32_bf16 v[8:11], v[156:159], v[208:211], v[8:11]
	v_mfma_f32_16x16x32_bf16 v[60:63], v[144:147], v[184:187], v[60:63]
	v_mfma_f32_16x16x32_bf16 v[56:59], v[160:163], v[184:187], v[56:59]
	v_mfma_f32_16x16x32_bf16 v[44:47], v[144:147], v[192:195], v[44:47]
	v_mfma_f32_16x16x32_bf16 v[40:43], v[160:163], v[192:195], v[40:43]
	v_mfma_f32_16x16x32_bf16 v[28:31], v[144:147], v[200:203], v[28:31]
	v_mfma_f32_16x16x32_bf16 v[24:27], v[160:163], v[200:203], v[24:27]
	v_mfma_f32_16x16x32_bf16 v[12:15], v[144:147], v[212:215], v[12:15]
	v_mfma_f32_16x16x32_bf16 v[8:11], v[160:163], v[212:215], v[8:11]
	v_mfma_f32_16x16x32_bf16 v[52:55], v[164:167], v[180:183], v[52:55]
	v_mfma_f32_16x16x32_bf16 v[48:51], v[172:175], v[180:183], v[48:51]
	v_mfma_f32_16x16x32_bf16 v[36:39], v[164:167], v[188:191], v[36:39]
	v_mfma_f32_16x16x32_bf16 v[32:35], v[172:175], v[188:191], v[32:35]
	v_mfma_f32_16x16x32_bf16 v[20:23], v[164:167], v[196:199], v[20:23]
	v_mfma_f32_16x16x32_bf16 v[16:19], v[172:175], v[196:199], v[16:19]
	v_mfma_f32_16x16x32_bf16 v[4:7], v[164:167], v[208:211], v[4:7]
	v_mfma_f32_16x16x32_bf16 v[0:3], v[172:175], v[208:211], v[0:3]
	v_mfma_f32_16x16x32_bf16 v[52:55], v[168:171], v[184:187], v[52:55]
	v_mfma_f32_16x16x32_bf16 v[48:51], v[176:179], v[184:187], v[48:51]
	v_mfma_f32_16x16x32_bf16 v[36:39], v[168:171], v[192:195], v[36:39]
	v_mfma_f32_16x16x32_bf16 v[32:35], v[176:179], v[192:195], v[32:35]
	v_mfma_f32_16x16x32_bf16 v[20:23], v[168:171], v[200:203], v[20:23]
	v_mfma_f32_16x16x32_bf16 v[16:19], v[176:179], v[200:203], v[16:19]
	v_mfma_f32_16x16x32_bf16 v[4:7], v[168:171], v[212:215], v[4:7]
	v_mfma_f32_16x16x32_bf16 v[0:3], v[176:179], v[212:215], v[0:3]
	s_barrier
	s_add_i32 s61, s61, 2
	s_add_u32 s59, s59, 0x100
	s_addc_u32 s60, s60, 0
	s_add_u32 s36, s36, 0x100
	s_addc_u32 s37, s37, 0
	s_cmp_gt_u32 s61, 13
	s_cbranch_scc0 .LBB0_1561
	s_setprio 0
	s_and_b64 vcc, exec, s[24:25]
	s_cbranch_vccz .LBB0_1564
	s_barrier

.Lbal_first_10:
	s_add_u32 s26, s24, 0xfffc0080
	s_addc_u32 s27, s25, -1
	s_cmp_eq_u32 s54, 12
	s_cselect_b32 s29, s19, s27
	s_cselect_b32 s28, s50, s26
	s_cselect_b32 s27, s17, s53
	s_cselect_b32 s26, s51, s52
	s_add_i32 m0, s38, 0xc000
	s_nop 0
	global_load_lds_dwordx4 v138, s[24:25]
	s_add_i32 m0, s38, 0xe000
	s_nop 0
	global_load_lds_dwordx4 v136, s[24:25]
	ds_read_b128 v[144:147], v151
	ds_read_b128 v[156:159], v151 offset:1024
	ds_read_b128 v[160:163], v151 offset:2048
	ds_read_b128 v[164:167], v151 offset:3072
	ds_read_b128 v[168:171], v152
	ds_read_b128 v[172:175], v152 offset:1024
	ds_read_b128 v[176:179], v152 offset:2048
	ds_read_b128 v[180:183], v152 offset:3072
	ds_read_b128 v[184:187], v153
	ds_read_b128 v[188:191], v153 offset:1024
	ds_read_b128 v[192:195], v153 offset:2048
	ds_read_b128 v[196:199], v153 offset:3072
	ds_read_b128 v[200:203], v153 offset:4096
	ds_read_b128 v[208:211], v153 offset:5120
	ds_read_b128 v[212:215], v153 offset:6144
	ds_read_b128 v[216:219], v153 offset:7168
	s_waitcnt vmcnt(8)
	s_waitcnt lgkmcnt(0)
	s_barrier
	s_waitcnt lgkmcnt(0)
	v_mfma_f32_16x16x32_bf16 v[124:127], v[144:147], v[184:187], v[124:127]
	v_mfma_f32_16x16x32_bf16 v[120:123], v[160:163], v[184:187], v[120:123]
	v_mfma_f32_16x16x32_bf16 v[108:111], v[144:147], v[192:195], v[108:111]
	v_mfma_f32_16x16x32_bf16 v[104:107], v[160:163], v[192:195], v[104:107]
	v_mfma_f32_16x16x32_bf16 v[92:95], v[144:147], v[200:203], v[92:95]
	v_mfma_f32_16x16x32_bf16 v[88:91], v[160:163], v[200:203], v[88:91]
	v_mfma_f32_16x16x32_bf16 v[76:79], v[144:147], v[212:215], v[76:79]
	v_mfma_f32_16x16x32_bf16 v[72:75], v[160:163], v[212:215], v[72:75]
	v_mfma_f32_16x16x32_bf16 v[124:127], v[156:159], v[188:191], v[124:127]
	v_mfma_f32_16x16x32_bf16 v[120:123], v[164:167], v[188:191], v[120:123]
	v_mfma_f32_16x16x32_bf16 v[108:111], v[156:159], v[196:199], v[108:111]
	v_mfma_f32_16x16x32_bf16 v[104:107], v[164:167], v[196:199], v[104:107]
	v_mfma_f32_16x16x32_bf16 v[92:95], v[156:159], v[208:211], v[92:95]
	v_mfma_f32_16x16x32_bf16 v[88:91], v[164:167], v[208:211], v[88:91]
	v_mfma_f32_16x16x32_bf16 v[76:79], v[156:159], v[216:219], v[76:79]
	v_mfma_f32_16x16x32_bf16 v[72:75], v[164:167], v[216:219], v[72:75]
	v_mfma_f32_16x16x32_bf16 v[116:119], v[168:171], v[184:187], v[116:119]
	v_mfma_f32_16x16x32_bf16 v[112:115], v[176:179], v[184:187], v[112:115]
	v_mfma_f32_16x16x32_bf16 v[100:103], v[168:171], v[192:195], v[100:103]
	v_mfma_f32_16x16x32_bf16 v[96:99], v[176:179], v[192:195], v[96:99]
	v_mfma_f32_16x16x32_bf16 v[84:87], v[168:171], v[200:203], v[84:87]
	v_mfma_f32_16x16x32_bf16 v[80:83], v[176:179], v[200:203], v[80:83]
	v_mfma_f32_16x16x32_bf16 v[68:71], v[168:171], v[212:215], v[68:71]
	v_mfma_f32_16x16x32_bf16 v[64:67], v[176:179], v[212:215], v[64:67]
	v_mfma_f32_16x16x32_bf16 v[116:119], v[172:175], v[188:191], v[116:119]
	v_mfma_f32_16x16x32_bf16 v[112:115], v[180:183], v[188:191], v[112:115]
	v_mfma_f32_16x16x32_bf16 v[100:103], v[172:175], v[196:199], v[100:103]
	v_mfma_f32_16x16x32_bf16 v[96:99], v[180:183], v[196:199], v[96:99]
	v_mfma_f32_16x16x32_bf16 v[84:87], v[172:175], v[208:211], v[84:87]
	v_mfma_f32_16x16x32_bf16 v[80:83], v[180:183], v[208:211], v[80:83]
	v_mfma_f32_16x16x32_bf16 v[68:71], v[172:175], v[216:219], v[68:71]
	v_mfma_f32_16x16x32_bf16 v[64:67], v[180:183], v[216:219], v[64:67]
	s_barrier
	s_add_i32 s55, s47, s35
	s_mov_b32 m0, s55
	s_nop 0
	global_load_lds_dwordx4 v132, s[26:27]
	s_add_i32 m0, s55, 0x2000
	s_add_u32 s56, s26, 0x40000
	s_mov_b64 s[98:99], s[26:27]
	s_addc_u32 s57, s27, 0
	s_add_i32 s55, s48, s35
	global_load_lds_dwordx4 v128, s[26:27]
	ds_read_b128 v[184:187], v153 offset:16384
	ds_read_b128 v[188:191], v153 offset:17408
	ds_read_b128 v[192:195], v153 offset:18432
	ds_read_b128 v[196:199], v153 offset:19456
	s_mov_b32 m0, s55
	s_mov_b64 s[100:101], s[28:29]
	global_load_lds_dwordx4 v132, s[56:57]
	s_add_i32 m0, s55, 0x2000
	s_nop 0
	global_load_lds_dwordx4 v128, s[56:57]
	ds_read_b128 v[200:203], v153 offset:20480
	ds_read_b128 v[208:211], v153 offset:21504
	ds_read_b128 v[212:215], v153 offset:22528
	ds_read_b128 v[216:219], v153 offset:23552
	s_waitcnt vmcnt(6)
	s_waitcnt lgkmcnt(0)
	s_barrier
	s_waitcnt lgkmcnt(0)
	v_mfma_f32_16x16x32_bf16 v[60:63], v[144:147], v[184:187], v[60:63]
	v_mfma_f32_16x16x32_bf16 v[56:59], v[160:163], v[184:187], v[56:59]
	v_mfma_f32_16x16x32_bf16 v[44:47], v[144:147], v[192:195], v[44:47]
	v_mfma_f32_16x16x32_bf16 v[40:43], v[160:163], v[192:195], v[40:43]
	v_mfma_f32_16x16x32_bf16 v[28:31], v[144:147], v[200:203], v[28:31]
	v_mfma_f32_16x16x32_bf16 v[24:27], v[160:163], v[200:203], v[24:27]
	v_mfma_f32_16x16x32_bf16 v[12:15], v[144:147], v[212:215], v[12:15]
	v_mfma_f32_16x16x32_bf16 v[8:11], v[160:163], v[212:215], v[8:11]
	v_mfma_f32_16x16x32_bf16 v[60:63], v[156:159], v[188:191], v[60:63]
	v_mfma_f32_16x16x32_bf16 v[56:59], v[164:167], v[188:191], v[56:59]
	v_mfma_f32_16x16x32_bf16 v[44:47], v[156:159], v[196:199], v[44:47]
	v_mfma_f32_16x16x32_bf16 v[40:43], v[164:167], v[196:199], v[40:43]
	v_mfma_f32_16x16x32_bf16 v[28:31], v[156:159], v[208:211], v[28:31]
	v_mfma_f32_16x16x32_bf16 v[24:27], v[164:167], v[208:211], v[24:27]
	v_mfma_f32_16x16x32_bf16 v[12:15], v[156:159], v[216:219], v[12:15]
	v_mfma_f32_16x16x32_bf16 v[8:11], v[164:167], v[216:219], v[8:11]
	v_mfma_f32_16x16x32_bf16 v[52:55], v[168:171], v[184:187], v[52:55]
	v_mfma_f32_16x16x32_bf16 v[48:51], v[176:179], v[184:187], v[48:51]
	v_mfma_f32_16x16x32_bf16 v[36:39], v[168:171], v[192:195], v[36:39]
	v_mfma_f32_16x16x32_bf16 v[32:35], v[176:179], v[192:195], v[32:35]
	v_mfma_f32_16x16x32_bf16 v[20:23], v[168:171], v[200:203], v[20:23]
	v_mfma_f32_16x16x32_bf16 v[16:19], v[176:179], v[200:203], v[16:19]
	v_mfma_f32_16x16x32_bf16 v[4:7], v[168:171], v[212:215], v[4:7]
	v_mfma_f32_16x16x32_bf16 v[0:3], v[176:179], v[212:215], v[0:3]
	v_mfma_f32_16x16x32_bf16 v[52:55], v[172:175], v[188:191], v[52:55]
	v_mfma_f32_16x16x32_bf16 v[48:51], v[180:183], v[188:191], v[48:51]
	v_mfma_f32_16x16x32_bf16 v[36:39], v[172:175], v[196:199], v[36:39]
	v_mfma_f32_16x16x32_bf16 v[32:35], v[180:183], v[196:199], v[32:35]
	v_mfma_f32_16x16x32_bf16 v[20:23], v[172:175], v[208:211], v[20:23]
	v_mfma_f32_16x16x32_bf16 v[16:19], v[180:183], v[208:211], v[16:19]
	v_mfma_f32_16x16x32_bf16 v[4:7], v[172:175], v[216:219], v[4:7]
	v_mfma_f32_16x16x32_bf16 v[0:3], v[180:183], v[216:219], v[0:3]
	s_barrier
	s_mov_b32 m0, s38
	s_nop 0
	global_load_lds_dwordx4 v134, s[28:29]
	s_mov_b32 m0, s39
	s_nop 0
	global_load_lds_dwordx4 v130, s[28:29]
	s_add_i32 s55, 0, 0x18000
	s_add_i32 s56, 0, 0x1c000
	s_add_u32 s28, s28, 0x40000
	s_addc_u32 s29, s29, 0
	s_mov_b32 m0, s40
	s_nop 0
	global_load_lds_dwordx4 v134, s[28:29]
	s_mov_b32 m0, s41
	s_nop 0
	global_load_lds_dwordx4 v130, s[28:29]
	v_add_u32_e32 v164, s55, v149
	v_add_u32_e32 v180, s56, v149
	ds_read_b128 v[144:147], v164
	ds_read_b128 v[156:159], v164 offset:1024
	ds_read_b128 v[160:163], v164 offset:2048
	ds_read_b128 v[164:167], v164 offset:3072
	ds_read_b128 v[168:171], v180
	ds_read_b128 v[172:175], v180 offset:1024
	ds_read_b128 v[176:179], v180 offset:2048
	ds_read_b128 v[180:183], v180 offset:3072
	ds_read_b128 v[184:187], v153 offset:32768
	ds_read_b128 v[188:191], v153 offset:33792
	ds_read_b128 v[192:195], v153 offset:34816
	ds_read_b128 v[196:199], v153 offset:35840
	ds_read_b128 v[200:203], v153 offset:36864
	ds_read_b128 v[208:211], v153 offset:37888
	ds_read_b128 v[212:215], v153 offset:38912
	ds_read_b128 v[216:219], v153 offset:39936
	s_waitcnt vmcnt(8)
	s_waitcnt lgkmcnt(0)
	s_barrier
	s_waitcnt lgkmcnt(0)
	v_mfma_f32_16x16x32_bf16 v[124:127], v[144:147], v[184:187], v[124:127]
	v_mfma_f32_16x16x32_bf16 v[120:123], v[160:163], v[184:187], v[120:123]
	v_mfma_f32_16x16x32_bf16 v[108:111], v[144:147], v[192:195], v[108:111]
	v_mfma_f32_16x16x32_bf16 v[104:107], v[160:163], v[192:195], v[104:107]
	v_mfma_f32_16x16x32_bf16 v[92:95], v[144:147], v[200:203], v[92:95]
	v_mfma_f32_16x16x32_bf16 v[88:91], v[160:163], v[200:203], v[88:91]
	v_mfma_f32_16x16x32_bf16 v[76:79], v[144:147], v[212:215], v[76:79]
	v_mfma_f32_16x16x32_bf16 v[72:75], v[160:163], v[212:215], v[72:75]
	v_mfma_f32_16x16x32_bf16 v[124:127], v[156:159], v[188:191], v[124:127]
	v_mfma_f32_16x16x32_bf16 v[120:123], v[164:167], v[188:191], v[120:123]
	v_mfma_f32_16x16x32_bf16 v[108:111], v[156:159], v[196:199], v[108:111]
	v_mfma_f32_16x16x32_bf16 v[104:107], v[164:167], v[196:199], v[104:107]
	v_mfma_f32_16x16x32_bf16 v[92:95], v[156:159], v[208:211], v[92:95]
	v_mfma_f32_16x16x32_bf16 v[88:91], v[164:167], v[208:211], v[88:91]
	v_mfma_f32_16x16x32_bf16 v[76:79], v[156:159], v[216:219], v[76:79]
	v_mfma_f32_16x16x32_bf16 v[72:75], v[164:167], v[216:219], v[72:75]
	v_mfma_f32_16x16x32_bf16 v[116:119], v[168:171], v[184:187], v[116:119]
	v_mfma_f32_16x16x32_bf16 v[112:115], v[176:179], v[184:187], v[112:115]
	v_mfma_f32_16x16x32_bf16 v[100:103], v[168:171], v[192:195], v[100:103]
	v_mfma_f32_16x16x32_bf16 v[96:99], v[176:179], v[192:195], v[96:99]
	v_mfma_f32_16x16x32_bf16 v[84:87], v[168:171], v[200:203], v[84:87]
	v_mfma_f32_16x16x32_bf16 v[80:83], v[176:179], v[200:203], v[80:83]
	v_mfma_f32_16x16x32_bf16 v[68:71], v[168:171], v[212:215], v[68:71]
	v_mfma_f32_16x16x32_bf16 v[64:67], v[176:179], v[212:215], v[64:67]
	v_mfma_f32_16x16x32_bf16 v[116:119], v[172:175], v[188:191], v[116:119]
	v_mfma_f32_16x16x32_bf16 v[112:115], v[180:183], v[188:191], v[112:115]
	v_mfma_f32_16x16x32_bf16 v[100:103], v[172:175], v[196:199], v[100:103]
	v_mfma_f32_16x16x32_bf16 v[96:99], v[180:183], v[196:199], v[96:99]
	v_mfma_f32_16x16x32_bf16 v[84:87], v[172:175], v[208:211], v[84:87]
	v_mfma_f32_16x16x32_bf16 v[80:83], v[180:183], v[208:211], v[80:83]
	v_mfma_f32_16x16x32_bf16 v[68:71], v[172:175], v[216:219], v[68:71]
	v_mfma_f32_16x16x32_bf16 v[64:67], v[180:183], v[216:219], v[64:67]
	s_barrier
	s_add_i32 s28, s55, s35
	s_mov_b32 m0, s28
	s_nop 0
	global_load_lds_dwordx4 v220, s[26:27]
	s_add_i32 m0, s28, 0x2000
	s_add_u32 s26, s26, 0x40080
	s_addc_u32 s27, s27, 0
	s_add_i32 s28, s56, s35
	global_load_lds_dwordx4 v204, s[98:99]
	ds_read_b128 v[184:187], v153 offset:49152
	ds_read_b128 v[188:191], v153 offset:50176
	ds_read_b128 v[192:195], v153 offset:51200
	ds_read_b128 v[196:199], v153 offset:52224
	s_mov_b32 m0, s28
	s_nop 0
	global_load_lds_dwordx4 v132, s[26:27]
	s_add_i32 m0, s28, 0x2000
	s_nop 0
	global_load_lds_dwordx4 v128, s[26:27]
	s_cmp_lg_u32 s54, 12
	s_cbranch_scc1 .Lbal_last_10
	s_mov_b32 m0, s45
	s_nop 0
	global_load_lds_dwordx4 v221, s[100:101]
	s_mov_b32 m0, s46
	s_nop 0
	global_load_lds_dwordx4 v205, s[100:101]
.Lbal_last_10:
	ds_read_b128 v[200:203], v153 offset:53248
	ds_read_b128 v[208:211], v153 offset:54272
	ds_read_b128 v[212:215], v153 offset:55296
	ds_read_b128 v[216:219], v153 offset:56320
	s_waitcnt vmcnt(6)
	s_waitcnt lgkmcnt(0)
	s_barrier
	s_waitcnt lgkmcnt(0)
	v_mfma_f32_16x16x32_bf16 v[60:63], v[144:147], v[184:187], v[60:63]
	v_mfma_f32_16x16x32_bf16 v[56:59], v[160:163], v[184:187], v[56:59]
	v_mfma_f32_16x16x32_bf16 v[44:47], v[144:147], v[192:195], v[44:47]
	v_mfma_f32_16x16x32_bf16 v[40:43], v[160:163], v[192:195], v[40:43]
	v_mfma_f32_16x16x32_bf16 v[28:31], v[144:147], v[200:203], v[28:31]
	v_mfma_f32_16x16x32_bf16 v[24:27], v[160:163], v[200:203], v[24:27]
	v_mfma_f32_16x16x32_bf16 v[12:15], v[144:147], v[212:215], v[12:15]
	v_mfma_f32_16x16x32_bf16 v[8:11], v[160:163], v[212:215], v[8:11]
	v_mfma_f32_16x16x32_bf16 v[60:63], v[156:159], v[188:191], v[60:63]
	v_mfma_f32_16x16x32_bf16 v[56:59], v[164:167], v[188:191], v[56:59]
	v_mfma_f32_16x16x32_bf16 v[44:47], v[156:159], v[196:199], v[44:47]
	v_mfma_f32_16x16x32_bf16 v[40:43], v[164:167], v[196:199], v[40:43]
	v_mfma_f32_16x16x32_bf16 v[28:31], v[156:159], v[208:211], v[28:31]
	v_mfma_f32_16x16x32_bf16 v[24:27], v[164:167], v[208:211], v[24:27]
	v_mfma_f32_16x16x32_bf16 v[12:15], v[156:159], v[216:219], v[12:15]
	v_mfma_f32_16x16x32_bf16 v[8:11], v[164:167], v[216:219], v[8:11]
	v_mfma_f32_16x16x32_bf16 v[52:55], v[168:171], v[184:187], v[52:55]
	v_mfma_f32_16x16x32_bf16 v[48:51], v[176:179], v[184:187], v[48:51]
	v_mfma_f32_16x16x32_bf16 v[36:39], v[168:171], v[192:195], v[36:39]
	v_mfma_f32_16x16x32_bf16 v[32:35], v[176:179], v[192:195], v[32:35]
	v_mfma_f32_16x16x32_bf16 v[20:23], v[168:171], v[200:203], v[20:23]
	v_mfma_f32_16x16x32_bf16 v[16:19], v[176:179], v[200:203], v[16:19]
	v_mfma_f32_16x16x32_bf16 v[4:7], v[168:171], v[212:215], v[4:7]
	v_mfma_f32_16x16x32_bf16 v[0:3], v[176:179], v[212:215], v[0:3]
	v_mfma_f32_16x16x32_bf16 v[52:55], v[172:175], v[188:191], v[52:55]
	v_mfma_f32_16x16x32_bf16 v[48:51], v[180:183], v[188:191], v[48:51]
	v_mfma_f32_16x16x32_bf16 v[36:39], v[172:175], v[196:199], v[36:39]
	v_mfma_f32_16x16x32_bf16 v[32:35], v[180:183], v[196:199], v[32:35]
	v_mfma_f32_16x16x32_bf16 v[20:23], v[172:175], v[208:211], v[20:23]
	v_mfma_f32_16x16x32_bf16 v[16:19], v[180:183], v[208:211], v[16:19]
	v_mfma_f32_16x16x32_bf16 v[4:7], v[172:175], v[216:219], v[4:7]
	v_mfma_f32_16x16x32_bf16 v[0:3], v[180:183], v[216:219], v[0:3]
	s_barrier
	s_add_i32 s54, s54, 2
	s_add_u32 s52, s52, 0x100
	s_addc_u32 s53, s53, 0
	s_add_u32 s24, s24, 0x100
	s_addc_u32 s25, s25, 0
	s_cmp_gt_u32 s54, 13
	s_cbranch_scc0 .LBB0_1646
	s_setprio 0
	s_and_b64 vcc, exec, s[14:15]
	s_cbranch_vccz .LBB0_1649
	s_barrier
